# nt cache policy extended to the read-once loads of the LN1 / LN2 / LN3 / softmax phases (pre, hb, yslot, scores, kvpart) on top of the phase-0 and mixout-residual nt loads
# speedup vs baseline: 1.0668x; 1.0124x over previous
; __device__ __forceinline__ u16 f2bf(float f) { return (u16)(pack2(f, f) & 0xffffu); }
; __device__ void memkv_reduce(const Params& p) {
;   const float* part = p.kvpart();
;   for (int i = blockIdx.x * 256 + threadIdx.x; i < MEML * 4096 / 4; i += gridDim.x * 256) {
;     const int m = i >> 10, n = (i & 1023) * 4;
;     f32x4 v = *(const f32x4*)(part + (long)m * 4096 + n);
; #pragma unroll
;     for (int kc = 1; kc < 4; kc++) v += *(const f32x4*)(part + ((long)kc * MEML + m) * 4096 + n);
;     if (n < 2048) store_bf4(p.kmem() + (long)m * DM + n, v[0], v[1], v[2], v[3]);
;     else {
; #pragma unroll
;       for (int e = 0; e < 4; e++) p.vmemT()[(long)(n - 2048 + e) * MEML + m] = f2bf(v[e]);
;     }
;   }
.LBB0_468:
	v_ashrrev_i32_e32 v2, 10, v131
	v_and_b32_e32 v9, 0xffc, v8
	v_ashrrev_i32_e32 v3, 31, v2
	v_lshlrev_b32_e32 v0, 2, v9
	v_lshlrev_b64 v[4:5], 14, v[2:3]
	v_lshl_add_u64 v[10:11], s[6:7], 0, v[0:1]
	v_lshl_add_u64 v[18:19], v[10:11], 0, v[4:5]
	v_add_co_u32_e32 v10, vcc, 0x400000, v18
	v_lshl_add_u64 v[6:7], s[6:7], 0, v[4:5]
	s_nop 0
	v_addc_co_u32_e32 v11, vcc, 0, v19, vcc
	v_add_co_u32_e32 v14, vcc, 0x800000, v18
	v_lshl_add_u64 v[6:7], v[6:7], 0, v[0:1]
	s_nop 0
	v_addc_co_u32_e32 v15, vcc, 0, v19, vcc
	global_load_dwordx4 v[4:7], v[6:7], off nt
	s_nop 0
	global_load_dwordx4 v[10:13], v[10:11], off nt
	v_add_co_u32_e32 v18, vcc, 0xc00000, v18
	global_load_dwordx4 v[14:17], v[14:15], off nt
	s_nop 0
	v_addc_co_u32_e32 v19, vcc, 0, v19, vcc
	global_load_dwordx4 v[18:21], v[18:19], off nt
	v_cmp_lt_u32_e32 vcc, s18, v9
	s_waitcnt vmcnt(2)
	v_pk_add_f32 v[6:7], v[6:7], v[12:13]
	v_pk_add_f32 v[4:5], v[4:5], v[10:11]
	s_waitcnt vmcnt(1)
	v_pk_add_f32 v[6:7], v[6:7], v[16:17]
	v_pk_add_f32 v[10:11], v[4:5], v[14:15]
	s_waitcnt vmcnt(0)
	v_pk_add_f32 v[4:5], v[6:7], v[20:21]
	v_pk_add_f32 v[6:7], v[10:11], v[18:19]
	s_and_saveexec_b64 s[16:17], vcc
	s_xor_b64 s[16:17], exec, s[16:17]
	s_cbranch_execz .LBB0_470
	v_add_u32_e32 v0, 0xfffff800, v9
	v_lshl_add_u64 v[2:3], v[2:3], 1, s[8:9]
	v_lshlrev_b64 v[10:11], 9, v[0:1]
	v_cvt_pk_bf16_f32 v6, v6, s0
	v_lshl_add_u64 v[10:11], v[2:3], 0, v[10:11]
	v_add_u32_e32 v0, 0xfffff801, v9
	global_store_short v[10:11], v6, off
	v_cvt_pk_bf16_f32 v10, v7, s0
	v_lshlrev_b64 v[6:7], 9, v[0:1]
	v_lshl_add_u64 v[6:7], v[2:3], 0, v[6:7]
	v_add_u32_e32 v0, 0xfffff802, v9
	global_store_short v[6:7], v10, off
	v_lshlrev_b64 v[6:7], 9, v[0:1]
	v_cvt_pk_bf16_f32 v4, v4, s0
	v_lshl_add_u64 v[6:7], v[2:3], 0, v[6:7]
	v_add_u32_e32 v0, 0xfffff803, v9
	global_store_short v[6:7], v4, off
	v_cvt_pk_bf16_f32 v6, v5, s0
	v_lshlrev_b64 v[4:5], 9, v[0:1]
	v_lshl_add_u64 v[2:3], v[2:3], 0, v[4:5]
	global_store_short v[2:3], v6, off

; template <class G, class T> __device__ __forceinline__ G opaque_g(T* q) { asm volatile("" : "+v"(q)); return (G)q; }
; __device__ __forceinline__ void ln_stats(const float (&v)[32], float& mean, float& rstd) {
;   float s = 0.f;
; #pragma unroll
;   for (int i = 0; i < 32; i++) s += v[i];
;   mean = wave_sum(s) * (1.f / DM);
;   float q = 0.f;
; #pragma unroll
;   for (int i = 0; i < 32; i++) { float d = v[i] - mean; q += d * d; }
;   rstd = rsqrtf(wave_sum(q) * (1.f / DM) + 1e-5f);
; }
; template <int MODE>
; __device__ void phase_ln(const Params& p, u16* smem) {
;     ...
;   for (int rb = (blockIdx.x * 4 + wid) * 2; rb < SEQ; rb += gridDim.x * 8) {
;     float v[2][32];
; #pragma unroll
;     for (int q = 0; q < 2; q++) {
;       const int r = rb + q;
;       if (MODE == 0) {
;         g_cv4 pr = opaque_g<g_cv4>(p.pre() + (long)r * DM + lane * 4);
; #pragma unroll
;         for (int i = 0; i < 8; i++) {
;           f32x4 a = pr[i * 64];
;           v[q][i * 4 + 0] = a[0]; v[q][i * 4 + 1] = a[1]; v[q][i * 4 + 2] = a[2]; v[q][i * 4 + 3] = a[3];
.LBB0_474:
	v_ashrrev_i32_e32 v55, 31, v54
	v_lshlrev_b64 v[0:1], 13, v[54:55]
	v_lshl_add_u64 v[2:3], v[48:49], 0, v[0:1]
	global_load_dwordx4 v[76:79], v[2:3], off nt
	global_load_dwordx4 v[80:83], v[2:3], off offset:1024 nt
	global_load_dwordx4 v[84:87], v[2:3], off offset:2048 nt
	global_load_dwordx4 v[88:91], v[2:3], off offset:3072 nt
	v_add_co_u32_e32 v2, vcc, s3, v2
	v_add_u32_e32 v60, 1, v54
	s_nop 0
	v_addc_co_u32_e32 v3, vcc, 0, v3, vcc
	global_load_dwordx4 v[92:95], v[2:3], off nt
	global_load_dwordx4 v[40:43], v[2:3], off offset:1024 nt
	global_load_dwordx4 v[36:39], v[2:3], off offset:2048 nt
	global_load_dwordx4 v[32:35], v[2:3], off offset:3072 nt
	v_cmp_lt_i32_e32 vcc, v68, v67
	v_ashrrev_i32_e32 v61, 31, v60
	v_lshlrev_b64 v[64:65], 13, v[60:61]
	v_cndmask_b32_e32 v2, v66, v68, vcc
	v_lshlrev_b32_e32 v75, 2, v2
	v_cmp_lt_i32_e32 vcc, v69, v67
	v_lshl_add_u64 v[96:97], v[50:51], 0, v[0:1]
	v_lshl_add_u64 v[0:1], v[48:49], 0, v[64:65]
	v_cndmask_b32_e32 v3, v66, v69, vcc
	v_cmp_lt_i32_e32 vcc, v70, v67
	v_lshlrev_b32_e32 v135, 2, v3
	v_mov_b64_e32 v[56:57], v[44:45]
	v_cndmask_b32_e32 v4, v66, v70, vcc
	v_cmp_lt_i32_e32 vcc, v71, v67
	v_lshlrev_b32_e32 v137, 2, v4
	v_mov_b64_e32 v[58:59], v[46:47]
	v_cndmask_b32_e32 v5, v66, v71, vcc
	v_lshlrev_b32_e32 v146, 2, v5
	v_cmp_lt_i32_e32 vcc, v72, v67
	global_load_dwordx4 v[28:31], v[0:1], off nt
	global_load_dwordx4 v[24:27], v[0:1], off offset:1024 nt
	global_load_dwordx4 v[20:23], v[0:1], off offset:2048 nt
	global_load_dwordx4 v[16:19], v[0:1], off offset:3072 nt
	v_cndmask_b32_e32 v6, v66, v72, vcc
	v_lshlrev_b32_e32 v147, 2, v6
	v_cmp_lt_i32_e32 vcc, v73, v67
	s_waitcnt vmcnt(11)
	v_add_f32_e32 v2, 0, v76
	v_add_f32_e32 v2, v77, v2
	v_add_f32_e32 v2, v78, v2
	v_add_f32_e32 v2, v79, v2
	s_waitcnt vmcnt(10)
	v_add_f32_e32 v2, v80, v2
	v_add_f32_e32 v2, v81, v2
	v_add_f32_e32 v2, v82, v2
	v_add_f32_e32 v2, v83, v2
	s_waitcnt vmcnt(9)
	v_add_f32_e32 v2, v84, v2
	v_add_f32_e32 v2, v85, v2
	v_add_f32_e32 v2, v86, v2
	v_add_f32_e32 v2, v87, v2
	s_waitcnt vmcnt(8)
	v_add_f32_e32 v2, v88, v2
	v_add_f32_e32 v2, v89, v2
	v_add_f32_e32 v2, v90, v2
	v_add_f32_e32 v2, v91, v2
	s_waitcnt vmcnt(7)
	v_add_f32_e32 v2, v92, v2
	v_add_f32_e32 v2, v93, v2
	v_add_f32_e32 v2, v94, v2
	v_add_f32_e32 v2, v95, v2
	s_waitcnt vmcnt(6)
	v_add_f32_e32 v2, v40, v2
	v_add_f32_e32 v2, v41, v2
	v_add_f32_e32 v2, v42, v2
	v_add_f32_e32 v2, v43, v2
	s_waitcnt vmcnt(5)
	v_add_f32_e32 v2, v36, v2
	v_add_f32_e32 v2, v37, v2
	v_add_f32_e32 v2, v38, v2
	v_add_f32_e32 v2, v39, v2
	s_waitcnt vmcnt(4)
	v_add_f32_e32 v2, v32, v2
	v_add_f32_e32 v2, v33, v2
	v_add_f32_e32 v2, v34, v2
	v_add_f32_e32 v4, v35, v2
	ds_bpermute_b32 v5, v75, v4
	v_lshlrev_b64 v[2:3], 12, v[54:55]
	v_lshl_add_u64 v[62:63], v[52:53], 0, v[2:3]
	v_cndmask_b32_e32 v7, v66, v73, vcc
	v_lshlrev_b32_e32 v148, 2, v7
	s_waitcnt lgkmcnt(0)
	v_add_f32_e32 v4, v4, v5
	ds_bpermute_b32 v5, v135, v4
	v_add_co_u32_e32 v98, vcc, s3, v0
	v_add_u32_e32 v54, s2, v54
	s_nop 0
	v_addc_co_u32_e32 v99, vcc, 0, v1, vcc
	s_waitcnt lgkmcnt(0)
	v_add_f32_e32 v2, v4, v5
	ds_bpermute_b32 v3, v137, v2
	global_load_dwordx4 v[12:15], v[98:99], off nt
	global_load_dwordx4 v[8:11], v[98:99], off offset:1024 nt
	s_waitcnt lgkmcnt(0)
	v_add_f32_e32 v2, v2, v3
	ds_bpermute_b32 v3, v146, v2
	s_waitcnt lgkmcnt(0)
	v_add_f32_e32 v55, v2, v3
	ds_bpermute_b32 v100, v147, v55
	global_load_dwordx4 v[4:7], v[98:99], off offset:2048 nt
	global_load_dwordx4 v[0:3], v[98:99], off offset:3072 nt
	s_waitcnt lgkmcnt(0)
	v_add_f32_e32 v55, v55, v100
	ds_bpermute_b32 v104, v148, v55
	global_load_dwordx4 v[96:99], v[56:57], off
	global_load_dwordx4 v[100:103], v[58:59], off
	s_waitcnt lgkmcnt(0)
	v_add_f32_e32 v55, v55, v104
	v_mul_f32_e32 v104, 0x3a000000, v55
	v_pk_add_f32 v[76:77], v[76:77], v[104:105] op_sel_hi:[1,0] neg_lo:[0,1] neg_hi:[0,1]
	v_pk_add_f32 v[78:79], v[78:79], v[104:105] op_sel_hi:[1,0] neg_lo:[0,1] neg_hi:[0,1]
	v_pk_add_f32 v[110:111], v[36:37], v[104:105] op_sel_hi:[1,0] neg_lo:[0,1] neg_hi:[0,1]
	v_pk_add_f32 v[36:37], v[34:35], v[104:105] op_sel_hi:[1,0] neg_lo:[0,1] neg_hi:[0,1]
	v_pk_mul_f32 v[34:35], v[76:77], v[76:77]
	v_pk_add_f32 v[108:109], v[38:39], v[104:105] op_sel_hi:[1,0] neg_lo:[0,1] neg_hi:[0,1]
	v_pk_add_f32 v[38:39], v[32:33], v[104:105] op_sel_hi:[1,0] neg_lo:[0,1] neg_hi:[0,1]
	v_pk_mul_f32 v[32:33], v[78:79], v[78:79]
	v_add_f32_e32 v34, v34, v35
	v_pk_add_f32 v[80:81], v[80:81], v[104:105] op_sel_hi:[1,0] neg_lo:[0,1] neg_hi:[0,1]
	v_add_f32_e32 v32, v32, v34
	v_pk_add_f32 v[82:83], v[82:83], v[104:105] op_sel_hi:[1,0] neg_lo:[0,1] neg_hi:[0,1]
	v_pk_add_f32 v[86:87], v[86:87], v[104:105] op_sel_hi:[1,0] neg_lo:[0,1] neg_hi:[0,1]
	v_pk_add_f32 v[84:85], v[84:85], v[104:105] op_sel_hi:[1,0] neg_lo:[0,1] neg_hi:[0,1]
	v_pk_add_f32 v[90:91], v[90:91], v[104:105] op_sel_hi:[1,0] neg_lo:[0,1] neg_hi:[0,1]
	v_pk_add_f32 v[88:89], v[88:89], v[104:105] op_sel_hi:[1,0] neg_lo:[0,1] neg_hi:[0,1]
	v_pk_add_f32 v[94:95], v[94:95], v[104:105] op_sel_hi:[1,0] neg_lo:[0,1] neg_hi:[0,1]
	v_pk_add_f32 v[92:93], v[92:93], v[104:105] op_sel_hi:[1,0] neg_lo:[0,1] neg_hi:[0,1]
	v_pk_add_f32 v[106:107], v[42:43], v[104:105] op_sel_hi:[1,0] neg_lo:[0,1] neg_hi:[0,1]
	v_pk_add_f32 v[40:41], v[40:41], v[104:105] op_sel_hi:[1,0] neg_lo:[0,1] neg_hi:[0,1]
	v_pk_mul_f32 v[104:105], v[80:81], v[80:81]
	v_add_f32_e32 v32, v33, v32
	v_add_f32_e32 v32, v104, v32
	v_pk_mul_f32 v[42:43], v[82:83], v[82:83]
	v_add_f32_e32 v32, v105, v32
	v_add_f32_e32 v32, v42, v32
	v_pk_mul_f32 v[114:115], v[84:85], v[84:85]
	v_add_f32_e32 v32, v43, v32
	v_add_f32_e32 v32, v114, v32
	v_pk_mul_f32 v[112:113], v[86:87], v[86:87]
	v_add_f32_e32 v32, v115, v32
	v_add_f32_e32 v32, v112, v32
	v_pk_mul_f32 v[118:119], v[88:89], v[88:89]
	v_add_f32_e32 v32, v113, v32
	v_add_f32_e32 v32, v118, v32
	v_pk_mul_f32 v[116:117], v[90:91], v[90:91]
	v_add_f32_e32 v32, v119, v32
	v_add_f32_e32 v32, v116, v32
	v_pk_mul_f32 v[122:123], v[92:93], v[92:93]
	v_add_f32_e32 v32, v117, v32
	v_add_f32_e32 v32, v122, v32
	v_pk_mul_f32 v[120:121], v[94:95], v[94:95]
	v_add_f32_e32 v32, v123, v32
	v_add_f32_e32 v32, v120, v32
	v_pk_mul_f32 v[126:127], v[40:41], v[40:41]
	v_add_f32_e32 v32, v121, v32
	v_add_f32_e32 v32, v126, v32
	v_pk_mul_f32 v[124:125], v[106:107], v[106:107]
	v_add_f32_e32 v32, v127, v32
	v_add_f32_e32 v32, v124, v32
	v_pk_mul_f32 v[140:141], v[110:111], v[110:111]
	v_add_f32_e32 v32, v125, v32
	v_add_f32_e32 v32, v140, v32
	v_pk_mul_f32 v[138:139], v[108:109], v[108:109]
	v_add_f32_e32 v32, v141, v32
	v_add_f32_e32 v32, v138, v32
	v_pk_mul_f32 v[144:145], v[38:39], v[38:39]
	v_add_f32_e32 v32, v139, v32
	v_add_f32_e32 v32, v144, v32
	v_pk_mul_f32 v[142:143], v[36:37], v[36:37]
	v_add_f32_e32 v32, v145, v32
	v_add_f32_e32 v32, v142, v32
	v_add_f32_e32 v32, v143, v32
	ds_bpermute_b32 v33, v75, v32
	s_waitcnt lgkmcnt(0)
; template <class G, class T> __device__ __forceinline__ G opaque_g(T* q) { asm volatile("" : "+v"(q)); return (G)q; }
; __device__ __forceinline__ void ln_stats(const float (&v)[32], float& mean, float& rstd) {
;   float s = 0.f;
; #pragma unroll
;   for (int i = 0; i < 32; i++) s += v[i];
;   mean = wave_sum(s) * (1.f / DM);
;   float q = 0.f;
; #pragma unroll
;   for (int i = 0; i < 32; i++) { float d = v[i] - mean; q += d * d; }
;   rstd = rsqrtf(wave_sum(q) * (1.f / DM) + 1e-5f);
; }
; template <int MODE>
; __device__ void phase_ln(const Params& p, u16* smem) {
;     ...
;     g_cv4 pg = opaque_g<g_cv4>(gam + lane * 4);
;     g_cv4 pb = opaque_g<g_cv4>(bet + lane * 4);
; #pragma unroll
;     for (int q = 0; q < 2; q++) {
;       g_v4 po = opaque_g<g_v4>(p.out + (long)(rb + q) * DM + lane * 4);
;       g_u2 ph = opaque_g<g_u2>(p.hb() + (long)(rb + q) * DM + lane * 4);
; #pragma unroll
;       for (int i = 0; i < 8; i++) {
;         f32x4 g = pg[i * 64], b = pb[i * 64];
;         f32x4 o4;
; #pragma unroll
;         for (int e = 0; e < 4; e++) o4[e] = (v[q][i * 4 + e] - mean[q]) * rstd[q] * g[e] + b[e];
;         if (MODE == 2) po[i * 64] = o4;
;         else { u32x2 w = {pack2(o4[0], o4[1]), pack2(o4[2], o4[3])}; ph[i * 64] = w; }
;       }
	v_add_f32_e32 v32, v32, v33
	ds_bpermute_b32 v33, v135, v32
	s_waitcnt lgkmcnt(0)
	v_add_f32_e32 v32, v32, v33
	ds_bpermute_b32 v33, v137, v32
	s_waitcnt lgkmcnt(0)
	v_add_f32_e32 v32, v32, v33
	ds_bpermute_b32 v33, v146, v32
	s_waitcnt lgkmcnt(0)
	v_add_f32_e32 v32, v32, v33
	ds_bpermute_b32 v33, v147, v32
	s_waitcnt lgkmcnt(0)
	v_add_f32_e32 v32, v32, v33
	ds_bpermute_b32 v33, v148, v32
	s_waitcnt lgkmcnt(0)
	v_add_f32_e32 v32, v32, v33
	v_fmamk_f32 v32, v32, 0x3a000000, v74
	v_mul_f32_e32 v33, 0x4b800000, v32
	v_cmp_gt_f32_e32 vcc, s10, v32
	s_nop 1
	v_cndmask_b32_e32 v32, v32, v33, vcc
	v_rsq_f32_e32 v32, v32
	s_nop 0
	v_mul_f32_e32 v33, 0x45800000, v32
	v_cndmask_b32_e32 v42, v32, v33, vcc
	v_pk_mul_f32 v[32:33], v[76:77], v[42:43] op_sel_hi:[1,0]
	v_pk_mul_f32 v[34:35], v[78:79], v[42:43] op_sel_hi:[1,0]
	s_waitcnt vmcnt(0)
	v_pk_fma_f32 v[32:33], v[96:97], v[32:33], v[100:101]
	v_pk_fma_f32 v[34:35], v[98:99], v[34:35], v[102:103]
	v_cvt_pk_bf16_f32 v32, v32, v33
	v_cvt_pk_bf16_f32 v33, v34, v35
	global_store_dwordx2 v[62:63], v[32:33], off
	global_load_dwordx4 v[32:35], v[56:57], off offset:1024
	s_nop 0
	global_load_dwordx4 v[76:79], v[58:59], off offset:1024
	v_pk_mul_f32 v[80:81], v[80:81], v[42:43] op_sel_hi:[1,0]
	v_pk_mul_f32 v[82:83], v[82:83], v[42:43] op_sel_hi:[1,0]
	v_pk_mul_f32 v[40:41], v[40:41], v[42:43] op_sel_hi:[1,0]
	s_waitcnt vmcnt(0)
	v_pk_fma_f32 v[32:33], v[32:33], v[80:81], v[76:77]
	v_pk_fma_f32 v[34:35], v[34:35], v[82:83], v[78:79]
	v_cvt_pk_bf16_f32 v32, v32, v33
	v_cvt_pk_bf16_f32 v33, v34, v35
	global_store_dwordx2 v[62:63], v[32:33], off offset:512
	global_load_dwordx4 v[32:35], v[56:57], off offset:2048
	s_nop 0
	global_load_dwordx4 v[76:79], v[58:59], off offset:2048
	v_pk_mul_f32 v[80:81], v[84:85], v[42:43] op_sel_hi:[1,0]
	v_pk_mul_f32 v[82:83], v[86:87], v[42:43] op_sel_hi:[1,0]
	v_pk_mul_f32 v[84:85], v[88:89], v[42:43] op_sel_hi:[1,0]
	v_pk_mul_f32 v[86:87], v[90:91], v[42:43] op_sel_hi:[1,0]
	s_waitcnt vmcnt(0)
	v_pk_fma_f32 v[32:33], v[32:33], v[80:81], v[76:77]
	v_pk_fma_f32 v[34:35], v[34:35], v[82:83], v[78:79]
	v_cvt_pk_bf16_f32 v32, v32, v33
	v_cvt_pk_bf16_f32 v33, v34, v35
	global_store_dwordx2 v[62:63], v[32:33], off offset:1024
	global_load_dwordx4 v[76:79], v[56:57], off offset:3072
	global_load_dwordx4 v[80:83], v[58:59], off offset:3072
	v_add_co_u32_e32 v32, vcc, s3, v56
	s_waitcnt vmcnt(0)
	v_pk_fma_f32 v[76:77], v[76:77], v[84:85], v[80:81]
	v_pk_fma_f32 v[78:79], v[78:79], v[86:87], v[82:83]
	v_addc_co_u32_e32 v33, vcc, 0, v57, vcc
	v_cvt_pk_bf16_f32 v76, v76, v77
	v_cvt_pk_bf16_f32 v77, v78, v79
	v_add_co_u32_e32 v34, vcc, s3, v58
	global_store_dwordx2 v[62:63], v[76:77], off offset:1536
	s_nop 0
	v_addc_co_u32_e32 v35, vcc, 0, v59, vcc
	global_load_dwordx4 v[76:79], v[32:33], off
	global_load_dwordx4 v[80:83], v[34:35], off
	v_pk_mul_f32 v[84:85], v[92:93], v[42:43] op_sel_hi:[1,0]
	v_pk_mul_f32 v[86:87], v[94:95], v[42:43] op_sel_hi:[1,0]
	s_waitcnt vmcnt(0)
	v_pk_fma_f32 v[76:77], v[76:77], v[84:85], v[80:81]
	v_pk_fma_f32 v[78:79], v[78:79], v[86:87], v[82:83]
	v_cvt_pk_bf16_f32 v76, v76, v77
	v_cvt_pk_bf16_f32 v77, v78, v79
	global_store_dwordx2 v[62:63], v[76:77], off offset:2048
	global_load_dwordx4 v[76:79], v[32:33], off offset:1024
	s_nop 0
	global_load_dwordx4 v[80:83], v[34:35], off offset:1024
	v_pk_mul_f32 v[84:85], v[106:107], v[42:43] op_sel_hi:[1,0]
	s_waitcnt vmcnt(0)
	v_pk_fma_f32 v[40:41], v[76:77], v[40:41], v[80:81]
	v_pk_fma_f32 v[76:77], v[78:79], v[84:85], v[82:83]
	v_cvt_pk_bf16_f32 v40, v40, v41
	v_cvt_pk_bf16_f32 v41, v76, v77
	global_store_dwordx2 v[62:63], v[40:41], off offset:2560
	global_load_dwordx4 v[76:79], v[32:33], off offset:2048
	global_load_dwordx4 v[80:83], v[34:35], off offset:2048
	v_add_f32_e32 v40, 0, v28
	v_add_f32_e32 v40, v29, v40
	v_add_f32_e32 v40, v30, v40
	v_add_f32_e32 v40, v31, v40
	v_add_f32_e32 v40, v24, v40
	v_add_f32_e32 v40, v25, v40
	v_add_f32_e32 v40, v26, v40
	v_add_f32_e32 v40, v27, v40
	v_add_f32_e32 v40, v20, v40
	v_add_f32_e32 v40, v21, v40
	v_add_f32_e32 v40, v22, v40
	v_add_f32_e32 v40, v23, v40
	v_add_f32_e32 v40, v16, v40
	v_add_f32_e32 v40, v17, v40
	v_add_f32_e32 v40, v18, v40
	v_add_f32_e32 v40, v19, v40
	v_add_f32_e32 v40, v12, v40
	v_add_f32_e32 v40, v13, v40
	v_add_f32_e32 v40, v14, v40
	v_add_f32_e32 v40, v15, v40
	v_add_f32_e32 v40, v8, v40
	v_add_f32_e32 v40, v9, v40
	v_add_f32_e32 v40, v10, v40
	v_add_f32_e32 v43, v11, v40
	v_pk_mul_f32 v[40:41], v[110:111], v[42:43] op_sel_hi:[1,0]
	v_pk_mul_f32 v[84:85], v[108:109], v[42:43] op_sel_hi:[1,0]
	s_waitcnt vmcnt(0)
	v_pk_fma_f32 v[40:41], v[76:77], v[40:41], v[80:81]
	v_pk_fma_f32 v[76:77], v[78:79], v[84:85], v[82:83]
	v_cvt_pk_bf16_f32 v40, v40, v41
	v_cvt_pk_bf16_f32 v41, v76, v77
	global_store_dwordx2 v[62:63], v[40:41], off offset:3072
	global_load_dwordx4 v[76:79], v[32:33], off offset:3072
	global_load_dwordx4 v[80:83], v[34:35], off offset:3072
	v_add_f32_e32 v40, v4, v43
	v_add_f32_e32 v40, v5, v40
	v_add_f32_e32 v40, v6, v40
	v_add_f32_e32 v40, v7, v40
	v_add_f32_e32 v40, v0, v40
	v_add_f32_e32 v40, v1, v40
	v_add_f32_e32 v40, v2, v40
	v_add_f32_e32 v40, v3, v40
	ds_bpermute_b32 v41, v75, v40
	s_waitcnt lgkmcnt(0)
	v_add_f32_e32 v40, v40, v41
	ds_bpermute_b32 v41, v135, v40
	s_waitcnt lgkmcnt(0)
	v_add_f32_e32 v40, v40, v41
	ds_bpermute_b32 v41, v137, v40
	s_waitcnt lgkmcnt(0)
	v_add_f32_e32 v40, v40, v41
	ds_bpermute_b32 v41, v146, v40
	s_waitcnt lgkmcnt(0)
	v_add_f32_e32 v40, v40, v41
	ds_bpermute_b32 v41, v147, v40
	s_waitcnt lgkmcnt(0)
; template <class G, class T> __device__ __forceinline__ G opaque_g(T* q) { asm volatile("" : "+v"(q)); return (G)q; }
; __device__ __forceinline__ void ln_stats(const float (&v)[32], float& mean, float& rstd) {
;   float s = 0.f;
; #pragma unroll
;   for (int i = 0; i < 32; i++) s += v[i];
;   mean = wave_sum(s) * (1.f / DM);
;   float q = 0.f;
; #pragma unroll
;   for (int i = 0; i < 32; i++) { float d = v[i] - mean; q += d * d; }
;   rstd = rsqrtf(wave_sum(q) * (1.f / DM) + 1e-5f);
; }
; template <int MODE>
; __device__ void phase_ln(const Params& p, u16* smem) {
;     ...
;     g_cv4 pg = opaque_g<g_cv4>(gam + lane * 4);
;     g_cv4 pb = opaque_g<g_cv4>(bet + lane * 4);
; #pragma unroll
;     for (int q = 0; q < 2; q++) {
;       g_v4 po = opaque_g<g_v4>(p.out + (long)(rb + q) * DM + lane * 4);
;       g_u2 ph = opaque_g<g_u2>(p.hb() + (long)(rb + q) * DM + lane * 4);
; #pragma unroll
;       for (int i = 0; i < 8; i++) {
;         f32x4 g = pg[i * 64], b = pb[i * 64];
;         f32x4 o4;
; #pragma unroll
;         for (int e = 0; e < 4; e++) o4[e] = (v[q][i * 4 + e] - mean[q]) * rstd[q] * g[e] + b[e];
;         if (MODE == 2) po[i * 64] = o4;
;         else { u32x2 w = {pack2(o4[0], o4[1]), pack2(o4[2], o4[3])}; ph[i * 64] = w; }
;       }
	v_add_f32_e32 v43, v40, v41
	ds_bpermute_b32 v55, v148, v43
	v_lshlrev_b64 v[40:41], 12, v[60:61]
	v_lshl_add_u64 v[60:61], v[50:51], 0, v[64:65]
	v_lshl_add_u64 v[40:41], v[52:53], 0, v[40:41]
	s_waitcnt lgkmcnt(0)
	v_add_f32_e32 v43, v43, v55
	v_mul_f32_e32 v64, 0x3a000000, v43
	v_pk_add_f32 v[30:31], v[30:31], v[64:65] op_sel_hi:[1,0] neg_lo:[0,1] neg_hi:[0,1]
	v_pk_add_f32 v[28:29], v[28:29], v[64:65] op_sel_hi:[1,0] neg_lo:[0,1] neg_hi:[0,1]
	v_pk_add_f32 v[26:27], v[26:27], v[64:65] op_sel_hi:[1,0] neg_lo:[0,1] neg_hi:[0,1]
	v_pk_add_f32 v[24:25], v[24:25], v[64:65] op_sel_hi:[1,0] neg_lo:[0,1] neg_hi:[0,1]
	v_pk_add_f32 v[22:23], v[22:23], v[64:65] op_sel_hi:[1,0] neg_lo:[0,1] neg_hi:[0,1]
	v_pk_add_f32 v[20:21], v[20:21], v[64:65] op_sel_hi:[1,0] neg_lo:[0,1] neg_hi:[0,1]
	v_pk_add_f32 v[18:19], v[18:19], v[64:65] op_sel_hi:[1,0] neg_lo:[0,1] neg_hi:[0,1]
	v_pk_add_f32 v[16:17], v[16:17], v[64:65] op_sel_hi:[1,0] neg_lo:[0,1] neg_hi:[0,1]
	v_pk_add_f32 v[14:15], v[14:15], v[64:65] op_sel_hi:[1,0] neg_lo:[0,1] neg_hi:[0,1]
	v_pk_add_f32 v[12:13], v[12:13], v[64:65] op_sel_hi:[1,0] neg_lo:[0,1] neg_hi:[0,1]
	v_pk_add_f32 v[10:11], v[10:11], v[64:65] op_sel_hi:[1,0] neg_lo:[0,1] neg_hi:[0,1]
	v_pk_add_f32 v[8:9], v[8:9], v[64:65] op_sel_hi:[1,0] neg_lo:[0,1] neg_hi:[0,1]
	v_pk_add_f32 v[84:85], v[6:7], v[64:65] op_sel_hi:[1,0] neg_lo:[0,1] neg_hi:[0,1]
	v_pk_add_f32 v[86:87], v[4:5], v[64:65] op_sel_hi:[1,0] neg_lo:[0,1] neg_hi:[0,1]
	v_pk_add_f32 v[88:89], v[2:3], v[64:65] op_sel_hi:[1,0] neg_lo:[0,1] neg_hi:[0,1]
	v_pk_add_f32 v[64:65], v[0:1], v[64:65] op_sel_hi:[1,0] neg_lo:[0,1] neg_hi:[0,1]
	v_pk_mul_f32 v[0:1], v[38:39], v[42:43] op_sel_hi:[1,0]
	v_pk_mul_f32 v[2:3], v[36:37], v[42:43] op_sel_hi:[1,0]
	v_pk_mul_f32 v[92:93], v[28:29], v[28:29]
	v_pk_mul_f32 v[90:91], v[30:31], v[30:31]
	v_add_f32_e32 v36, v92, v93
	v_add_f32_e32 v36, v90, v36
	v_pk_mul_f32 v[96:97], v[24:25], v[24:25]
	v_add_f32_e32 v36, v91, v36
	v_add_f32_e32 v36, v96, v36
	v_pk_mul_f32 v[94:95], v[26:27], v[26:27]
	v_add_f32_e32 v36, v97, v36
	v_add_f32_e32 v36, v94, v36
	v_pk_mul_f32 v[100:101], v[20:21], v[20:21]
	v_add_f32_e32 v36, v95, v36
	v_add_f32_e32 v36, v100, v36
	v_pk_mul_f32 v[98:99], v[22:23], v[22:23]
	v_add_f32_e32 v36, v101, v36
	v_add_f32_e32 v36, v98, v36
	s_waitcnt vmcnt(0)
	v_pk_fma_f32 v[0:1], v[76:77], v[0:1], v[80:81]
	v_pk_fma_f32 v[2:3], v[78:79], v[2:3], v[82:83]
	v_cvt_pk_bf16_f32 v0, v0, v1
	v_cvt_pk_bf16_f32 v1, v2, v3
	global_store_dwordx2 v[62:63], v[0:1], off offset:3584
	global_load_dwordx4 v[0:3], v[56:57], off
	global_load_dwordx4 v[4:7], v[58:59], off
	v_pk_mul_f32 v[104:105], v[16:17], v[16:17]
	v_add_f32_e32 v36, v99, v36
	v_add_f32_e32 v36, v104, v36
	v_pk_mul_f32 v[102:103], v[18:19], v[18:19]
	v_add_f32_e32 v36, v105, v36
	v_add_f32_e32 v36, v102, v36
	v_pk_mul_f32 v[108:109], v[12:13], v[12:13]
	v_add_f32_e32 v36, v103, v36
	v_add_f32_e32 v36, v108, v36
	v_pk_mul_f32 v[106:107], v[14:15], v[14:15]
	v_add_f32_e32 v36, v109, v36
	v_add_f32_e32 v36, v106, v36
	v_pk_mul_f32 v[112:113], v[8:9], v[8:9]
	v_add_f32_e32 v36, v107, v36
	v_add_f32_e32 v36, v112, v36
	v_pk_mul_f32 v[110:111], v[10:11], v[10:11]
	v_add_f32_e32 v36, v113, v36
	v_add_f32_e32 v36, v110, v36
	v_pk_mul_f32 v[116:117], v[86:87], v[86:87]
	v_add_f32_e32 v36, v111, v36
	v_add_f32_e32 v36, v116, v36
	v_pk_mul_f32 v[114:115], v[84:85], v[84:85]
	v_add_f32_e32 v36, v117, v36
	v_add_f32_e32 v36, v114, v36
	v_pk_mul_f32 v[120:121], v[64:65], v[64:65]
	v_add_f32_e32 v36, v115, v36
	v_add_f32_e32 v36, v120, v36
	v_pk_mul_f32 v[118:119], v[88:89], v[88:89]
	v_add_f32_e32 v36, v121, v36
	v_add_f32_e32 v36, v118, v36
	v_add_f32_e32 v36, v119, v36
	ds_bpermute_b32 v37, v75, v36
	s_waitcnt lgkmcnt(0)
	v_add_f32_e32 v36, v36, v37
	ds_bpermute_b32 v37, v135, v36
	s_waitcnt lgkmcnt(0)
	v_add_f32_e32 v36, v36, v37
	ds_bpermute_b32 v37, v137, v36
	s_waitcnt lgkmcnt(0)
	v_add_f32_e32 v36, v36, v37
	ds_bpermute_b32 v37, v146, v36
	s_waitcnt lgkmcnt(0)
	v_add_f32_e32 v36, v36, v37
	ds_bpermute_b32 v37, v147, v36
	s_waitcnt lgkmcnt(0)
; template <class G, class T> __device__ __forceinline__ G opaque_g(T* q) { asm volatile("" : "+v"(q)); return (G)q; }
; template <int MODE>
; __device__ void phase_ln(const Params& p, u16* smem) {
;     ...
;     g_cv4 pg = opaque_g<g_cv4>(gam + lane * 4);
;     g_cv4 pb = opaque_g<g_cv4>(bet + lane * 4);
; #pragma unroll
;     for (int q = 0; q < 2; q++) {
;       g_v4 po = opaque_g<g_v4>(p.out + (long)(rb + q) * DM + lane * 4);
;       g_u2 ph = opaque_g<g_u2>(p.hb() + (long)(rb + q) * DM + lane * 4);
; #pragma unroll
;       for (int i = 0; i < 8; i++) {
;         f32x4 g = pg[i * 64], b = pb[i * 64];
;         f32x4 o4;
; #pragma unroll
;         for (int e = 0; e < 4; e++) o4[e] = (v[q][i * 4 + e] - mean[q]) * rstd[q] * g[e] + b[e];
;         if (MODE == 2) po[i * 64] = o4;
;         else { u32x2 w = {pack2(o4[0], o4[1]), pack2(o4[2], o4[3])}; ph[i * 64] = w; }
;       }
;     }
;   }
	v_add_f32_e32 v36, v36, v37
	ds_bpermute_b32 v37, v148, v36
	s_waitcnt lgkmcnt(0)
	v_add_f32_e32 v36, v36, v37
	v_fmamk_f32 v36, v36, 0x3a000000, v74
	v_mul_f32_e32 v37, 0x4b800000, v36
	v_cmp_gt_f32_e32 vcc, s10, v36
	s_nop 1
	v_cndmask_b32_e32 v36, v36, v37, vcc
	v_rsq_f32_e32 v36, v36
	s_nop 0
	v_mul_f32_e32 v37, 0x45800000, v36
	v_cndmask_b32_e32 v36, v36, v37, vcc
	v_pk_mul_f32 v[28:29], v[28:29], v[36:37] op_sel_hi:[1,0]
	v_pk_mul_f32 v[30:31], v[30:31], v[36:37] op_sel_hi:[1,0]
	s_waitcnt vmcnt(0)
	v_pk_fma_f32 v[0:1], v[0:1], v[28:29], v[4:5]
	v_pk_fma_f32 v[2:3], v[2:3], v[30:31], v[6:7]
	v_cvt_pk_bf16_f32 v0, v0, v1
	v_cvt_pk_bf16_f32 v1, v2, v3
	global_store_dwordx2 v[40:41], v[0:1], off
	global_load_dwordx4 v[0:3], v[56:57], off offset:1024
	s_nop 0
	global_load_dwordx4 v[4:7], v[58:59], off offset:1024
	v_pk_mul_f32 v[24:25], v[24:25], v[36:37] op_sel_hi:[1,0]
	v_pk_mul_f32 v[26:27], v[26:27], v[36:37] op_sel_hi:[1,0]
	v_pk_mul_f32 v[20:21], v[20:21], v[36:37] op_sel_hi:[1,0]
	v_pk_mul_f32 v[22:23], v[22:23], v[36:37] op_sel_hi:[1,0]
	v_pk_mul_f32 v[16:17], v[16:17], v[36:37] op_sel_hi:[1,0]
	v_pk_mul_f32 v[18:19], v[18:19], v[36:37] op_sel_hi:[1,0]
	v_pk_mul_f32 v[12:13], v[12:13], v[36:37] op_sel_hi:[1,0]
	v_pk_mul_f32 v[14:15], v[14:15], v[36:37] op_sel_hi:[1,0]
	v_pk_mul_f32 v[8:9], v[8:9], v[36:37] op_sel_hi:[1,0]
	v_pk_mul_f32 v[10:11], v[10:11], v[36:37] op_sel_hi:[1,0]
	v_cmp_lt_i32_e32 vcc, s11, v54
	s_or_b64 s[8:9], vcc, s[8:9]
	s_waitcnt vmcnt(0)
	v_pk_fma_f32 v[0:1], v[0:1], v[24:25], v[4:5]
	v_pk_fma_f32 v[2:3], v[2:3], v[26:27], v[6:7]
	v_cvt_pk_bf16_f32 v0, v0, v1
	v_cvt_pk_bf16_f32 v1, v2, v3
	global_store_dwordx2 v[40:41], v[0:1], off offset:512
	global_load_dwordx4 v[0:3], v[56:57], off offset:2048
	s_nop 0
	global_load_dwordx4 v[4:7], v[58:59], off offset:2048
	s_waitcnt vmcnt(0)
	v_pk_fma_f32 v[0:1], v[0:1], v[20:21], v[4:5]
	v_pk_fma_f32 v[2:3], v[2:3], v[22:23], v[6:7]
	v_cvt_pk_bf16_f32 v0, v0, v1
	v_cvt_pk_bf16_f32 v1, v2, v3
	global_store_dwordx2 v[40:41], v[0:1], off offset:1024
	global_load_dwordx4 v[0:3], v[56:57], off offset:3072
	s_nop 0
	global_load_dwordx4 v[4:7], v[58:59], off offset:3072
	s_waitcnt vmcnt(0)
	v_pk_fma_f32 v[0:1], v[0:1], v[16:17], v[4:5]
	v_pk_fma_f32 v[2:3], v[2:3], v[18:19], v[6:7]
	v_cvt_pk_bf16_f32 v0, v0, v1
	v_cvt_pk_bf16_f32 v1, v2, v3
	global_store_dwordx2 v[40:41], v[0:1], off offset:1536
	global_load_dwordx4 v[0:3], v[32:33], off
	s_nop 0
	global_load_dwordx4 v[4:7], v[34:35], off
	s_waitcnt vmcnt(0)
	v_pk_fma_f32 v[0:1], v[0:1], v[12:13], v[4:5]
	v_pk_fma_f32 v[2:3], v[2:3], v[14:15], v[6:7]
	v_cvt_pk_bf16_f32 v0, v0, v1
	v_cvt_pk_bf16_f32 v1, v2, v3
	global_store_dwordx2 v[40:41], v[0:1], off offset:2048
	global_load_dwordx4 v[0:3], v[32:33], off offset:1024
	s_nop 0
	global_load_dwordx4 v[4:7], v[34:35], off offset:1024
	s_waitcnt vmcnt(0)
	v_pk_fma_f32 v[0:1], v[0:1], v[8:9], v[4:5]
	v_pk_fma_f32 v[2:3], v[2:3], v[10:11], v[6:7]
	v_cvt_pk_bf16_f32 v0, v0, v1
	v_cvt_pk_bf16_f32 v1, v2, v3
	global_store_dwordx2 v[40:41], v[0:1], off offset:2560
	global_load_dwordx4 v[0:3], v[32:33], off offset:2048
	s_nop 0
	global_load_dwordx4 v[4:7], v[34:35], off offset:2048
	v_pk_mul_f32 v[8:9], v[86:87], v[36:37] op_sel_hi:[1,0]
	v_pk_mul_f32 v[10:11], v[84:85], v[36:37] op_sel_hi:[1,0]
	s_waitcnt vmcnt(0)
	v_pk_fma_f32 v[0:1], v[0:1], v[8:9], v[4:5]
	v_pk_fma_f32 v[2:3], v[2:3], v[10:11], v[6:7]
	v_cvt_pk_bf16_f32 v0, v0, v1
	v_cvt_pk_bf16_f32 v1, v2, v3
	global_store_dwordx2 v[40:41], v[0:1], off offset:3072
	global_load_dwordx4 v[0:3], v[32:33], off offset:3072
	s_nop 0
	global_load_dwordx4 v[4:7], v[34:35], off offset:3072
	v_pk_mul_f32 v[8:9], v[64:65], v[36:37] op_sel_hi:[1,0]
	v_pk_mul_f32 v[10:11], v[88:89], v[36:37] op_sel_hi:[1,0]
	s_waitcnt vmcnt(0)
	v_pk_fma_f32 v[0:1], v[0:1], v[8:9], v[4:5]
	v_pk_fma_f32 v[2:3], v[2:3], v[10:11], v[6:7]
	v_cvt_pk_bf16_f32 v0, v0, v1
	v_cvt_pk_bf16_f32 v1, v2, v3
	global_store_dwordx2 v[40:41], v[0:1], off offset:3584
	s_andn2_b64 exec, exec, s[8:9]
	s_cbranch_execnz .LBB0_474

; __device__ void phase_softmax(const Params& p) {
;   const int wpb = 4, lane = threadIdx.x & 63, wid = threadIdx.x >> 6;
;   const int nrows = 4 * SEQ;
;   for (int r = blockIdx.x * wpb + wid; r < nrows; r += gridDim.x * wpb) {
;     float4 v = *(const float4*)(p.scores() + (long)r * MEML + lane * 4);
;     float mx = wave_max(fmaxf(fmaxf(v.x, v.y), fmaxf(v.z, v.w)));
;     float e0 = __expf(v.x - mx), e1 = __expf(v.y - mx), e2 = __expf(v.z - mx), e3 = __expf(v.w - mx);
;     float inv = 1.f / wave_sum(e0 + e1 + e2 + e3);
;     store_bf4(p.Pm() + (long)r * MEML + lane * 4, e0 * inv, e1 * inv, e2 * inv, e3 * inv);
;   }
; }
.LBB0_646:
	v_ashrrev_i32_e32 v1, 31, v0
	v_lshlrev_b64 v[12:13], 10, v[0:1]
	v_lshl_add_u64 v[12:13], v[2:3], 0, v[12:13]
	global_load_dwordx4 v[12:15], v[12:13], off nt
	s_waitcnt vmcnt(0)
	v_max_f32_e32 v16, v15, v15
	v_max_f32_e32 v17, v14, v14
	v_max_f32_e32 v16, v17, v16
	v_max3_f32 v16, v12, v13, v16
	ds_bpermute_b32 v17, v6, v16
	s_waitcnt lgkmcnt(0)
	v_max_f32_e32 v17, v17, v17
	v_max_f32_e32 v16, v16, v17
	ds_bpermute_b32 v17, v7, v16
	s_waitcnt lgkmcnt(0)
	v_max_f32_e32 v17, v17, v17
	v_max_f32_e32 v16, v16, v17
	ds_bpermute_b32 v17, v8, v16
	s_waitcnt lgkmcnt(0)
	v_max_f32_e32 v17, v17, v17
	v_max_f32_e32 v16, v16, v17
	ds_bpermute_b32 v17, v9, v16
	s_waitcnt lgkmcnt(0)
	v_max_f32_e32 v17, v17, v17
	v_max_f32_e32 v16, v16, v17
	ds_bpermute_b32 v17, v10, v16
	s_waitcnt lgkmcnt(0)
	v_max_f32_e32 v17, v17, v17
	v_max_f32_e32 v16, v16, v17
	ds_bpermute_b32 v17, v11, v16
	s_waitcnt lgkmcnt(0)
	v_max_f32_e32 v17, v17, v17
	v_max_f32_e32 v16, v16, v17
	v_sub_f32_e32 v12, v12, v16
	v_sub_f32_e32 v13, v13, v16
	v_sub_f32_e32 v14, v14, v16
	v_mul_f32_e32 v12, 0x3fb8aa3b, v12
	v_mul_f32_e32 v13, 0x3fb8aa3b, v13
	v_sub_f32_e32 v15, v15, v16
	v_mul_f32_e32 v14, 0x3fb8aa3b, v14
	v_exp_f32_e32 v12, v12
	v_exp_f32_e32 v13, v13
	v_mul_f32_e32 v15, 0x3fb8aa3b, v15
	v_exp_f32_e32 v14, v14
	v_exp_f32_e32 v15, v15
	v_add_f32_e32 v16, v12, v13
	v_add_f32_e32 v16, v14, v16
	v_add_f32_e32 v16, v15, v16
	ds_bpermute_b32 v17, v6, v16
	s_waitcnt lgkmcnt(0)
	v_add_f32_e32 v16, v16, v17
	ds_bpermute_b32 v17, v7, v16
	s_waitcnt lgkmcnt(0)
	v_add_f32_e32 v16, v16, v17
	ds_bpermute_b32 v17, v8, v16
	s_waitcnt lgkmcnt(0)
	v_add_f32_e32 v16, v16, v17
	ds_bpermute_b32 v17, v9, v16
	s_waitcnt lgkmcnt(0)
	v_add_f32_e32 v16, v16, v17
	ds_bpermute_b32 v17, v10, v16
	s_waitcnt lgkmcnt(0)
	v_add_f32_e32 v18, v16, v17
	ds_bpermute_b32 v19, v11, v18
	v_lshlrev_b64 v[16:17], 9, v[0:1]
	v_add_u32_e32 v0, s2, v0
	v_lshl_add_u64 v[16:17], v[4:5], 0, v[16:17]
	s_waitcnt lgkmcnt(0)
	v_add_f32_e32 v1, v18, v19
	v_div_scale_f32 v18, s[0:1], v1, v1, 1.0
	v_rcp_f32_e32 v19, v18
	v_div_scale_f32 v20, vcc, 1.0, v1, 1.0
	v_cmp_lt_i32_e64 s[0:1], s3, v0
	v_fma_f32 v21, -v18, v19, 1.0
	v_fmac_f32_e32 v19, v21, v19
	v_mul_f32_e32 v21, v20, v19
	v_fma_f32 v22, -v18, v21, v20
	v_fmac_f32_e32 v21, v22, v19
	v_fma_f32 v18, -v18, v21, v20
	v_div_fmas_f32 v18, v18, v19, v21
	v_div_fixup_f32 v18, v18, v1, 1.0
	v_pk_mul_f32 v[12:13], v[12:13], v[18:19] op_sel_hi:[1,0]
	v_pk_mul_f32 v[14:15], v[14:15], v[18:19] op_sel_hi:[1,0]
	v_cvt_pk_bf16_f32 v12, v12, v13
	v_cvt_pk_bf16_f32 v13, v14, v15
	s_or_b64 s[10:11], s[0:1], s[10:11]
	global_store_dwordx2 v[16:17], v[12:13], off
	s_andn2_b64 exec, exec, s[10:11]
	s_cbranch_execnz .LBB0_646

; __device__ __forceinline__ void ln_stats(const float (&v)[32], float& mean, float& rstd) {
;   float s = 0.f;
; #pragma unroll
;   for (int i = 0; i < 32; i++) s += v[i];
;   mean = wave_sum(s) * (1.f / DM);
; __device__ void phase_ln2_route(const Params& p) {
;     ...
;   for (int rb = (blockIdx.x * 4 + wid) * 2; rb < SEQ; rb += gridDim.x * 8) {
;     float v[2][32];
; #pragma unroll
;     for (int q = 0; q < 2; q++)
; #pragma unroll
;       for (int i = 0; i < 8; i++) {
;         f32x4 a = *(const f32x4*)(p.pre() + (long)(rb + q) * DM + CH(i) + lane * 4);
;         v[q][i * 4 + 0] = a[0]; v[q][i * 4 + 1] = a[1]; v[q][i * 4 + 2] = a[2]; v[q][i * 4 + 3] = a[3];
;       }
;     float mean[2], rstd[2];
;     ln_stats(v[0], mean[0], rstd[0]);
;     ln_stats(v[1], mean[1], rstd[1]);
.LBB0_818:
	v_ashrrev_i32_e32 v91, 31, v90
	v_lshlrev_b64 v[0:1], 13, v[90:91]
	v_lshl_add_u64 v[0:1], v[62:63], 0, v[0:1]
	global_load_dwordx4 v[94:97], v[0:1], off nt
	v_add_u32_e32 v92, 1, v90
	v_ashrrev_i32_e32 v93, 31, v92
	v_lshlrev_b64 v[2:3], 13, v[92:93]
	v_lshl_add_u64 v[2:3], v[62:63], 0, v[2:3]
	global_load_dwordx4 v[112:115], v[2:3], off nt
	global_load_dwordx4 v[104:107], v[0:1], off offset:1024 nt
	global_load_dwordx4 v[116:119], v[2:3], off offset:1024 nt
	global_load_dwordx4 v[120:123], v[0:1], off offset:2048 nt
	global_load_dwordx4 v[124:127], v[2:3], off offset:2048 nt
	global_load_dwordx4 v[134:137], v[0:1], off offset:3072 nt
	global_load_dwordx4 v[40:43], v[2:3], off offset:3072 nt
	v_add_co_u32_e32 v0, vcc, s65, v0
	s_nop 1
	v_addc_co_u32_e32 v1, vcc, 0, v1, vcc
	global_load_dwordx4 v[36:39], v[0:1], off nt
	v_add_co_u32_e32 v2, vcc, s65, v2
	s_nop 1
	v_addc_co_u32_e32 v3, vcc, 0, v3, vcc
	global_load_dwordx4 v[32:35], v[2:3], off nt
	s_waitcnt lgkmcnt(8)
	global_load_dwordx4 v[28:31], v[0:1], off offset:1024 nt
	s_waitcnt lgkmcnt(0)
	global_load_dwordx4 v[24:27], v[2:3], off offset:1024 nt
	global_load_dwordx4 v[20:23], v[0:1], off offset:2048 nt
	global_load_dwordx4 v[16:19], v[2:3], off offset:2048 nt
	global_load_dwordx4 v[12:15], v[0:1], off offset:3072 nt
	global_load_dwordx4 v[8:11], v[2:3], off offset:3072 nt
	s_waitcnt vmcnt(14)
	v_add_f32_e32 v1, 0, v112
	v_add_f32_e32 v0, 0, v94
	v_add_f32_e32 v0, v95, v0
	v_add_f32_e32 v0, v96, v0
	v_add_f32_e32 v1, v113, v1
	v_add_f32_e32 v0, v97, v0
	v_add_f32_e32 v1, v114, v1
	s_waitcnt vmcnt(13)
	v_add_f32_e32 v0, v104, v0
	v_add_f32_e32 v1, v115, v1
	v_add_f32_e32 v0, v105, v0
	s_waitcnt vmcnt(12)
	v_add_f32_e32 v1, v116, v1
	v_add_f32_e32 v0, v106, v0
	v_add_f32_e32 v1, v117, v1
	v_add_f32_e32 v0, v107, v0
	v_add_f32_e32 v1, v118, v1
	s_waitcnt vmcnt(11)
	v_add_f32_e32 v0, v120, v0
	v_add_f32_e32 v1, v119, v1
	v_add_f32_e32 v0, v121, v0
	s_waitcnt vmcnt(10)
	v_add_f32_e32 v1, v124, v1
	v_add_f32_e32 v0, v122, v0
	v_add_f32_e32 v1, v125, v1
	v_add_f32_e32 v0, v123, v0
	v_add_f32_e32 v1, v126, v1
	s_waitcnt vmcnt(9)
	v_add_f32_e32 v0, v134, v0
	v_add_f32_e32 v1, v127, v1
	v_add_f32_e32 v0, v135, v0
	s_waitcnt vmcnt(8)
	v_add_f32_e32 v1, v40, v1
	v_add_f32_e32 v0, v136, v0
	v_add_f32_e32 v1, v41, v1
	v_add_f32_e32 v0, v137, v0
	v_add_f32_e32 v1, v42, v1
	s_waitcnt vmcnt(7)
	v_add_f32_e32 v0, v36, v0
	v_add_f32_e32 v1, v43, v1
	v_add_f32_e32 v0, v37, v0
	s_waitcnt vmcnt(6)
	v_add_f32_e32 v1, v32, v1
	v_add_f32_e32 v0, v38, v0
	v_add_f32_e32 v1, v33, v1
	v_add_f32_e32 v0, v39, v0
	v_add_f32_e32 v1, v34, v1
	s_waitcnt vmcnt(5)
	v_add_f32_e32 v0, v28, v0
	v_add_f32_e32 v1, v35, v1
	v_add_f32_e32 v0, v29, v0
	s_waitcnt vmcnt(4)
	v_add_f32_e32 v1, v24, v1
	v_add_f32_e32 v0, v30, v0
	v_add_f32_e32 v1, v25, v1
	v_add_f32_e32 v0, v31, v0
	v_add_f32_e32 v1, v26, v1
	s_waitcnt vmcnt(3)
	v_add_f32_e32 v0, v20, v0
	v_add_f32_e32 v1, v27, v1
	v_add_f32_e32 v0, v21, v0
	s_waitcnt vmcnt(2)
	v_add_f32_e32 v1, v16, v1
	v_add_f32_e32 v0, v22, v0
	v_add_f32_e32 v1, v17, v1
	v_add_f32_e32 v0, v23, v0
	v_add_f32_e32 v1, v18, v1
	s_waitcnt vmcnt(1)
	v_add_f32_e32 v0, v12, v0
	v_add_f32_e32 v1, v19, v1
	v_add_f32_e32 v0, v13, v0
	s_waitcnt vmcnt(0)
	v_add_f32_e32 v1, v8, v1
	v_add_f32_e32 v0, v14, v0
	v_add_f32_e32 v1, v9, v1
	v_add_f32_e32 v0, v15, v0
	v_add_f32_e32 v1, v10, v1
	ds_bpermute_b32 v2, v89, v0
	v_add_f32_e32 v1, v11, v1
	ds_bpermute_b32 v3, v89, v1
	s_waitcnt lgkmcnt(1)
	v_add_f32_e32 v0, v0, v2
	ds_bpermute_b32 v2, v145, v0
	s_waitcnt lgkmcnt(1)
	v_add_f32_e32 v1, v1, v3
	ds_bpermute_b32 v3, v145, v1
	s_waitcnt lgkmcnt(1)
	v_add_f32_e32 v0, v0, v2
	ds_bpermute_b32 v2, v146, v0
	s_waitcnt lgkmcnt(1)
	v_add_f32_e32 v1, v1, v3
	ds_bpermute_b32 v3, v146, v1
	s_waitcnt lgkmcnt(1)
	v_add_f32_e32 v0, v0, v2
	ds_bpermute_b32 v2, v147, v0
	s_waitcnt lgkmcnt(1)
	v_add_f32_e32 v1, v1, v3
	ds_bpermute_b32 v3, v147, v1
	s_waitcnt lgkmcnt(1)
	v_add_f32_e32 v0, v0, v2
	ds_bpermute_b32 v2, v148, v0
	s_waitcnt lgkmcnt(1)
	v_add_f32_e32 v1, v1, v3
	ds_bpermute_b32 v3, v148, v1
	s_waitcnt lgkmcnt(1)
	v_add_f32_e32 v87, v0, v2
	ds_bpermute_b32 v98, v149, v87
	s_waitcnt lgkmcnt(1)
	v_add_f32_e32 v99, v1, v3
	ds_bpermute_b32 v100, v149, v99
	global_load_dwordx4 v[0:3], v[64:65], off
	global_load_dwordx4 v[4:7], v[66:67], off
	s_waitcnt lgkmcnt(1)
	v_add_f32_e32 v87, v87, v98
	v_mul_f32_e32 v138, 0x3a000000, v87
	s_waitcnt lgkmcnt(0)
; __device__ __forceinline__ void ln_stats(const float (&v)[32], float& mean, float& rstd) {
;   float s = 0.f;
; #pragma unroll
;   for (int i = 0; i < 32; i++) s += v[i];
;   mean = wave_sum(s) * (1.f / DM);
;   float q = 0.f;
; #pragma unroll
;   for (int i = 0; i < 32; i++) { float d = v[i] - mean; q += d * d; }
;   rstd = rsqrtf(wave_sum(q) * (1.f / DM) + 1e-5f);
; }
	v_add_f32_e32 v87, v99, v100
	v_mul_f32_e32 v140, 0x3a000000, v87
	v_pk_add_f32 v[102:103], v[94:95], v[138:139] op_sel_hi:[1,0] neg_lo:[0,1] neg_hi:[0,1]
	v_pk_add_f32 v[162:163], v[112:113], v[140:141] op_sel_hi:[1,0] neg_lo:[0,1] neg_hi:[0,1]
	v_pk_add_f32 v[100:101], v[96:97], v[138:139] op_sel_hi:[1,0] neg_lo:[0,1] neg_hi:[0,1]
	v_pk_add_f32 v[96:97], v[134:135], v[138:139] op_sel_hi:[1,0] neg_lo:[0,1] neg_hi:[0,1]
	v_mov_b32_e32 v135, v103
	v_mov_b32_e32 v134, v163
	v_pk_add_f32 v[98:99], v[106:107], v[138:139] op_sel_hi:[1,0] neg_lo:[0,1] neg_hi:[0,1]
	v_pk_add_f32 v[108:109], v[122:123], v[138:139] op_sel_hi:[1,0] neg_lo:[0,1] neg_hi:[0,1]
	v_pk_add_f32 v[160:161], v[114:115], v[140:141] op_sel_hi:[1,0] neg_lo:[0,1] neg_hi:[0,1]
	v_pk_add_f32 v[106:107], v[118:119], v[140:141] op_sel_hi:[1,0] neg_lo:[0,1] neg_hi:[0,1]
	v_mov_b32_e32 v123, v102
	v_pk_add_f32 v[118:119], v[124:125], v[140:141] op_sel_hi:[1,0] neg_lo:[0,1] neg_hi:[0,1]
	v_mov_b32_e32 v122, v162
	v_pk_mul_f32 v[124:125], v[134:135], v[134:135]
	v_mov_b32_e32 v113, v100
	v_mov_b32_e32 v112, v160
	v_pk_fma_f32 v[122:123], v[122:123], v[122:123], v[124:125]
	v_pk_add_f32 v[104:105], v[104:105], v[138:139] op_sel_hi:[1,0] neg_lo:[0,1] neg_hi:[0,1]
	v_pk_add_f32 v[142:143], v[116:117], v[140:141] op_sel_hi:[1,0] neg_lo:[0,1] neg_hi:[0,1]
	v_mov_b32_e32 v117, v101
	v_mov_b32_e32 v116, v161
	v_pk_fma_f32 v[112:113], v[112:113], v[112:113], v[122:123]
	v_mov_b32_e32 v171, v104
	v_mov_b32_e32 v170, v142
	v_pk_fma_f32 v[112:113], v[116:117], v[116:117], v[112:113]
	v_mov_b32_e32 v173, v105
	v_mov_b32_e32 v172, v143
	v_pk_fma_f32 v[112:113], v[170:171], v[170:171], v[112:113]
	v_pk_add_f32 v[94:95], v[136:137], v[138:139] op_sel_hi:[1,0] neg_lo:[0,1] neg_hi:[0,1]
	v_mov_b32_e32 v137, v98
	v_mov_b32_e32 v136, v106
	v_pk_fma_f32 v[112:113], v[172:173], v[172:173], v[112:113]
	v_pk_add_f32 v[110:111], v[120:121], v[138:139] op_sel_hi:[1,0] neg_lo:[0,1] neg_hi:[0,1]
	v_mov_b32_e32 v121, v99
	v_mov_b32_e32 v120, v107
	v_pk_fma_f32 v[122:123], v[136:137], v[136:137], v[112:113]
	v_pk_add_f32 v[116:117], v[32:33], v[140:141] op_sel_hi:[1,0] neg_lo:[0,1] neg_hi:[0,1]
	v_pk_fma_f32 v[32:33], v[120:121], v[120:121], v[122:123]
	v_mov_b32_e32 v124, v118
	v_mov_b32_e32 v125, v110
	v_pk_add_f32 v[114:115], v[126:127], v[140:141] op_sel_hi:[1,0] neg_lo:[0,1] neg_hi:[0,1]
	v_mov_b32_e32 v126, v119
	v_mov_b32_e32 v127, v111
	v_pk_fma_f32 v[32:33], v[124:125], v[124:125], v[32:33]
	v_mov_b32_e32 v120, v114
	v_mov_b32_e32 v121, v108
	v_pk_fma_f32 v[32:33], v[126:127], v[126:127], v[32:33]
	v_pk_add_f32 v[112:113], v[40:41], v[140:141] op_sel_hi:[1,0] neg_lo:[0,1] neg_hi:[0,1]
	v_mov_b32_e32 v122, v115
	v_mov_b32_e32 v123, v109
	v_pk_fma_f32 v[32:33], v[120:121], v[120:121], v[32:33]
	v_mov_b32_e32 v124, v112
	v_pk_fma_f32 v[32:33], v[122:123], v[122:123], v[32:33]
	v_mov_b32_e32 v125, v96
	v_pk_add_f32 v[42:43], v[42:43], v[140:141] op_sel_hi:[1,0] neg_lo:[0,1] neg_hi:[0,1]
	v_mov_b32_e32 v126, v113
	v_mov_b32_e32 v127, v97
	v_pk_fma_f32 v[32:33], v[124:125], v[124:125], v[32:33]
	v_mov_b32_e32 v120, v42
	v_mov_b32_e32 v121, v94
	v_pk_fma_f32 v[32:33], v[126:127], v[126:127], v[32:33]
	v_pk_add_f32 v[36:37], v[36:37], v[138:139] op_sel_hi:[1,0] neg_lo:[0,1] neg_hi:[0,1]
	v_mov_b32_e32 v122, v43
	v_mov_b32_e32 v123, v95
	v_pk_fma_f32 v[32:33], v[120:121], v[120:121], v[32:33]
	v_mov_b32_e32 v120, v116
	v_pk_fma_f32 v[32:33], v[122:123], v[122:123], v[32:33]
	v_mov_b32_e32 v121, v36
	v_pk_add_f32 v[38:39], v[38:39], v[138:139] op_sel_hi:[1,0] neg_lo:[0,1] neg_hi:[0,1]
	v_pk_add_f32 v[40:41], v[34:35], v[140:141] op_sel_hi:[1,0] neg_lo:[0,1] neg_hi:[0,1]
	v_mov_b32_e32 v122, v117
	v_mov_b32_e32 v123, v37
	v_pk_fma_f32 v[32:33], v[120:121], v[120:121], v[32:33]
	v_mov_b32_e32 v34, v40
	v_mov_b32_e32 v35, v38
	v_pk_fma_f32 v[32:33], v[122:123], v[122:123], v[32:33]
	v_pk_add_f32 v[120:121], v[30:31], v[138:139] op_sel_hi:[1,0] neg_lo:[0,1] neg_hi:[0,1]
	v_pk_add_f32 v[122:123], v[28:29], v[138:139] op_sel_hi:[1,0] neg_lo:[0,1] neg_hi:[0,1]
	v_pk_add_f32 v[136:137], v[24:25], v[140:141] op_sel_hi:[1,0] neg_lo:[0,1] neg_hi:[0,1]
	v_mov_b32_e32 v28, v41
	v_mov_b32_e32 v29, v39
	v_pk_fma_f32 v[30:31], v[34:35], v[34:35], v[32:33]
	v_mov_b32_e32 v34, v136
	v_pk_fma_f32 v[28:29], v[28:29], v[28:29], v[30:31]
	v_mov_b32_e32 v35, v122
	v_pk_add_f32 v[134:135], v[26:27], v[140:141] op_sel_hi:[1,0] neg_lo:[0,1] neg_hi:[0,1]
	v_pk_add_f32 v[124:125], v[22:23], v[138:139] op_sel_hi:[1,0] neg_lo:[0,1] neg_hi:[0,1]
	v_pk_add_f32 v[126:127], v[20:21], v[138:139] op_sel_hi:[1,0] neg_lo:[0,1] neg_hi:[0,1]
	v_pk_add_f32 v[14:15], v[14:15], v[138:139] op_sel_hi:[1,0] neg_lo:[0,1] neg_hi:[0,1]
	v_pk_add_f32 v[12:13], v[12:13], v[138:139] op_sel_hi:[1,0] neg_lo:[0,1] neg_hi:[0,1]
	v_mov_b32_e32 v138, v137
	v_mov_b32_e32 v139, v123
	v_pk_fma_f32 v[28:29], v[34:35], v[34:35], v[28:29]
	v_mov_b32_e32 v30, v134
	v_mov_b32_e32 v31, v120
	v_pk_fma_f32 v[28:29], v[138:139], v[138:139], v[28:29]
	v_pk_add_f32 v[16:17], v[16:17], v[140:141] op_sel_hi:[1,0] neg_lo:[0,1] neg_hi:[0,1]
	v_mov_b32_e32 v32, v135
	v_mov_b32_e32 v33, v121
	v_pk_fma_f32 v[28:29], v[30:31], v[30:31], v[28:29]
	v_mov_b32_e32 v34, v16
	v_pk_fma_f32 v[28:29], v[32:33], v[32:33], v[28:29]
	v_mov_b32_e32 v35, v126
	v_pk_add_f32 v[18:19], v[18:19], v[140:141] op_sel_hi:[1,0] neg_lo:[0,1] neg_hi:[0,1]
	v_mov_b32_e32 v138, v17
	v_mov_b32_e32 v139, v127
	v_pk_fma_f32 v[28:29], v[34:35], v[34:35], v[28:29]
	v_pk_add_f32 v[8:9], v[8:9], v[140:141] op_sel_hi:[1,0] neg_lo:[0,1] neg_hi:[0,1]
	v_mov_b32_e32 v30, v18
	v_mov_b32_e32 v31, v124
	v_pk_fma_f32 v[28:29], v[138:139], v[138:139], v[28:29]
	v_pk_mul_f32 v[22:23], v[12:13], v[12:13]
	v_pk_mul_f32 v[26:27], v[8:9], v[8:9]
	v_mov_b32_e32 v32, v19
	v_mov_b32_e32 v33, v125
	v_pk_fma_f32 v[28:29], v[30:31], v[30:31], v[28:29]
	v_pk_add_f32 v[10:11], v[10:11], v[140:141] op_sel_hi:[1,0] neg_lo:[0,1] neg_hi:[0,1]
	v_pk_fma_f32 v[28:29], v[32:33], v[32:33], v[28:29]
	v_mov_b32_e32 v30, v26
	v_mov_b32_e32 v31, v22
	v_pk_mul_f32 v[20:21], v[14:15], v[14:15]
	v_pk_mul_f32 v[24:25], v[10:11], v[10:11]
	v_pk_add_f32 v[28:29], v[30:31], v[28:29]
	v_mov_b32_e32 v22, v27
	v_pk_add_f32 v[22:23], v[22:23], v[28:29]
	v_mov_b32_e32 v26, v24
	v_mov_b32_e32 v27, v20
	v_pk_add_f32 v[22:23], v[26:27], v[22:23]
	v_mov_b32_e32 v20, v25
	v_pk_add_f32 v[20:21], v[20:21], v[22:23]
	ds_bpermute_b32 v23, v89, v21
	ds_bpermute_b32 v22, v89, v20
	v_lshlrev_b64 v[24:25], 12, v[90:91]
	v_lshl_add_u64 v[138:139], v[84:85], 0, v[24:25]
	v_mov_b64_e32 v[172:173], v[48:49]
	s_waitcnt lgkmcnt(0)
; __device__ void phase_ln2_route(const Params& p) {
;     ...
; #pragma unroll
;     for (int i = 0; i < 8; i++) {
;       int c = CH(i) + lane * 4;
;       f32x4 g = *(const f32x4*)(p.ln2_g + c), b = *(const f32x4*)(p.ln2_b + c);
; #pragma unroll
;       for (int q = 0; q < 2; q++) {
;         f32x4 o4;
; #pragma unroll
;         for (int e = 0; e < 4; e++) { o4[e] = (v[q][i * 4 + e] - mean[q]) * rstd[q] * g[e] + b[e]; v[q][i * 4 + e] = o4[e]; }
;         store_bf4(p.hb() + (long)(rb + q) * DM + c, o4[0], o4[1], o4[2], o4[3]);
;       }
;     }
	v_pk_add_f32 v[20:21], v[20:21], v[22:23]
	ds_bpermute_b32 v23, v145, v21
	ds_bpermute_b32 v22, v145, v20
	s_waitcnt lgkmcnt(0)
	v_pk_add_f32 v[20:21], v[20:21], v[22:23]
	ds_bpermute_b32 v23, v146, v21
	ds_bpermute_b32 v22, v146, v20
	s_waitcnt lgkmcnt(0)
	v_pk_add_f32 v[20:21], v[20:21], v[22:23]
	ds_bpermute_b32 v23, v147, v21
	ds_bpermute_b32 v22, v147, v20
	s_waitcnt lgkmcnt(0)
	v_pk_add_f32 v[20:21], v[20:21], v[22:23]
	ds_bpermute_b32 v23, v148, v21
	ds_bpermute_b32 v22, v148, v20
	s_waitcnt lgkmcnt(0)
	v_pk_add_f32 v[20:21], v[20:21], v[22:23]
	ds_bpermute_b32 v23, v149, v21
	ds_bpermute_b32 v22, v149, v20
	s_waitcnt lgkmcnt(0)
	v_pk_add_f32 v[20:21], v[20:21], v[22:23]
	s_nop 0
	v_pk_fma_f32 v[20:21], v[20:21], s[42:43], v[88:89] op_sel_hi:[1,0,0]
	s_nop 0
	v_mul_f32_e32 v22, 0x4b800000, v21
	v_cmp_gt_f32_e32 vcc, s68, v21
	s_nop 1
	v_cndmask_b32_e32 v21, v21, v22, vcc
	v_rsq_f32_e32 v21, v21
	v_lshlrev_b64 v[22:23], 12, v[92:93]
	v_lshl_add_u64 v[140:141], v[84:85], 0, v[22:23]
	v_mul_f32_e32 v22, 0x45800000, v21
	v_cndmask_b32_e32 v144, v21, v22, vcc
	v_pk_mul_f32 v[22:23], v[102:103], v[144:145] op_sel_hi:[1,0]
	v_mul_f32_e32 v21, 0x4b800000, v20
	v_cmp_gt_f32_e32 vcc, s68, v20
	s_waitcnt vmcnt(0)
	v_pk_fma_f32 v[102:103], v[0:1], v[22:23], v[4:5]
	v_pk_mul_f32 v[22:23], v[100:101], v[144:145] op_sel_hi:[1,0]
	v_cndmask_b32_e32 v20, v20, v21, vcc
	v_pk_fma_f32 v[100:101], v[2:3], v[22:23], v[6:7]
	v_rsq_f32_e32 v22, v20
	v_cvt_pk_bf16_f32 v20, v102, v103
	v_cvt_pk_bf16_f32 v21, v100, v101
	global_store_dwordx2 v[138:139], v[20:21], off
	v_mul_f32_e32 v20, 0x45800000, v22
	v_cndmask_b32_e32 v170, v22, v20, vcc
	v_pk_mul_f32 v[20:21], v[162:163], v[170:171] op_sel_hi:[1,0]
	v_pk_mul_f32 v[24:25], v[104:105], v[144:145] op_sel_hi:[1,0]
	v_pk_fma_f32 v[22:23], v[0:1], v[20:21], v[4:5]
	v_pk_mul_f32 v[0:1], v[160:161], v[170:171] op_sel_hi:[1,0]
	v_pk_mul_f32 v[26:27], v[98:99], v[144:145] op_sel_hi:[1,0]
	v_pk_fma_f32 v[20:21], v[2:3], v[0:1], v[6:7]
	v_cvt_pk_bf16_f32 v0, v22, v23
	v_cvt_pk_bf16_f32 v1, v20, v21
	global_store_dwordx2 v[140:141], v[0:1], off
	global_load_dwordx4 v[0:3], v[64:65], off offset:1024
	s_nop 0
	global_load_dwordx4 v[4:7], v[66:67], off offset:1024
	v_pk_mul_f32 v[28:29], v[142:143], v[170:171] op_sel_hi:[1,0]
	v_pk_mul_f32 v[30:31], v[106:107], v[170:171] op_sel_hi:[1,0]
	v_pk_mul_f32 v[32:33], v[118:119], v[170:171] op_sel_hi:[1,0]
	v_pk_mul_f32 v[34:35], v[114:115], v[170:171] op_sel_hi:[1,0]
	v_pk_mul_f32 v[92:93], v[112:113], v[170:171] op_sel_hi:[1,0]
	v_pk_mul_f32 v[42:43], v[42:43], v[170:171] op_sel_hi:[1,0]
	v_pk_mul_f32 v[36:37], v[36:37], v[144:145] op_sel_hi:[1,0]
	v_pk_mul_f32 v[38:39], v[38:39], v[144:145] op_sel_hi:[1,0]
	v_pk_mul_f32 v[40:41], v[40:41], v[170:171] op_sel_hi:[1,0]
	v_pk_mul_f32 v[16:17], v[16:17], v[170:171] op_sel_hi:[1,0]
	v_pk_mul_f32 v[18:19], v[18:19], v[170:171] op_sel_hi:[1,0]
	v_pk_mul_f32 v[12:13], v[12:13], v[144:145] op_sel_hi:[1,0]
	v_pk_mul_f32 v[14:15], v[14:15], v[144:145] op_sel_hi:[1,0]
	v_pk_mul_f32 v[8:9], v[8:9], v[170:171] op_sel_hi:[1,0]
	v_pk_mul_f32 v[10:11], v[10:11], v[170:171] op_sel_hi:[1,0]
	v_mov_b64_e32 v[142:143], v[46:47]
	s_waitcnt vmcnt(0)
	v_pk_fma_f32 v[104:105], v[0:1], v[24:25], v[4:5]
	v_pk_fma_f32 v[106:107], v[2:3], v[26:27], v[6:7]
	v_pk_fma_f32 v[26:27], v[0:1], v[28:29], v[4:5]
	v_pk_fma_f32 v[24:25], v[2:3], v[30:31], v[6:7]
	v_cvt_pk_bf16_f32 v0, v104, v105
	v_cvt_pk_bf16_f32 v1, v106, v107
	v_cvt_pk_bf16_f32 v2, v26, v27
	v_cvt_pk_bf16_f32 v3, v24, v25
	global_store_dwordx2 v[138:139], v[0:1], off offset:512
	global_store_dwordx2 v[140:141], v[2:3], off offset:512
	global_load_dwordx4 v[0:3], v[64:65], off offset:2048
	s_nop 0
	global_load_dwordx4 v[4:7], v[66:67], off offset:2048
	v_pk_mul_f32 v[28:29], v[110:111], v[144:145] op_sel_hi:[1,0]
	v_pk_mul_f32 v[30:31], v[108:109], v[144:145] op_sel_hi:[1,0]
	s_waitcnt vmcnt(0)
	v_pk_fma_f32 v[108:109], v[0:1], v[28:29], v[4:5]
	v_pk_fma_f32 v[110:111], v[2:3], v[30:31], v[6:7]
	v_pk_fma_f32 v[30:31], v[0:1], v[32:33], v[4:5]
	v_pk_fma_f32 v[28:29], v[2:3], v[34:35], v[6:7]
	v_cvt_pk_bf16_f32 v0, v108, v109
	v_cvt_pk_bf16_f32 v1, v110, v111
	v_cvt_pk_bf16_f32 v2, v30, v31
	v_cvt_pk_bf16_f32 v3, v28, v29
	global_store_dwordx2 v[138:139], v[0:1], off offset:1024
	global_store_dwordx2 v[140:141], v[2:3], off offset:1024
	global_load_dwordx4 v[0:3], v[64:65], off offset:3072
	s_nop 0
	global_load_dwordx4 v[4:7], v[66:67], off offset:3072
	v_pk_mul_f32 v[32:33], v[96:97], v[144:145] op_sel_hi:[1,0]
	v_pk_mul_f32 v[34:35], v[94:95], v[144:145] op_sel_hi:[1,0]
	v_pk_mul_f32 v[94:95], v[134:135], v[170:171] op_sel_hi:[1,0]
	s_waitcnt vmcnt(0)
	v_pk_fma_f32 v[112:113], v[0:1], v[32:33], v[4:5]
	v_pk_fma_f32 v[114:115], v[2:3], v[34:35], v[6:7]
	v_pk_fma_f32 v[34:35], v[0:1], v[92:93], v[4:5]
	v_pk_fma_f32 v[32:33], v[2:3], v[42:43], v[6:7]
	v_cvt_pk_bf16_f32 v0, v112, v113
	v_cvt_pk_bf16_f32 v1, v114, v115
	v_cvt_pk_bf16_f32 v2, v34, v35
	v_cvt_pk_bf16_f32 v3, v32, v33
	global_store_dwordx2 v[138:139], v[0:1], off offset:1536
	global_store_dwordx2 v[140:141], v[2:3], off offset:1536
	global_load_dwordx4 v[0:3], v[68:69], off
	s_nop 0
	global_load_dwordx4 v[4:7], v[70:71], off
	v_pk_mul_f32 v[42:43], v[116:117], v[170:171] op_sel_hi:[1,0]
	v_pk_mul_f32 v[92:93], v[136:137], v[170:171] op_sel_hi:[1,0]
	s_waitcnt vmcnt(0)
; __device__ __forceinline__ gv4p launder_g(const float* q) { asm volatile("" : "+v"(q)); return (gv4p)q; }
; __device__ void phase_ln2_route(const Params& p) {
;     ...
; #pragma unroll
;     for (int i = 0; i < 8; i++) {
;       int c = CH(i) + lane * 4;
;       f32x4 g = *(const f32x4*)(p.ln2_g + c), b = *(const f32x4*)(p.ln2_b + c);
; #pragma unroll
;       for (int q = 0; q < 2; q++) {
;         f32x4 o4;
; #pragma unroll
;         for (int e = 0; e < 4; e++) { o4[e] = (v[q][i * 4 + e] - mean[q]) * rstd[q] * g[e] + b[e]; v[q][i * 4 + e] = o4[e]; }
;         store_bf4(p.hb() + (long)(rb + q) * DM + c, o4[0], o4[1], o4[2], o4[3]);
;       }
;     }
;     float lg[2][8];
;     {
;       f32x4 wb[2][8];
;       {
;         gv4p wp = launder_g(wgT + lane * 4);
; #pragma unroll
;         for (int i = 0; i < 8; i++) wb[0][i] = wp[CH(i) >> 2];
;       }
; #pragma unroll
;       for (int g = 0; g < 8; g++) {
;         if (g + 1 < 8) {
;           gv4p wp = launder_g(wgT + (g + 1) * DM + lane * 4);
; #pragma unroll
;           for (int i = 0; i < 8; i++) wb[(g + 1) & 1][i] = wp[CH(i) >> 2];
;         }
;         __builtin_amdgcn_sched_barrier(0);
;         float s0 = 0.f, s1 = 0.f;
; #pragma unroll
;         for (int i = 0; i < 8; i++)
; #pragma unroll
;           for (int e = 0; e < 4; e++) { s0 += wb[g & 1][i][e] * v[0][i * 4 + e]; s1 += wb[g & 1][i][e] * v[1][i * 4 + e]; }
;         lg[0][g] = s0; lg[1][g] = s1;
;         __builtin_amdgcn_sched_barrier(0);
;       }
;     }
	v_pk_fma_f32 v[116:117], v[0:1], v[36:37], v[4:5]
	v_pk_fma_f32 v[118:119], v[2:3], v[38:39], v[6:7]
	v_pk_fma_f32 v[38:39], v[0:1], v[42:43], v[4:5]
	v_pk_fma_f32 v[36:37], v[2:3], v[40:41], v[6:7]
	v_cvt_pk_bf16_f32 v0, v116, v117
	v_cvt_pk_bf16_f32 v1, v118, v119
	v_cvt_pk_bf16_f32 v2, v38, v39
	v_cvt_pk_bf16_f32 v3, v36, v37
	global_store_dwordx2 v[138:139], v[0:1], off offset:2048
	global_store_dwordx2 v[140:141], v[2:3], off offset:2048
	global_load_dwordx4 v[0:3], v[72:73], off
	s_nop 0
	global_load_dwordx4 v[4:7], v[74:75], off
	v_pk_mul_f32 v[40:41], v[122:123], v[144:145] op_sel_hi:[1,0]
	v_pk_mul_f32 v[42:43], v[120:121], v[144:145] op_sel_hi:[1,0]
	s_waitcnt vmcnt(0)
	v_pk_fma_f32 v[120:121], v[0:1], v[40:41], v[4:5]
	v_pk_fma_f32 v[122:123], v[2:3], v[42:43], v[6:7]
	v_pk_fma_f32 v[42:43], v[0:1], v[92:93], v[4:5]
	v_pk_fma_f32 v[40:41], v[2:3], v[94:95], v[6:7]
	v_cvt_pk_bf16_f32 v0, v120, v121
	v_cvt_pk_bf16_f32 v1, v122, v123
	v_cvt_pk_bf16_f32 v2, v42, v43
	v_cvt_pk_bf16_f32 v3, v40, v41
	global_store_dwordx2 v[138:139], v[0:1], off offset:2560
	global_store_dwordx2 v[140:141], v[2:3], off offset:2560
	global_load_dwordx4 v[0:3], v[76:77], off
	s_nop 0
	global_load_dwordx4 v[4:7], v[78:79], off
	v_pk_mul_f32 v[92:93], v[126:127], v[144:145] op_sel_hi:[1,0]
	v_pk_mul_f32 v[94:95], v[124:125], v[144:145] op_sel_hi:[1,0]
	s_waitcnt vmcnt(0)
	v_pk_fma_f32 v[124:125], v[0:1], v[92:93], v[4:5]
	v_pk_fma_f32 v[126:127], v[2:3], v[94:95], v[6:7]
	v_pk_fma_f32 v[94:95], v[0:1], v[16:17], v[4:5]
	v_pk_fma_f32 v[92:93], v[2:3], v[18:19], v[6:7]
	v_cvt_pk_bf16_f32 v0, v124, v125
	v_cvt_pk_bf16_f32 v1, v126, v127
	v_cvt_pk_bf16_f32 v2, v94, v95
	v_cvt_pk_bf16_f32 v3, v92, v93
	global_store_dwordx2 v[138:139], v[0:1], off offset:3072
	global_store_dwordx2 v[140:141], v[2:3], off offset:3072
	global_load_dwordx4 v[0:3], v[80:81], off
	s_nop 0
	global_load_dwordx4 v[4:7], v[82:83], off
	s_waitcnt vmcnt(0)
	v_pk_fma_f32 v[136:137], v[0:1], v[12:13], v[4:5]
	v_pk_fma_f32 v[134:135], v[2:3], v[14:15], v[6:7]
	v_pk_fma_f32 v[98:99], v[0:1], v[8:9], v[4:5]
	v_pk_fma_f32 v[96:97], v[2:3], v[10:11], v[6:7]
	v_cvt_pk_bf16_f32 v0, v136, v137
	v_cvt_pk_bf16_f32 v1, v134, v135
	v_cvt_pk_bf16_f32 v2, v98, v99
	v_cvt_pk_bf16_f32 v3, v96, v97
	global_store_dwordx2 v[138:139], v[0:1], off offset:3584
	global_store_dwordx2 v[140:141], v[2:3], off offset:3584
	global_load_dwordx4 v[4:7], v[142:143], off
	global_load_dwordx4 v[12:15], v[142:143], off offset:1024
	global_load_dwordx4 v[16:19], v[142:143], off offset:2048
	global_load_dwordx4 v[138:141], v[142:143], off offset:3072
	v_add_co_u32_e32 v0, vcc, s65, v142
	s_nop 1
	v_addc_co_u32_e32 v1, vcc, 0, v143, vcc
	global_load_dwordx4 v[160:163], v[0:1], off
	global_load_dwordx4 v[178:181], v[0:1], off offset:1024
	global_load_dwordx4 v[182:185], v[0:1], off offset:2048
	global_load_dwordx4 v[186:189], v[0:1], off offset:3072
	global_load_dwordx4 v[190:193], v[172:173], off
	global_load_dwordx4 v[194:197], v[172:173], off offset:1024
	global_load_dwordx4 v[198:201], v[172:173], off offset:2048
	global_load_dwordx4 v[202:205], v[172:173], off offset:3072
	v_add_co_u32_e32 v0, vcc, s65, v172
	s_nop 1
	v_addc_co_u32_e32 v1, vcc, 0, v173, vcc
	global_load_dwordx4 v[206:209], v[0:1], off
	global_load_dwordx4 v[210:213], v[0:1], off offset:1024
	global_load_dwordx4 v[8:11], v[0:1], off offset:2048
	s_nop 0
	global_load_dwordx4 v[0:3], v[0:1], off offset:3072
	s_waitcnt vmcnt(15)
	v_fma_f32 v91, v102, v4, 0
	v_fma_f32 v87, v4, v22, 0
	v_fmac_f32_e32 v91, v103, v5
	v_fmac_f32_e32 v87, v5, v23
	v_fmac_f32_e32 v91, v100, v6
	v_fmac_f32_e32 v87, v6, v20
	v_fmac_f32_e32 v91, v101, v7
	v_fmac_f32_e32 v87, v7, v21
	s_waitcnt vmcnt(14)
	v_fmac_f32_e32 v91, v104, v12
	v_fmac_f32_e32 v87, v12, v26
	v_fmac_f32_e32 v91, v105, v13
	v_fmac_f32_e32 v87, v13, v27
	v_fmac_f32_e32 v91, v106, v14
	v_fmac_f32_e32 v87, v14, v24
	v_fmac_f32_e32 v91, v107, v15
	v_fmac_f32_e32 v87, v15, v25
	s_waitcnt vmcnt(13)
	v_fmac_f32_e32 v91, v108, v16
	v_fmac_f32_e32 v87, v16, v30
	v_fmac_f32_e32 v91, v109, v17
	v_fmac_f32_e32 v87, v17, v31
	v_fmac_f32_e32 v91, v110, v18
	v_fmac_f32_e32 v87, v18, v28
	v_fmac_f32_e32 v91, v111, v19
	v_fmac_f32_e32 v87, v19, v29
	s_waitcnt vmcnt(12)
	v_fmac_f32_e32 v91, v112, v138
	v_fmac_f32_e32 v87, v138, v34
	v_fmac_f32_e32 v91, v113, v139
	v_fmac_f32_e32 v87, v139, v35
	v_fmac_f32_e32 v91, v114, v140
	v_fmac_f32_e32 v87, v140, v32
	v_fmac_f32_e32 v91, v115, v141
	v_fmac_f32_e32 v87, v141, v33
	s_waitcnt vmcnt(11)
	v_fmac_f32_e32 v91, v116, v160
	v_fmac_f32_e32 v87, v160, v38
	v_fmac_f32_e32 v91, v117, v161
	v_fmac_f32_e32 v87, v161, v39
	v_fmac_f32_e32 v91, v118, v162
	v_fmac_f32_e32 v87, v162, v36
	v_fmac_f32_e32 v91, v119, v163
	v_fmac_f32_e32 v87, v163, v37
	s_waitcnt vmcnt(10)
	v_fmac_f32_e32 v91, v120, v178
	v_fmac_f32_e32 v87, v178, v42
	v_fmac_f32_e32 v91, v121, v179
	v_fmac_f32_e32 v87, v179, v43
	v_fmac_f32_e32 v91, v122, v180
	v_fmac_f32_e32 v87, v180, v40
	v_fmac_f32_e32 v91, v123, v181
	v_fmac_f32_e32 v87, v181, v41
	s_waitcnt vmcnt(9)
	v_fmac_f32_e32 v91, v124, v182
	v_fmac_f32_e32 v87, v182, v94
	v_fmac_f32_e32 v91, v125, v183
	v_fmac_f32_e32 v87, v183, v95
	v_fmac_f32_e32 v91, v126, v184
	v_fmac_f32_e32 v87, v184, v92
	v_fmac_f32_e32 v91, v127, v185
	v_fmac_f32_e32 v87, v185, v93
	s_waitcnt vmcnt(8)
; __device__ __forceinline__ gv4p launder_g(const float* q) { asm volatile("" : "+v"(q)); return (gv4p)q; }
; __device__ void phase_ln2_route(const Params& p) {
;     ...
; #pragma unroll
;       for (int g = 0; g < 8; g++) {
;         if (g + 1 < 8) {
;           gv4p wp = launder_g(wgT + (g + 1) * DM + lane * 4);
; #pragma unroll
;           for (int i = 0; i < 8; i++) wb[(g + 1) & 1][i] = wp[CH(i) >> 2];
;         }
;         __builtin_amdgcn_sched_barrier(0);
;         float s0 = 0.f, s1 = 0.f;
; #pragma unroll
;         for (int i = 0; i < 8; i++)
; #pragma unroll
;           for (int e = 0; e < 4; e++) { s0 += wb[g & 1][i][e] * v[0][i * 4 + e]; s1 += wb[g & 1][i][e] * v[1][i * 4 + e]; }
;         lg[0][g] = s0; lg[1][g] = s1;
;         __builtin_amdgcn_sched_barrier(0);
;       }
	v_fmac_f32_e32 v91, v136, v186
	v_fmac_f32_e32 v87, v186, v98
	v_fmac_f32_e32 v91, v137, v187
	v_fmac_f32_e32 v87, v187, v99
	v_fmac_f32_e32 v91, v134, v188
	v_fmac_f32_e32 v87, v188, v96
	v_fmac_f32_e32 v91, v135, v189
	v_fmac_f32_e32 v87, v189, v97
	v_mov_b64_e32 v[4:5], v[50:51]
	global_load_dwordx4 v[16:19], v[4:5], off
	global_load_dwordx4 v[160:163], v[4:5], off offset:1024
	global_load_dwordx4 v[178:181], v[4:5], off offset:2048
	global_load_dwordx4 v[182:185], v[4:5], off offset:3072
	v_add_co_u32_e32 v4, vcc, s65, v4
	s_nop 1
	v_addc_co_u32_e32 v5, vcc, 0, v5, vcc
	global_load_dwordx4 v[186:189], v[4:5], off
	global_load_dwordx4 v[214:217], v[4:5], off offset:1024
	global_load_dwordx4 v[12:15], v[4:5], off offset:2048
	s_nop 0
	global_load_dwordx4 v[4:7], v[4:5], off offset:3072
	s_waitcnt vmcnt(15)
	v_fma_f32 v140, v102, v190, 0
	v_fma_f32 v138, v22, v190, 0
	v_fmac_f32_e32 v140, v103, v191
	v_fmac_f32_e32 v138, v23, v191
	v_fmac_f32_e32 v140, v100, v192
	v_fmac_f32_e32 v138, v20, v192
	v_fmac_f32_e32 v140, v101, v193
	v_fmac_f32_e32 v138, v21, v193
	s_waitcnt vmcnt(14)
	v_fmac_f32_e32 v140, v104, v194
	v_fmac_f32_e32 v138, v26, v194
	v_fmac_f32_e32 v140, v105, v195
	v_fmac_f32_e32 v138, v27, v195
	v_fmac_f32_e32 v140, v106, v196
	v_fmac_f32_e32 v138, v24, v196
	v_fmac_f32_e32 v140, v107, v197
	v_fmac_f32_e32 v138, v25, v197
	s_waitcnt vmcnt(13)
	v_fmac_f32_e32 v140, v108, v198
	v_fmac_f32_e32 v138, v30, v198
	v_fmac_f32_e32 v140, v109, v199
	v_fmac_f32_e32 v138, v31, v199
	v_fmac_f32_e32 v140, v110, v200
	v_fmac_f32_e32 v138, v28, v200
	v_fmac_f32_e32 v140, v111, v201
	v_fmac_f32_e32 v138, v29, v201
	s_waitcnt vmcnt(12)
	v_fmac_f32_e32 v140, v112, v202
	v_fmac_f32_e32 v138, v34, v202
	v_fmac_f32_e32 v140, v113, v203
	v_fmac_f32_e32 v138, v35, v203
	v_fmac_f32_e32 v140, v114, v204
	v_fmac_f32_e32 v138, v32, v204
	v_fmac_f32_e32 v140, v115, v205
	v_fmac_f32_e32 v138, v33, v205
	s_waitcnt vmcnt(11)
	v_fmac_f32_e32 v140, v116, v206
	v_fmac_f32_e32 v138, v38, v206
	v_fmac_f32_e32 v140, v117, v207
	v_fmac_f32_e32 v138, v39, v207
	v_fmac_f32_e32 v140, v118, v208
	v_fmac_f32_e32 v138, v36, v208
	v_fmac_f32_e32 v140, v119, v209
	v_fmac_f32_e32 v138, v37, v209
	s_waitcnt vmcnt(10)
	v_fmac_f32_e32 v140, v120, v210
	v_fmac_f32_e32 v138, v42, v210
	v_fmac_f32_e32 v140, v121, v211
	v_fmac_f32_e32 v138, v43, v211
	v_fmac_f32_e32 v140, v122, v212
	v_fmac_f32_e32 v138, v40, v212
	v_fmac_f32_e32 v140, v123, v213
	v_fmac_f32_e32 v138, v41, v213
	s_waitcnt vmcnt(9)
	v_fmac_f32_e32 v140, v124, v8
	v_fmac_f32_e32 v138, v94, v8
	v_fmac_f32_e32 v140, v125, v9
	v_fmac_f32_e32 v138, v95, v9
	v_fmac_f32_e32 v140, v126, v10
	v_fmac_f32_e32 v138, v92, v10
	v_fmac_f32_e32 v140, v127, v11
	v_fmac_f32_e32 v138, v93, v11
	s_waitcnt vmcnt(8)
	v_fmac_f32_e32 v140, v136, v0
	v_fmac_f32_e32 v138, v98, v0
	v_fmac_f32_e32 v140, v137, v1
	v_fmac_f32_e32 v138, v99, v1
	v_fmac_f32_e32 v140, v134, v2
	v_fmac_f32_e32 v138, v96, v2
	v_fmac_f32_e32 v140, v135, v3
	v_fmac_f32_e32 v138, v97, v3
	v_mov_b64_e32 v[0:1], v[52:53]
	global_load_dwordx4 v[190:193], v[0:1], off
	global_load_dwordx4 v[194:197], v[0:1], off offset:1024
	global_load_dwordx4 v[198:201], v[0:1], off offset:2048
	global_load_dwordx4 v[202:205], v[0:1], off offset:3072
	v_add_co_u32_e32 v0, vcc, s65, v0
	s_nop 1
	v_addc_co_u32_e32 v1, vcc, 0, v1, vcc
	global_load_dwordx4 v[206:209], v[0:1], off
	global_load_dwordx4 v[210:213], v[0:1], off offset:1024
	global_load_dwordx4 v[8:11], v[0:1], off offset:2048
	s_nop 0
	global_load_dwordx4 v[0:3], v[0:1], off offset:3072
	s_waitcnt vmcnt(15)
	v_fma_f32 v142, v102, v16, 0
	v_fma_f32 v139, v22, v16, 0
	v_fmac_f32_e32 v142, v103, v17
	v_fmac_f32_e32 v139, v23, v17
	v_fmac_f32_e32 v142, v100, v18
	v_fmac_f32_e32 v139, v20, v18
	v_fmac_f32_e32 v142, v101, v19
	v_fmac_f32_e32 v139, v21, v19
	s_waitcnt vmcnt(14)
	v_fmac_f32_e32 v142, v104, v160
	v_fmac_f32_e32 v139, v26, v160
	v_fmac_f32_e32 v142, v105, v161
	v_fmac_f32_e32 v139, v27, v161
	v_fmac_f32_e32 v142, v106, v162
	v_fmac_f32_e32 v139, v24, v162
	v_fmac_f32_e32 v142, v107, v163
	v_fmac_f32_e32 v139, v25, v163
	s_waitcnt vmcnt(13)
	v_fmac_f32_e32 v142, v108, v178
	v_fmac_f32_e32 v139, v30, v178
	v_fmac_f32_e32 v142, v109, v179
	v_fmac_f32_e32 v139, v31, v179
	v_fmac_f32_e32 v142, v110, v180
	v_fmac_f32_e32 v139, v28, v180
	v_fmac_f32_e32 v142, v111, v181
	v_fmac_f32_e32 v139, v29, v181
	s_waitcnt vmcnt(12)
	v_fmac_f32_e32 v142, v112, v182
	v_fmac_f32_e32 v139, v34, v182
	v_fmac_f32_e32 v142, v113, v183
	v_fmac_f32_e32 v139, v35, v183
	v_fmac_f32_e32 v142, v114, v184
	v_fmac_f32_e32 v139, v32, v184
	v_fmac_f32_e32 v142, v115, v185
	v_fmac_f32_e32 v139, v33, v185
	s_waitcnt vmcnt(11)
	v_fmac_f32_e32 v142, v116, v186
	v_fmac_f32_e32 v139, v38, v186
	v_fmac_f32_e32 v142, v117, v187
	v_fmac_f32_e32 v139, v39, v187
	v_fmac_f32_e32 v142, v118, v188
	v_fmac_f32_e32 v139, v36, v188
	v_fmac_f32_e32 v142, v119, v189
	v_fmac_f32_e32 v139, v37, v189
	s_waitcnt vmcnt(10)
	v_fmac_f32_e32 v142, v120, v214
	v_fmac_f32_e32 v139, v42, v214
	v_fmac_f32_e32 v142, v121, v215
	v_fmac_f32_e32 v139, v43, v215
	v_fmac_f32_e32 v142, v122, v216
	v_fmac_f32_e32 v139, v40, v216
	v_fmac_f32_e32 v142, v123, v217
	v_fmac_f32_e32 v139, v41, v217
	s_waitcnt vmcnt(9)
	v_fmac_f32_e32 v142, v124, v12
	v_fmac_f32_e32 v139, v94, v12
	v_fmac_f32_e32 v142, v125, v13
	v_fmac_f32_e32 v139, v95, v13
	v_fmac_f32_e32 v142, v126, v14
	v_fmac_f32_e32 v139, v92, v14
	v_fmac_f32_e32 v142, v127, v15
	v_fmac_f32_e32 v139, v93, v15
	s_waitcnt vmcnt(8)
; __device__ __forceinline__ gv4p launder_g(const float* q) { asm volatile("" : "+v"(q)); return (gv4p)q; }
; __device__ void phase_ln2_route(const Params& p) {
;     ...
; #pragma unroll
;       for (int g = 0; g < 8; g++) {
;         if (g + 1 < 8) {
;           gv4p wp = launder_g(wgT + (g + 1) * DM + lane * 4);
; #pragma unroll
;           for (int i = 0; i < 8; i++) wb[(g + 1) & 1][i] = wp[CH(i) >> 2];
;         }
;         __builtin_amdgcn_sched_barrier(0);
;         float s0 = 0.f, s1 = 0.f;
; #pragma unroll
;         for (int i = 0; i < 8; i++)
; #pragma unroll
;           for (int e = 0; e < 4; e++) { s0 += wb[g & 1][i][e] * v[0][i * 4 + e]; s1 += wb[g & 1][i][e] * v[1][i * 4 + e]; }
;         lg[0][g] = s0; lg[1][g] = s1;
;         __builtin_amdgcn_sched_barrier(0);
;       }
	v_fmac_f32_e32 v142, v136, v4
	v_fmac_f32_e32 v139, v98, v4
	v_fmac_f32_e32 v142, v137, v5
	v_fmac_f32_e32 v139, v99, v5
	v_fmac_f32_e32 v142, v134, v6
	v_fmac_f32_e32 v139, v96, v6
	v_fmac_f32_e32 v142, v135, v7
	v_fmac_f32_e32 v139, v97, v7
	v_mov_b64_e32 v[4:5], v[54:55]
	global_load_dwordx4 v[178:181], v[4:5], off
	global_load_dwordx4 v[182:185], v[4:5], off offset:1024
	global_load_dwordx4 v[186:189], v[4:5], off offset:2048
	global_load_dwordx4 v[214:217], v[4:5], off offset:3072
	v_add_co_u32_e32 v4, vcc, s65, v4
	s_nop 1
	v_addc_co_u32_e32 v5, vcc, 0, v5, vcc
	global_load_dwordx4 v[218:221], v[4:5], off
	global_load_dwordx4 v[222:225], v[4:5], off offset:1024
	global_load_dwordx4 v[12:15], v[4:5], off offset:2048
	s_nop 0
	global_load_dwordx4 v[4:7], v[4:5], off offset:3072
	s_waitcnt vmcnt(15)
	v_fma_f32 v143, v102, v190, 0
	v_fma_f32 v141, v22, v190, 0
	v_fmac_f32_e32 v143, v103, v191
	v_fmac_f32_e32 v141, v23, v191
	v_fmac_f32_e32 v143, v100, v192
	v_fmac_f32_e32 v141, v20, v192
	v_fmac_f32_e32 v143, v101, v193
	v_fmac_f32_e32 v141, v21, v193
	s_waitcnt vmcnt(14)
	v_fmac_f32_e32 v143, v104, v194
	v_fmac_f32_e32 v141, v26, v194
	v_fmac_f32_e32 v143, v105, v195
	v_fmac_f32_e32 v141, v27, v195
	v_fmac_f32_e32 v143, v106, v196
	v_fmac_f32_e32 v141, v24, v196
	v_fmac_f32_e32 v143, v107, v197
	v_fmac_f32_e32 v141, v25, v197
	s_waitcnt vmcnt(13)
	v_fmac_f32_e32 v143, v108, v198
	v_fmac_f32_e32 v141, v30, v198
	v_fmac_f32_e32 v143, v109, v199
	v_fmac_f32_e32 v141, v31, v199
	v_fmac_f32_e32 v143, v110, v200
	v_fmac_f32_e32 v141, v28, v200
	v_fmac_f32_e32 v143, v111, v201
	v_fmac_f32_e32 v141, v29, v201
	s_waitcnt vmcnt(12)
	v_fmac_f32_e32 v143, v112, v202
	v_fmac_f32_e32 v141, v34, v202
	v_fmac_f32_e32 v143, v113, v203
	v_fmac_f32_e32 v141, v35, v203
	v_fmac_f32_e32 v143, v114, v204
	v_fmac_f32_e32 v141, v32, v204
	v_fmac_f32_e32 v143, v115, v205
	v_fmac_f32_e32 v141, v33, v205
	s_waitcnt vmcnt(11)
	v_fmac_f32_e32 v143, v116, v206
	v_fmac_f32_e32 v141, v38, v206
	v_fmac_f32_e32 v143, v117, v207
	v_fmac_f32_e32 v141, v39, v207
	v_fmac_f32_e32 v143, v118, v208
	v_fmac_f32_e32 v141, v36, v208
	v_fmac_f32_e32 v143, v119, v209
	v_fmac_f32_e32 v141, v37, v209
	s_waitcnt vmcnt(10)
	v_fmac_f32_e32 v143, v120, v210
	v_fmac_f32_e32 v141, v42, v210
	v_fmac_f32_e32 v143, v121, v211
	v_fmac_f32_e32 v141, v43, v211
	v_fmac_f32_e32 v143, v122, v212
	v_fmac_f32_e32 v141, v40, v212
	v_fmac_f32_e32 v143, v123, v213
	v_fmac_f32_e32 v141, v41, v213
	s_waitcnt vmcnt(9)
	v_fmac_f32_e32 v143, v124, v8
	v_fmac_f32_e32 v141, v94, v8
	v_fmac_f32_e32 v143, v125, v9
	v_fmac_f32_e32 v141, v95, v9
	v_fmac_f32_e32 v143, v126, v10
	v_fmac_f32_e32 v141, v92, v10
	v_fmac_f32_e32 v143, v127, v11
	v_fmac_f32_e32 v141, v93, v11
	s_waitcnt vmcnt(8)
	v_fmac_f32_e32 v143, v136, v0
	v_fmac_f32_e32 v141, v98, v0
	v_fmac_f32_e32 v143, v137, v1
	v_fmac_f32_e32 v141, v99, v1
	v_fmac_f32_e32 v143, v134, v2
	v_fmac_f32_e32 v141, v96, v2
	v_fmac_f32_e32 v143, v135, v3
	v_fmac_f32_e32 v141, v97, v3
	v_mov_b64_e32 v[0:1], v[56:57]
	global_load_dwordx4 v[190:193], v[0:1], off
	global_load_dwordx4 v[194:197], v[0:1], off offset:1024
	global_load_dwordx4 v[198:201], v[0:1], off offset:2048
	global_load_dwordx4 v[202:205], v[0:1], off offset:3072
	v_add_co_u32_e32 v0, vcc, s65, v0
	s_nop 1
	v_addc_co_u32_e32 v1, vcc, 0, v1, vcc
	global_load_dwordx4 v[206:209], v[0:1], off
	global_load_dwordx4 v[210:213], v[0:1], off offset:1024
	global_load_dwordx4 v[16:19], v[0:1], off offset:2048
	global_load_dwordx4 v[8:11], v[0:1], off offset:3072
	s_waitcnt vmcnt(15)
	v_fma_f32 v160, v102, v178, 0
	v_fma_f32 v144, v22, v178, 0
	v_fmac_f32_e32 v160, v103, v179
	v_fmac_f32_e32 v144, v23, v179
	v_fmac_f32_e32 v160, v100, v180
	v_fmac_f32_e32 v144, v20, v180
	v_fmac_f32_e32 v160, v101, v181
	v_fmac_f32_e32 v144, v21, v181
	s_waitcnt vmcnt(14)
	v_fmac_f32_e32 v160, v104, v182
	v_fmac_f32_e32 v144, v26, v182
	v_fmac_f32_e32 v160, v105, v183
	v_fmac_f32_e32 v144, v27, v183
	v_fmac_f32_e32 v160, v106, v184
	v_fmac_f32_e32 v144, v24, v184
	v_fmac_f32_e32 v160, v107, v185
	v_fmac_f32_e32 v144, v25, v185
	s_waitcnt vmcnt(13)
	v_fmac_f32_e32 v160, v108, v186
	v_fmac_f32_e32 v144, v30, v186
	v_fmac_f32_e32 v160, v109, v187
	v_fmac_f32_e32 v144, v31, v187
	v_fmac_f32_e32 v160, v110, v188
	v_fmac_f32_e32 v144, v28, v188
	v_fmac_f32_e32 v160, v111, v189
	v_fmac_f32_e32 v144, v29, v189
	s_waitcnt vmcnt(12)
	v_fmac_f32_e32 v160, v112, v214
	v_fmac_f32_e32 v144, v34, v214
	v_fmac_f32_e32 v160, v113, v215
	v_fmac_f32_e32 v144, v35, v215
	v_fmac_f32_e32 v160, v114, v216
	v_fmac_f32_e32 v144, v32, v216
	v_fmac_f32_e32 v160, v115, v217
	v_fmac_f32_e32 v144, v33, v217
	s_waitcnt vmcnt(11)
	v_fmac_f32_e32 v160, v116, v218
	v_fmac_f32_e32 v144, v38, v218
	v_fmac_f32_e32 v160, v117, v219
	v_fmac_f32_e32 v144, v39, v219
	v_fmac_f32_e32 v160, v118, v220
	v_fmac_f32_e32 v144, v36, v220
	v_fmac_f32_e32 v160, v119, v221
	v_fmac_f32_e32 v144, v37, v221
	s_waitcnt vmcnt(10)
	v_fmac_f32_e32 v160, v120, v222
	v_fmac_f32_e32 v144, v42, v222
	v_fmac_f32_e32 v160, v121, v223
	v_fmac_f32_e32 v144, v43, v223
	v_fmac_f32_e32 v160, v122, v224
	v_fmac_f32_e32 v144, v40, v224
	v_fmac_f32_e32 v160, v123, v225
	v_fmac_f32_e32 v144, v41, v225
	s_waitcnt vmcnt(9)
	v_fmac_f32_e32 v160, v124, v12
	v_fmac_f32_e32 v144, v94, v12
	v_fmac_f32_e32 v160, v125, v13
	v_fmac_f32_e32 v144, v95, v13
	v_fmac_f32_e32 v160, v126, v14
	v_fmac_f32_e32 v144, v92, v14
	v_fmac_f32_e32 v160, v127, v15
	v_fmac_f32_e32 v144, v93, v15
	s_waitcnt vmcnt(8)
; __device__ __forceinline__ gv4p launder_g(const float* q) { asm volatile("" : "+v"(q)); return (gv4p)q; }
; __device__ void phase_ln2_route(const Params& p) {
;     ...
; #pragma unroll
;       for (int g = 0; g < 8; g++) {
;         if (g + 1 < 8) {
;           gv4p wp = launder_g(wgT + (g + 1) * DM + lane * 4);
; #pragma unroll
;           for (int i = 0; i < 8; i++) wb[(g + 1) & 1][i] = wp[CH(i) >> 2];
;         }
;         __builtin_amdgcn_sched_barrier(0);
;         float s0 = 0.f, s1 = 0.f;
; #pragma unroll
;         for (int i = 0; i < 8; i++)
; #pragma unroll
;           for (int e = 0; e < 4; e++) { s0 += wb[g & 1][i][e] * v[0][i * 4 + e]; s1 += wb[g & 1][i][e] * v[1][i * 4 + e]; }
;         lg[0][g] = s0; lg[1][g] = s1;
;         __builtin_amdgcn_sched_barrier(0);
;       }
	v_fmac_f32_e32 v160, v136, v4
	v_fmac_f32_e32 v144, v98, v4
	v_fmac_f32_e32 v160, v137, v5
	v_fmac_f32_e32 v144, v99, v5
	v_fmac_f32_e32 v160, v134, v6
	v_fmac_f32_e32 v144, v96, v6
	v_fmac_f32_e32 v160, v135, v7
	v_fmac_f32_e32 v144, v97, v7
	v_mov_b64_e32 v[0:1], v[58:59]
	global_load_dwordx4 v[178:181], v[0:1], off
	global_load_dwordx4 v[182:185], v[0:1], off offset:1024
	global_load_dwordx4 v[186:189], v[0:1], off offset:2048
	global_load_dwordx4 v[214:217], v[0:1], off offset:3072
	v_add_co_u32_e32 v0, vcc, s65, v0
	s_nop 1
	v_addc_co_u32_e32 v1, vcc, 0, v1, vcc
	global_load_dwordx4 v[218:221], v[0:1], off
	global_load_dwordx4 v[12:15], v[0:1], off offset:1024
	global_load_dwordx4 v[4:7], v[0:1], off offset:2048
	s_nop 0
	global_load_dwordx4 v[0:3], v[0:1], off offset:3072
	s_waitcnt vmcnt(15)
	v_fma_f32 v162, v102, v190, 0
	v_fma_f32 v161, v22, v190, 0
	v_fmac_f32_e32 v162, v103, v191
	v_fmac_f32_e32 v161, v23, v191
	v_fmac_f32_e32 v162, v100, v192
	v_fmac_f32_e32 v161, v20, v192
	v_fmac_f32_e32 v162, v101, v193
	v_fmac_f32_e32 v161, v21, v193
	s_waitcnt vmcnt(14)
	v_fmac_f32_e32 v162, v104, v194
	v_fmac_f32_e32 v161, v26, v194
	v_fmac_f32_e32 v162, v105, v195
	v_fmac_f32_e32 v161, v27, v195
	v_fmac_f32_e32 v162, v106, v196
	v_fmac_f32_e32 v161, v24, v196
	v_fmac_f32_e32 v162, v107, v197
	v_fmac_f32_e32 v161, v25, v197
	s_waitcnt vmcnt(13)
	v_fmac_f32_e32 v162, v108, v198
	v_fmac_f32_e32 v161, v30, v198
	v_fmac_f32_e32 v162, v109, v199
	v_fmac_f32_e32 v161, v31, v199
	v_fmac_f32_e32 v162, v110, v200
	v_fmac_f32_e32 v161, v28, v200
	v_fmac_f32_e32 v162, v111, v201
	v_fmac_f32_e32 v161, v29, v201
	s_waitcnt vmcnt(12)
	v_fmac_f32_e32 v162, v112, v202
	v_fmac_f32_e32 v161, v34, v202
	v_fmac_f32_e32 v162, v113, v203
	v_fmac_f32_e32 v161, v35, v203
	v_fmac_f32_e32 v162, v114, v204
	v_fmac_f32_e32 v161, v32, v204
	v_fmac_f32_e32 v162, v115, v205
	v_fmac_f32_e32 v161, v33, v205
	s_waitcnt vmcnt(11)
	v_fmac_f32_e32 v162, v116, v206
	v_fmac_f32_e32 v161, v38, v206
	v_fmac_f32_e32 v162, v117, v207
	v_fmac_f32_e32 v161, v39, v207
	v_fmac_f32_e32 v162, v118, v208
	v_fmac_f32_e32 v161, v36, v208
	v_fmac_f32_e32 v162, v119, v209
	v_fmac_f32_e32 v161, v37, v209
	s_waitcnt vmcnt(10)
	v_fmac_f32_e32 v162, v120, v210
	v_fmac_f32_e32 v161, v42, v210
	v_fmac_f32_e32 v162, v121, v211
	v_fmac_f32_e32 v161, v43, v211
	v_fmac_f32_e32 v162, v122, v212
	v_fmac_f32_e32 v161, v40, v212
	v_fmac_f32_e32 v162, v123, v213
	v_fmac_f32_e32 v161, v41, v213
	s_waitcnt vmcnt(9)
	v_fmac_f32_e32 v162, v124, v16
	v_fmac_f32_e32 v161, v94, v16
	v_fmac_f32_e32 v162, v125, v17
	v_fmac_f32_e32 v161, v95, v17
	v_fmac_f32_e32 v162, v126, v18
	v_fmac_f32_e32 v161, v92, v18
	v_fmac_f32_e32 v162, v127, v19
	v_fmac_f32_e32 v161, v93, v19
	s_waitcnt vmcnt(8)
	v_fmac_f32_e32 v162, v136, v8
	v_fmac_f32_e32 v161, v98, v8
	v_fmac_f32_e32 v162, v137, v9
	v_fmac_f32_e32 v161, v99, v9
	v_fmac_f32_e32 v162, v134, v10
	v_fmac_f32_e32 v161, v96, v10
	v_fmac_f32_e32 v162, v135, v11
	v_fmac_f32_e32 v161, v97, v11
	v_mov_b64_e32 v[8:9], v[60:61]
	global_load_dwordx4 v[190:193], v[8:9], off
	global_load_dwordx4 v[194:197], v[8:9], off offset:1024
	global_load_dwordx4 v[198:201], v[8:9], off offset:2048
	global_load_dwordx4 v[202:205], v[8:9], off offset:3072
	v_add_co_u32_e32 v8, vcc, s65, v8
	s_nop 1
	v_addc_co_u32_e32 v9, vcc, 0, v9, vcc
	global_load_dwordx4 v[206:209], v[8:9], off
	global_load_dwordx4 v[210:213], v[8:9], off offset:1024
	global_load_dwordx4 v[222:225], v[8:9], off offset:2048
	s_nop 0
	global_load_dwordx4 v[8:11], v[8:9], off offset:3072
	s_waitcnt vmcnt(15)
	v_fma_f32 v16, v22, v178, 0
	v_fma_f32 v17, v102, v178, 0
	v_fmac_f32_e32 v16, v23, v179
	v_fmac_f32_e32 v17, v103, v179
	v_fmac_f32_e32 v16, v20, v180
	v_fmac_f32_e32 v17, v100, v180
	v_fmac_f32_e32 v16, v21, v181
	v_fmac_f32_e32 v17, v101, v181
	s_waitcnt vmcnt(14)
	v_fmac_f32_e32 v16, v26, v182
	v_fmac_f32_e32 v17, v104, v182
	v_fmac_f32_e32 v16, v27, v183
	v_fmac_f32_e32 v17, v105, v183
	v_fmac_f32_e32 v16, v24, v184
	v_fmac_f32_e32 v17, v106, v184
	v_fmac_f32_e32 v16, v25, v185
	v_fmac_f32_e32 v17, v107, v185
	s_waitcnt vmcnt(13)
	v_fmac_f32_e32 v16, v30, v186
	v_fmac_f32_e32 v17, v108, v186
	v_fmac_f32_e32 v16, v31, v187
	v_fmac_f32_e32 v17, v109, v187
	v_fmac_f32_e32 v16, v28, v188
	v_fmac_f32_e32 v17, v110, v188
	v_fmac_f32_e32 v16, v29, v189
	v_fmac_f32_e32 v17, v111, v189
	s_waitcnt vmcnt(12)
	v_fmac_f32_e32 v16, v34, v214
	v_fmac_f32_e32 v17, v112, v214
	v_fmac_f32_e32 v16, v35, v215
	v_fmac_f32_e32 v17, v113, v215
	v_fmac_f32_e32 v16, v32, v216
	v_fmac_f32_e32 v17, v114, v216
	v_fmac_f32_e32 v16, v33, v217
	v_fmac_f32_e32 v17, v115, v217
	s_waitcnt vmcnt(11)
	v_fmac_f32_e32 v16, v38, v218
	v_fmac_f32_e32 v17, v116, v218
	v_fmac_f32_e32 v16, v39, v219
	v_fmac_f32_e32 v17, v117, v219
	v_fmac_f32_e32 v16, v36, v220
	v_fmac_f32_e32 v17, v118, v220
	v_fmac_f32_e32 v16, v37, v221
	v_fmac_f32_e32 v17, v119, v221
	s_waitcnt vmcnt(10)
	v_fmac_f32_e32 v16, v42, v12
	v_fmac_f32_e32 v17, v120, v12
	v_fmac_f32_e32 v16, v43, v13
	v_fmac_f32_e32 v17, v121, v13
	v_fmac_f32_e32 v16, v40, v14
	v_fmac_f32_e32 v17, v122, v14
	v_fmac_f32_e32 v16, v41, v15
	v_fmac_f32_e32 v17, v123, v15
	s_waitcnt vmcnt(9)
	v_fmac_f32_e32 v16, v94, v4
	v_fmac_f32_e32 v17, v124, v4
	v_fmac_f32_e32 v16, v95, v5
	v_fmac_f32_e32 v17, v125, v5
	v_fmac_f32_e32 v16, v92, v6
	v_fmac_f32_e32 v17, v126, v6
	v_fmac_f32_e32 v16, v93, v7
	v_fmac_f32_e32 v17, v127, v7
	s_waitcnt vmcnt(8)
	v_fmac_f32_e32 v16, v98, v0
	v_fmac_f32_e32 v17, v136, v0
	v_fmac_f32_e32 v16, v99, v1
	v_fmac_f32_e32 v17, v137, v1
	v_fmac_f32_e32 v16, v96, v2
	v_fmac_f32_e32 v17, v134, v2
	v_fmac_f32_e32 v16, v97, v3
	v_fmac_f32_e32 v17, v135, v3
	s_waitcnt vmcnt(7)
; __device__ __forceinline__ gv4p launder_g(const float* q) { asm volatile("" : "+v"(q)); return (gv4p)q; }
; __device__ __forceinline__ void wave_reduce8(float (&a)[8], int lane) {
;   float b[4], c[2], d;
;   const bool h5 = lane & 32, h4 = lane & 16, h3 = lane & 8;
; #pragma unroll
;   for (int k = 0; k < 4; k++) {
;     float send = h5 ? a[k] : a[k + 4];
;     float keep = h5 ? a[k + 4] : a[k];
;     b[k] = keep + __shfl_xor(send, 32);
;   }
; #pragma unroll
;   for (int k = 0; k < 2; k++) {
;     float send = h4 ? b[k] : b[k + 2];
;     float keep = h4 ? b[k + 2] : b[k];
;     c[k] = keep + __shfl_xor(send, 16);
;   }
;   {
;     float send = h3 ? c[0] : c[1];
;     float keep = h3 ? c[1] : c[0];
;     d = keep + __shfl_xor(send, 8);
;   }
;   d += __shfl_xor(d, 4);
;   d += __shfl_xor(d, 2);
;   d += __shfl_xor(d, 1);
; #pragma unroll
;   for (int g = 0; g < 8; g++) a[g] = __shfl(d, ((g >> 2) & 1) * 32 + ((g >> 1) & 1) * 16 + (g & 1) * 8);
; }
; __device__ void phase_ln2_route(const Params& p) {
;     ...
; #pragma unroll
;       for (int g = 0; g < 8; g++) {
;         if (g + 1 < 8) {
;           gv4p wp = launder_g(wgT + (g + 1) * DM + lane * 4);
; #pragma unroll
;           for (int i = 0; i < 8; i++) wb[(g + 1) & 1][i] = wp[CH(i) >> 2];
;         }
;         __builtin_amdgcn_sched_barrier(0);
;         float s0 = 0.f, s1 = 0.f;
; #pragma unroll
;         for (int i = 0; i < 8; i++)
; #pragma unroll
;           for (int e = 0; e < 4; e++) { s0 += wb[g & 1][i][e] * v[0][i * 4 + e]; s1 += wb[g & 1][i][e] * v[1][i * 4 + e]; }
;         lg[0][g] = s0; lg[1][g] = s1;
;         __builtin_amdgcn_sched_barrier(0);
;       }
;     }
;     wave_reduce8(lg[0], lane);
;     wave_reduce8(lg[1], lane);
;     int gi[2]; float gval[2];
; #pragma unroll
;     for (int q = 0; q < 2; q++) {
; #pragma unroll
;       for (int g = 0; g < 8; g++) lg[q][g] += p.b_group[g];
;       int bi = 0; float gm = lg[q][0];
; #pragma unroll
;       for (int g = 1; g < 8; g++) if (lg[q][g] > gm) { gm = lg[q][g]; bi = g; }
;       float gs = 0.f;
; #pragma unroll
;       for (int g = 0; g < 8; g++) gs += __expf(lg[q][g] - gm);
;       gval[q] = 1.f / gs;
;       gi[q] = __builtin_amdgcn_readfirstlane(bi);
	v_fma_f32 v0, v102, v190, 0
	v_fma_f32 v6, v22, v190, 0
	v_fmac_f32_e32 v0, v103, v191
	v_fmac_f32_e32 v6, v23, v191
	v_fmac_f32_e32 v0, v100, v192
	v_fmac_f32_e32 v6, v20, v192
	v_fmac_f32_e32 v0, v101, v193
	v_fmac_f32_e32 v6, v21, v193
	s_waitcnt vmcnt(6)
	v_fmac_f32_e32 v0, v104, v194
	v_fmac_f32_e32 v6, v26, v194
	v_fmac_f32_e32 v0, v105, v195
	v_fmac_f32_e32 v6, v27, v195
	v_fmac_f32_e32 v0, v106, v196
	v_fmac_f32_e32 v6, v24, v196
	v_fmac_f32_e32 v0, v107, v197
	v_fmac_f32_e32 v6, v25, v197
	s_waitcnt vmcnt(5)
	v_fmac_f32_e32 v0, v108, v198
	v_fmac_f32_e32 v6, v30, v198
	v_fmac_f32_e32 v0, v109, v199
	v_fmac_f32_e32 v6, v31, v199
	v_fmac_f32_e32 v0, v110, v200
	v_fmac_f32_e32 v6, v28, v200
	v_fmac_f32_e32 v0, v111, v201
	v_fmac_f32_e32 v6, v29, v201
	s_waitcnt vmcnt(4)
	v_fmac_f32_e32 v0, v112, v202
	v_fmac_f32_e32 v6, v34, v202
	v_fmac_f32_e32 v0, v113, v203
	v_fmac_f32_e32 v6, v35, v203
	v_fmac_f32_e32 v0, v114, v204
	v_fmac_f32_e32 v6, v32, v204
	v_fmac_f32_e32 v0, v115, v205
	v_fmac_f32_e32 v6, v33, v205
	s_waitcnt vmcnt(3)
	v_fmac_f32_e32 v0, v116, v206
	v_fmac_f32_e32 v6, v38, v206
	v_fmac_f32_e32 v0, v117, v207
	v_fmac_f32_e32 v6, v39, v207
	v_fmac_f32_e32 v0, v118, v208
	v_fmac_f32_e32 v6, v36, v208
	v_fmac_f32_e32 v0, v119, v209
	v_fmac_f32_e32 v6, v37, v209
	s_waitcnt vmcnt(2)
	v_fmac_f32_e32 v0, v120, v210
	v_fmac_f32_e32 v6, v42, v210
	v_fmac_f32_e32 v0, v121, v211
	v_fmac_f32_e32 v6, v43, v211
	v_fmac_f32_e32 v0, v122, v212
	v_fmac_f32_e32 v6, v40, v212
	v_fmac_f32_e32 v0, v123, v213
	v_fmac_f32_e32 v6, v41, v213
	s_waitcnt vmcnt(1)
	v_fmac_f32_e32 v0, v124, v222
	v_fmac_f32_e32 v6, v94, v222
	v_fmac_f32_e32 v0, v125, v223
	v_fmac_f32_e32 v6, v95, v223
	v_fmac_f32_e32 v0, v126, v224
	v_fmac_f32_e32 v6, v92, v224
	v_fmac_f32_e32 v0, v127, v225
	v_fmac_f32_e32 v6, v93, v225
	s_waitcnt vmcnt(0)
	v_fmac_f32_e32 v0, v136, v8
	v_fmac_f32_e32 v6, v98, v8
	v_fmac_f32_e32 v0, v137, v9
	v_fmac_f32_e32 v6, v99, v9
	v_fmac_f32_e32 v0, v134, v10
	v_fmac_f32_e32 v6, v96, v10
	v_fmac_f32_e32 v0, v135, v11
	v_fmac_f32_e32 v6, v97, v11
	v_readlane_b32 s72, v255, 8
	v_readlane_b32 s74, v255, 10
	v_readlane_b32 s75, v255, 11
	s_nop 4
	global_load_dwordx4 v[178:181], v45, s[74:75]
	global_load_dwordx4 v[182:185], v45, s[74:75] offset:16
	v_cndmask_b32_e64 v1, v91, v160, s[6:7]
	v_cndmask_b32_e64 v3, v140, v162, s[6:7]
	v_cndmask_b32_e64 v5, v142, v17, s[6:7]
	v_cndmask_b32_e64 v8, v143, v0, s[6:7]
	ds_bpermute_b32 v1, v89, v1
	ds_bpermute_b32 v3, v89, v3
	ds_bpermute_b32 v5, v89, v5
	ds_bpermute_b32 v8, v89, v8
	v_cndmask_b32_e64 v2, v160, v91, s[6:7]
	v_cndmask_b32_e64 v4, v162, v140, s[6:7]
	v_cndmask_b32_e64 v7, v17, v142, s[6:7]
	v_cndmask_b32_e64 v0, v0, v143, s[6:7]
	s_waitcnt lgkmcnt(3)
	v_add_f32_e32 v1, v2, v1
	s_waitcnt lgkmcnt(2)
	v_add_f32_e32 v2, v4, v3
	s_waitcnt lgkmcnt(1)
	v_add_f32_e32 v3, v7, v5
	s_waitcnt lgkmcnt(0)
	v_add_f32_e32 v0, v0, v8
	v_cndmask_b32_e64 v4, v1, v3, s[8:9]
	v_cndmask_b32_e64 v5, v2, v0, s[8:9]
	ds_bpermute_b32 v4, v145, v4
	ds_bpermute_b32 v5, v145, v5
	v_cndmask_b32_e64 v1, v3, v1, s[8:9]
	v_cndmask_b32_e64 v0, v0, v2, s[8:9]
	v_cndmask_b32_e64 v3, v144, v87, s[6:7]
	s_waitcnt lgkmcnt(1)
	v_add_f32_e32 v1, v1, v4
	s_waitcnt lgkmcnt(0)
	v_add_f32_e32 v0, v0, v5
	v_cndmask_b32_e64 v2, v1, v0, s[10:11]
	ds_bpermute_b32 v2, v146, v2
	v_cndmask_b32_e64 v0, v0, v1, s[10:11]
	v_cndmask_b32_e64 v4, v138, v161, s[6:7]
	v_cndmask_b32_e64 v5, v139, v16, s[6:7]
	v_cndmask_b32_e64 v8, v141, v6, s[6:7]
	s_waitcnt lgkmcnt(0)
	v_add_f32_e32 v0, v0, v2
	ds_bpermute_b32 v1, v147, v0
	v_cndmask_b32_e64 v2, v87, v144, s[6:7]
	ds_bpermute_b32 v2, v89, v2
	ds_bpermute_b32 v15, v89, v4
	ds_bpermute_b32 v17, v89, v5
	s_waitcnt lgkmcnt(3)
	v_add_f32_e32 v0, v0, v1
	ds_bpermute_b32 v1, v148, v0
	s_waitcnt lgkmcnt(3)
	v_add_f32_e32 v19, v3, v2
	ds_bpermute_b32 v18, v89, v8
	v_cndmask_b32_e64 v7, v161, v138, s[6:7]
	v_cndmask_b32_e64 v6, v6, v141, s[6:7]
	s_waitcnt lgkmcnt(1)
	v_add_f32_e32 v0, v0, v1
	ds_bpermute_b32 v1, v149, v0
	s_waitcnt lgkmcnt(1)
	v_add_f32_e32 v6, v6, v18
	v_readlane_b32 s73, v255, 9
	v_readlane_b32 s76, v255, 12
	v_readlane_b32 s77, v255, 13
	s_waitcnt lgkmcnt(0)
	v_add_f32_e32 v2, v0, v1
	ds_bpermute_b32 v0, v150, v2
	ds_bpermute_b32 v1, v151, v2
	ds_bpermute_b32 v3, v152, v2
	ds_bpermute_b32 v4, v153, v2
	ds_bpermute_b32 v5, v154, v2
	ds_bpermute_b32 v8, v155, v2
	ds_bpermute_b32 v9, v156, v2
	ds_bpermute_b32 v2, v157, v2
	v_readlane_b32 s78, v255, 14
	v_readlane_b32 s79, v255, 15
	v_readlane_b32 s80, v255, 16
	v_readlane_b32 s81, v255, 17
	v_readlane_b32 s82, v255, 18
	v_readlane_b32 s83, v255, 19
	v_readlane_b32 s84, v255, 20
	v_readlane_b32 s85, v255, 21
	v_readlane_b32 s86, v255, 22
	v_readlane_b32 s87, v255, 23
	s_waitcnt vmcnt(1) lgkmcnt(6)
	v_pk_add_f32 v[0:1], v[178:179], v[0:1]
	s_nop 0
	v_cmp_gt_f32_e32 vcc, v1, v0
	s_waitcnt lgkmcnt(5)
	v_add_f32_e32 v13, v180, v3
	s_waitcnt vmcnt(0) lgkmcnt(2)
	v_add_f32_e32 v10, v183, v8
	s_waitcnt lgkmcnt(0)
; __device__ __forceinline__ gv4p launder_g(const float* q) { asm volatile("" : "+v"(q)); return (gv4p)q; }
; __device__ __forceinline__ void wave_reduce8(float (&a)[8], int lane) {
;   float b[4], c[2], d;
;   const bool h5 = lane & 32, h4 = lane & 16, h3 = lane & 8;
; #pragma unroll
;   for (int k = 0; k < 4; k++) {
;     float send = h5 ? a[k] : a[k + 4];
;     float keep = h5 ? a[k + 4] : a[k];
;     b[k] = keep + __shfl_xor(send, 32);
;   }
; #pragma unroll
;   for (int k = 0; k < 2; k++) {
;     float send = h4 ? b[k] : b[k + 2];
;     float keep = h4 ? b[k + 2] : b[k];
;     c[k] = keep + __shfl_xor(send, 16);
;   }
;   {
;     float send = h3 ? c[0] : c[1];
;     float keep = h3 ? c[1] : c[0];
;     d = keep + __shfl_xor(send, 8);
;   }
;   d += __shfl_xor(d, 4);
;   d += __shfl_xor(d, 2);
;   d += __shfl_xor(d, 1);
; #pragma unroll
;   for (int g = 0; g < 8; g++) a[g] = __shfl(d, ((g >> 2) & 1) * 32 + ((g >> 1) & 1) * 16 + (g & 1) * 8);
; }
; __device__ void phase_ln2_route(const Params& p) {
;     ...
;     int gi[2]; float gval[2];
; #pragma unroll
;     for (int q = 0; q < 2; q++) {
; #pragma unroll
;       for (int g = 0; g < 8; g++) lg[q][g] += p.b_group[g];
;       int bi = 0; float gm = lg[q][0];
; #pragma unroll
;       for (int g = 1; g < 8; g++) if (lg[q][g] > gm) { gm = lg[q][g]; bi = g; }
;       float gs = 0.f;
; #pragma unroll
;       for (int g = 0; g < 8; g++) gs += __expf(lg[q][g] - gm);
;       gval[q] = 1.f / gs;
;       gi[q] = __builtin_amdgcn_readfirstlane(bi);
;     }
;     float le[2][8];
;     {
;       const float* wr0_ = wrT + (long)gi[0] * 8 * DM;
;       const float* wr1_ = wrT + (long)gi[1] * 8 * DM;
;       f32x4 wb[2][8];
;       {
;         gv4p wp = launder_g(wr0_ + lane * 4);
; #pragma unroll
;         for (int i = 0; i < 8; i++) wb[0][i] = wp[CH(i) >> 2];
;       }
; #pragma unroll
;       for (int u = 0; u < 16; u++) {
;         if (u + 1 < 16) {
;           gv4p wp = launder_g((((u + 1) >> 3) ? wr1_ : wr0_) + ((u + 1) & 7) * DM + lane * 4);
; #pragma unroll
;           for (int i = 0; i < 8; i++) wb[(u + 1) & 1][i] = wp[CH(i) >> 2];
;         }
;         __builtin_amdgcn_sched_barrier(0);
;         float s0 = 0.f;
	v_add_f32_e32 v8, v185, v2
	v_cndmask_b32_e32 v2, v0, v1, vcc
	v_cmp_gt_f32_e64 s[0:1], v13, v2
	v_add_f32_e32 v12, v181, v4
	v_cndmask_b32_e64 v3, 0, 1, vcc
	v_cndmask_b32_e64 v2, v2, v13, s[0:1]
	v_cmp_gt_f32_e32 vcc, v12, v2
	v_add_f32_e32 v11, v182, v5
	v_cndmask_b32_e64 v3, v3, 2, s[0:1]
	v_cndmask_b32_e32 v2, v2, v12, vcc
	v_cmp_gt_f32_e64 s[0:1], v11, v2
	v_cndmask_b32_e64 v3, v3, 3, vcc
	v_add_f32_e32 v9, v184, v9
	v_cndmask_b32_e64 v2, v2, v11, s[0:1]
	v_cmp_gt_f32_e32 vcc, v10, v2
	v_cndmask_b32_e64 v3, v3, 4, s[0:1]
	s_nop 0
	v_cndmask_b32_e32 v2, v2, v10, vcc
	v_cmp_gt_f32_e64 s[0:1], v9, v2
	s_nop 1
	v_cndmask_b32_e64 v14, v2, v9, s[0:1]
	v_cndmask_b32_e64 v2, v3, 5, vcc
	v_cndmask_b32_e64 v2, v2, 6, s[0:1]
	v_cmp_gt_f32_e64 s[14:15], v8, v14
	s_nop 1
	v_cndmask_b32_e64 v2, v2, 7, s[14:15]
	s_nop 0
	v_readfirstlane_b32 s24, v2
	s_ashr_i32 s25, s24, 31
	s_lshl_b64 s[0:1], s[24:25], 16
	s_add_u32 s0, s43, s0
	s_addc_u32 s1, s64, s1
	v_lshl_add_u64 v[4:5], s[0:1], 0, v[44:45]
	v_mov_b64_e32 v[2:3], v[4:5]
	global_load_dwordx4 v[160:163], v[2:3], off
	global_load_dwordx4 v[186:189], v[2:3], off offset:1024
	global_load_dwordx4 v[190:193], v[2:3], off offset:2048
	global_load_dwordx4 v[194:197], v[2:3], off offset:3072
	v_add_co_u32_e32 v2, vcc, s65, v2
	s_nop 1
	v_addc_co_u32_e32 v3, vcc, 0, v3, vcc
	global_load_dwordx4 v[198:201], v[2:3], off
	global_load_dwordx4 v[202:205], v[2:3], off offset:1024
	global_load_dwordx4 v[206:209], v[2:3], off offset:2048
	global_load_dwordx4 v[210:213], v[2:3], off offset:3072
	v_lshl_add_u64 v[2:3], v[4:5], 0, s[44:45]
	global_load_dwordx4 v[214:217], v[2:3], off
	global_load_dwordx4 v[218:221], v[2:3], off offset:1024
	global_load_dwordx4 v[222:225], v[2:3], off offset:2048
	global_load_dwordx4 v[226:229], v[2:3], off offset:3072
	v_add_co_u32_e32 v2, vcc, s65, v2
	s_nop 1
	v_addc_co_u32_e32 v3, vcc, 0, v3, vcc
	global_load_dwordx4 v[230:233], v[2:3], off
	global_load_dwordx4 v[234:237], v[2:3], off offset:1024
	global_load_dwordx4 v[238:241], v[2:3], off offset:2048
	global_load_dwordx4 v[242:245], v[2:3], off offset:3072
	v_cndmask_b32_e64 v3, v16, v139, s[6:7]
	v_add_f32_e32 v2, v7, v15
	v_add_f32_e32 v3, v3, v17
	v_cndmask_b32_e64 v7, v19, v3, s[8:9]
	v_cndmask_b32_e64 v15, v2, v6, s[8:9]
	ds_bpermute_b32 v7, v145, v7
	ds_bpermute_b32 v15, v145, v15
	v_cndmask_b32_e64 v3, v3, v19, s[8:9]
	v_cndmask_b32_e64 v2, v6, v2, s[8:9]
	s_waitcnt lgkmcnt(1)
	v_add_f32_e32 v3, v3, v7
	s_waitcnt lgkmcnt(0)
	v_add_f32_e32 v2, v2, v15
	v_cndmask_b32_e64 v6, v3, v2, s[10:11]
	ds_bpermute_b32 v6, v146, v6
	v_cndmask_b32_e64 v2, v2, v3, s[10:11]
	s_waitcnt lgkmcnt(0)
	v_add_f32_e32 v2, v2, v6
	ds_bpermute_b32 v3, v147, v2
	s_waitcnt lgkmcnt(0)
	v_add_f32_e32 v2, v2, v3
	ds_bpermute_b32 v3, v148, v2
	s_waitcnt lgkmcnt(0)
	v_add_f32_e32 v2, v2, v3
	ds_bpermute_b32 v3, v149, v2
	s_waitcnt lgkmcnt(0)
	v_add_f32_e32 v6, v2, v3
	ds_bpermute_b32 v2, v150, v6
	ds_bpermute_b32 v3, v151, v6
	ds_bpermute_b32 v7, v152, v6
	ds_bpermute_b32 v16, v153, v6
	ds_bpermute_b32 v17, v154, v6
	ds_bpermute_b32 v18, v155, v6
	ds_bpermute_b32 v19, v156, v6
	ds_bpermute_b32 v6, v157, v6
	s_waitcnt lgkmcnt(6)
	v_pk_add_f32 v[2:3], v[178:179], v[2:3]
	s_waitcnt lgkmcnt(5)
	v_add_f32_e32 v15, v180, v7
	v_cmp_gt_f32_e32 vcc, v3, v2
	s_waitcnt lgkmcnt(4)
	v_add_f32_e32 v16, v181, v16
	s_waitcnt lgkmcnt(0)
	v_add_f32_e32 v87, v185, v6
	v_cndmask_b32_e32 v6, v2, v3, vcc
	v_cmp_gt_f32_e64 s[0:1], v15, v6
	v_add_f32_e32 v17, v182, v17
	v_add_f32_e32 v18, v183, v18
	v_cndmask_b32_e64 v6, v6, v15, s[0:1]
	v_cmp_gt_f32_e64 s[16:17], v16, v6
	v_add_f32_e32 v19, v184, v19
	s_nop 0
	v_cndmask_b32_e64 v6, v6, v16, s[16:17]
	v_cmp_gt_f32_e64 s[18:19], v17, v6
	s_nop 1
	v_cndmask_b32_e64 v6, v6, v17, s[18:19]
	v_cmp_gt_f32_e64 s[20:21], v18, v6
	s_nop 1
	v_cndmask_b32_e64 v6, v6, v18, s[20:21]
	v_cmp_gt_f32_e64 s[22:23], v19, v6
	s_nop 1
	v_cndmask_b32_e64 v91, v6, v19, s[22:23]
	v_cndmask_b32_e64 v6, 0, 1, vcc
	v_cndmask_b32_e64 v6, v6, 2, s[0:1]
	v_cndmask_b32_e64 v6, v6, 3, s[16:17]
	v_cndmask_b32_e64 v6, v6, 4, s[18:19]
	v_cndmask_b32_e64 v6, v6, 5, s[20:21]
	v_cndmask_b32_e64 v6, v6, 6, s[22:23]
	v_cmp_gt_f32_e32 vcc, v87, v91
	s_nop 1
	v_cndmask_b32_e64 v6, v6, 7, vcc
	s_nop 0
	v_readfirstlane_b32 s58, v6
	s_ashr_i32 s59, s58, 31
	s_lshl_b64 s[0:1], s[58:59], 16
	s_add_u32 s16, s43, s0
	s_addc_u32 s17, s64, s1
	s_waitcnt vmcnt(15)
	v_fma_f32 v6, v102, v160, 0
	v_fmac_f32_e32 v6, v103, v161
	v_fmac_f32_e32 v6, v100, v162
	v_fmac_f32_e32 v6, v101, v163
	s_waitcnt vmcnt(14)
	v_fmac_f32_e32 v6, v104, v186
	v_fmac_f32_e32 v6, v105, v187
	v_fmac_f32_e32 v6, v106, v188
	v_fmac_f32_e32 v6, v107, v189
	s_waitcnt vmcnt(13)
	v_fmac_f32_e32 v6, v108, v190
	v_fmac_f32_e32 v6, v109, v191
	v_fmac_f32_e32 v6, v110, v192
	v_fmac_f32_e32 v6, v111, v193
	s_waitcnt vmcnt(12)
	v_fmac_f32_e32 v6, v112, v194
	v_fmac_f32_e32 v6, v113, v195
	v_fmac_f32_e32 v6, v114, v196
	v_fmac_f32_e32 v6, v115, v197
	s_waitcnt vmcnt(11)
	v_fmac_f32_e32 v6, v116, v198
	v_fmac_f32_e32 v6, v117, v199
	v_fmac_f32_e32 v6, v118, v200
	v_fmac_f32_e32 v6, v119, v201
	s_waitcnt vmcnt(10)
	v_fmac_f32_e32 v6, v120, v202
	v_fmac_f32_e32 v6, v121, v203
	v_fmac_f32_e32 v6, v122, v204
	v_fmac_f32_e32 v6, v123, v205
	s_waitcnt vmcnt(9)
	v_fmac_f32_e32 v6, v124, v206
	v_fmac_f32_e32 v6, v125, v207
	v_fmac_f32_e32 v6, v126, v208
	v_fmac_f32_e32 v6, v127, v209
	s_waitcnt vmcnt(8)
; __device__ __forceinline__ gv4p launder_g(const float* q) { asm volatile("" : "+v"(q)); return (gv4p)q; }
; __device__ void phase_ln2_route(const Params& p) {
;     ...
; #pragma unroll
;       for (int u = 0; u < 16; u++) {
;         if (u + 1 < 16) {
;           gv4p wp = launder_g((((u + 1) >> 3) ? wr1_ : wr0_) + ((u + 1) & 7) * DM + lane * 4);
; #pragma unroll
;           for (int i = 0; i < 8; i++) wb[(u + 1) & 1][i] = wp[CH(i) >> 2];
;         }
;         __builtin_amdgcn_sched_barrier(0);
;         float s0 = 0.f;
; #pragma unroll
;         for (int i = 0; i < 8; i++)
; #pragma unroll
;           for (int e = 0; e < 4; e++) s0 += wb[u & 1][i][e] * v[u >> 3][i * 4 + e];
;         le[u >> 3][u & 7] = s0;
;         __builtin_amdgcn_sched_barrier(0);
;       }
	v_fmac_f32_e32 v6, v136, v210
	v_fmac_f32_e32 v6, v137, v211
	v_fmac_f32_e32 v6, v134, v212
	v_fmac_f32_e32 v6, v135, v213
	v_lshl_add_u64 v[142:143], v[4:5], 0, s[46:47]
	global_load_dwordx4 v[138:141], v[142:143], off
	global_load_dwordx4 v[160:163], v[142:143], off offset:1024
	global_load_dwordx4 v[178:181], v[142:143], off offset:2048
	global_load_dwordx4 v[182:185], v[142:143], off offset:3072
	v_add_co_u32_e64 v142, s[0:1], s65, v142
	s_nop 1
	v_addc_co_u32_e64 v143, s[0:1], 0, v143, s[0:1]
	global_load_dwordx4 v[186:189], v[142:143], off
	global_load_dwordx4 v[190:193], v[142:143], off offset:1024
	global_load_dwordx4 v[194:197], v[142:143], off offset:2048
	global_load_dwordx4 v[198:201], v[142:143], off offset:3072
	s_waitcnt vmcnt(15)
	v_fma_f32 v7, v102, v214, 0
	v_fmac_f32_e32 v7, v103, v215
	v_fmac_f32_e32 v7, v100, v216
	v_fmac_f32_e32 v7, v101, v217
	s_waitcnt vmcnt(14)
	v_fmac_f32_e32 v7, v104, v218
	v_fmac_f32_e32 v7, v105, v219
	v_fmac_f32_e32 v7, v106, v220
	v_fmac_f32_e32 v7, v107, v221
	s_waitcnt vmcnt(13)
	v_fmac_f32_e32 v7, v108, v222
	v_fmac_f32_e32 v7, v109, v223
	v_fmac_f32_e32 v7, v110, v224
	v_fmac_f32_e32 v7, v111, v225
	s_waitcnt vmcnt(12)
	v_fmac_f32_e32 v7, v112, v226
	v_fmac_f32_e32 v7, v113, v227
	v_fmac_f32_e32 v7, v114, v228
	v_fmac_f32_e32 v7, v115, v229
	s_waitcnt vmcnt(11)
	v_fmac_f32_e32 v7, v116, v230
	v_fmac_f32_e32 v7, v117, v231
	v_fmac_f32_e32 v7, v118, v232
	v_fmac_f32_e32 v7, v119, v233
	s_waitcnt vmcnt(10)
	v_fmac_f32_e32 v7, v120, v234
	v_fmac_f32_e32 v7, v121, v235
	v_fmac_f32_e32 v7, v122, v236
	v_fmac_f32_e32 v7, v123, v237
	s_waitcnt vmcnt(9)
	v_fmac_f32_e32 v7, v124, v238
	v_fmac_f32_e32 v7, v125, v239
	v_fmac_f32_e32 v7, v126, v240
	v_fmac_f32_e32 v7, v127, v241
	s_waitcnt vmcnt(8)
	v_fmac_f32_e32 v7, v136, v242
	v_fmac_f32_e32 v7, v137, v243
	v_fmac_f32_e32 v7, v134, v244
	v_fmac_f32_e32 v7, v135, v245
	v_lshl_add_u64 v[142:143], v[4:5], 0, s[48:49]
	global_load_dwordx4 v[202:205], v[142:143], off
	global_load_dwordx4 v[206:209], v[142:143], off offset:1024
	global_load_dwordx4 v[210:213], v[142:143], off offset:2048
	global_load_dwordx4 v[214:217], v[142:143], off offset:3072
	v_add_co_u32_e64 v142, s[0:1], s65, v142
	s_nop 1
	v_addc_co_u32_e64 v143, s[0:1], 0, v143, s[0:1]
	global_load_dwordx4 v[218:221], v[142:143], off
	global_load_dwordx4 v[222:225], v[142:143], off offset:1024
	global_load_dwordx4 v[226:229], v[142:143], off offset:2048
	global_load_dwordx4 v[230:233], v[142:143], off offset:3072
	s_waitcnt vmcnt(15)
	v_fma_f32 v138, v102, v138, 0
	v_fmac_f32_e32 v138, v103, v139
	v_fmac_f32_e32 v138, v100, v140
	v_fmac_f32_e32 v138, v101, v141
	s_waitcnt vmcnt(14)
	v_fmac_f32_e32 v138, v104, v160
	v_fmac_f32_e32 v138, v105, v161
	v_fmac_f32_e32 v138, v106, v162
	v_fmac_f32_e32 v138, v107, v163
	s_waitcnt vmcnt(13)
	v_fmac_f32_e32 v138, v108, v178
	v_fmac_f32_e32 v138, v109, v179
	v_fmac_f32_e32 v138, v110, v180
	v_fmac_f32_e32 v138, v111, v181
	s_waitcnt vmcnt(12)
	v_fmac_f32_e32 v138, v112, v182
	v_fmac_f32_e32 v138, v113, v183
	v_fmac_f32_e32 v138, v114, v184
	v_fmac_f32_e32 v138, v115, v185
	s_waitcnt vmcnt(11)
	v_fmac_f32_e32 v138, v116, v186
	v_fmac_f32_e32 v138, v117, v187
	v_fmac_f32_e32 v138, v118, v188
	v_fmac_f32_e32 v138, v119, v189
	s_waitcnt vmcnt(10)
	v_fmac_f32_e32 v138, v120, v190
	v_fmac_f32_e32 v138, v121, v191
	v_fmac_f32_e32 v138, v122, v192
	v_fmac_f32_e32 v138, v123, v193
	s_waitcnt vmcnt(9)
	v_fmac_f32_e32 v138, v124, v194
	v_fmac_f32_e32 v138, v125, v195
	v_fmac_f32_e32 v138, v126, v196
	v_fmac_f32_e32 v138, v127, v197
	s_waitcnt vmcnt(8)
	v_fmac_f32_e32 v138, v136, v198
	v_fmac_f32_e32 v138, v137, v199
	v_fmac_f32_e32 v138, v134, v200
	v_fmac_f32_e32 v138, v135, v201
	v_lshl_add_u64 v[170:171], v[4:5], 0, s[50:51]
	global_load_dwordx4 v[140:143], v[170:171], off
	global_load_dwordx4 v[160:163], v[170:171], off offset:1024
	global_load_dwordx4 v[178:181], v[170:171], off offset:2048
	global_load_dwordx4 v[182:185], v[170:171], off offset:3072
	v_add_co_u32_e64 v170, s[0:1], s65, v170
	s_nop 1
	v_addc_co_u32_e64 v171, s[0:1], 0, v171, s[0:1]
	global_load_dwordx4 v[186:189], v[170:171], off
	global_load_dwordx4 v[190:193], v[170:171], off offset:1024
	global_load_dwordx4 v[194:197], v[170:171], off offset:2048
	global_load_dwordx4 v[198:201], v[170:171], off offset:3072
	s_waitcnt vmcnt(15)
	v_fma_f32 v139, v102, v202, 0
	v_fmac_f32_e32 v139, v103, v203
	v_fmac_f32_e32 v139, v100, v204
	v_fmac_f32_e32 v139, v101, v205
	s_waitcnt vmcnt(14)
	v_fmac_f32_e32 v139, v104, v206
	v_fmac_f32_e32 v139, v105, v207
	v_fmac_f32_e32 v139, v106, v208
	v_fmac_f32_e32 v139, v107, v209
	s_waitcnt vmcnt(13)
	v_fmac_f32_e32 v139, v108, v210
	v_fmac_f32_e32 v139, v109, v211
	v_fmac_f32_e32 v139, v110, v212
	v_fmac_f32_e32 v139, v111, v213
	s_waitcnt vmcnt(12)
	v_fmac_f32_e32 v139, v112, v214
	v_fmac_f32_e32 v139, v113, v215
	v_fmac_f32_e32 v139, v114, v216
	v_fmac_f32_e32 v139, v115, v217
	s_waitcnt vmcnt(11)
	v_fmac_f32_e32 v139, v116, v218
	v_fmac_f32_e32 v139, v117, v219
	v_fmac_f32_e32 v139, v118, v220
	v_fmac_f32_e32 v139, v119, v221
	s_waitcnt vmcnt(10)
	v_fmac_f32_e32 v139, v120, v222
	v_fmac_f32_e32 v139, v121, v223
	v_fmac_f32_e32 v139, v122, v224
	v_fmac_f32_e32 v139, v123, v225
	s_waitcnt vmcnt(9)
	v_fmac_f32_e32 v139, v124, v226
	v_fmac_f32_e32 v139, v125, v227
	v_fmac_f32_e32 v139, v126, v228
	v_fmac_f32_e32 v139, v127, v229
	s_waitcnt vmcnt(8)
; __device__ __forceinline__ gv4p launder_g(const float* q) { asm volatile("" : "+v"(q)); return (gv4p)q; }
; __device__ void phase_ln2_route(const Params& p) {
;     ...
; #pragma unroll
;       for (int u = 0; u < 16; u++) {
;         if (u + 1 < 16) {
;           gv4p wp = launder_g((((u + 1) >> 3) ? wr1_ : wr0_) + ((u + 1) & 7) * DM + lane * 4);
; #pragma unroll
;           for (int i = 0; i < 8; i++) wb[(u + 1) & 1][i] = wp[CH(i) >> 2];
;         }
;         __builtin_amdgcn_sched_barrier(0);
;         float s0 = 0.f;
; #pragma unroll
;         for (int i = 0; i < 8; i++)
; #pragma unroll
;           for (int e = 0; e < 4; e++) s0 += wb[u & 1][i][e] * v[u >> 3][i * 4 + e];
;         le[u >> 3][u & 7] = s0;
;         __builtin_amdgcn_sched_barrier(0);
;       }
	v_fmac_f32_e32 v139, v136, v230
	v_fmac_f32_e32 v139, v137, v231
	v_fmac_f32_e32 v139, v134, v232
	v_fmac_f32_e32 v139, v135, v233
	v_lshl_add_u64 v[170:171], v[4:5], 0, s[52:53]
	global_load_dwordx4 v[202:205], v[170:171], off
	global_load_dwordx4 v[206:209], v[170:171], off offset:1024
	global_load_dwordx4 v[210:213], v[170:171], off offset:2048
	global_load_dwordx4 v[214:217], v[170:171], off offset:3072
	v_add_co_u32_e64 v170, s[0:1], s65, v170
	s_nop 1
	v_addc_co_u32_e64 v171, s[0:1], 0, v171, s[0:1]
	global_load_dwordx4 v[218:221], v[170:171], off
	global_load_dwordx4 v[222:225], v[170:171], off offset:1024
	global_load_dwordx4 v[226:229], v[170:171], off offset:2048
	global_load_dwordx4 v[230:233], v[170:171], off offset:3072
	s_waitcnt vmcnt(15)
	v_fma_f32 v140, v102, v140, 0
	v_fmac_f32_e32 v140, v103, v141
	v_fmac_f32_e32 v140, v100, v142
	v_fmac_f32_e32 v140, v101, v143
	s_waitcnt vmcnt(14)
	v_fmac_f32_e32 v140, v104, v160
	v_fmac_f32_e32 v140, v105, v161
	v_fmac_f32_e32 v140, v106, v162
	v_fmac_f32_e32 v140, v107, v163
	s_waitcnt vmcnt(13)
	v_fmac_f32_e32 v140, v108, v178
	v_fmac_f32_e32 v140, v109, v179
	v_fmac_f32_e32 v140, v110, v180
	v_fmac_f32_e32 v140, v111, v181
	s_waitcnt vmcnt(12)
	v_fmac_f32_e32 v140, v112, v182
	v_fmac_f32_e32 v140, v113, v183
	v_fmac_f32_e32 v140, v114, v184
	v_fmac_f32_e32 v140, v115, v185
	s_waitcnt vmcnt(11)
	v_fmac_f32_e32 v140, v116, v186
	v_fmac_f32_e32 v140, v117, v187
	v_fmac_f32_e32 v140, v118, v188
	v_fmac_f32_e32 v140, v119, v189
	s_waitcnt vmcnt(10)
	v_fmac_f32_e32 v140, v120, v190
	v_fmac_f32_e32 v140, v121, v191
	v_fmac_f32_e32 v140, v122, v192
	v_fmac_f32_e32 v140, v123, v193
	s_waitcnt vmcnt(9)
	v_fmac_f32_e32 v140, v124, v194
	v_fmac_f32_e32 v140, v125, v195
	v_fmac_f32_e32 v140, v126, v196
	v_fmac_f32_e32 v140, v127, v197
	s_waitcnt vmcnt(8)
	v_fmac_f32_e32 v140, v136, v198
	v_fmac_f32_e32 v140, v137, v199
	v_fmac_f32_e32 v140, v134, v200
	v_fmac_f32_e32 v140, v135, v201
	v_lshl_add_u64 v[142:143], v[4:5], 0, s[54:55]
	global_load_dwordx4 v[160:163], v[142:143], off
	global_load_dwordx4 v[178:181], v[142:143], off offset:1024
	global_load_dwordx4 v[182:185], v[142:143], off offset:2048
	global_load_dwordx4 v[186:189], v[142:143], off offset:3072
	v_add_co_u32_e64 v142, s[0:1], s65, v142
	s_nop 1
	v_addc_co_u32_e64 v143, s[0:1], 0, v143, s[0:1]
	global_load_dwordx4 v[190:193], v[142:143], off
	global_load_dwordx4 v[194:197], v[142:143], off offset:1024
	global_load_dwordx4 v[198:201], v[142:143], off offset:2048
	global_load_dwordx4 v[234:237], v[142:143], off offset:3072
	s_waitcnt vmcnt(15)
	v_fma_f32 v141, v102, v202, 0
	v_fmac_f32_e32 v141, v103, v203
	v_fmac_f32_e32 v141, v100, v204
	v_fmac_f32_e32 v141, v101, v205
	s_waitcnt vmcnt(14)
	v_fmac_f32_e32 v141, v104, v206
	v_fmac_f32_e32 v141, v105, v207
	v_fmac_f32_e32 v141, v106, v208
	v_fmac_f32_e32 v141, v107, v209
	s_waitcnt vmcnt(13)
	v_fmac_f32_e32 v141, v108, v210
	v_fmac_f32_e32 v141, v109, v211
	v_fmac_f32_e32 v141, v110, v212
	v_fmac_f32_e32 v141, v111, v213
	s_waitcnt vmcnt(12)
	v_fmac_f32_e32 v141, v112, v214
	v_fmac_f32_e32 v141, v113, v215
	v_fmac_f32_e32 v141, v114, v216
	v_fmac_f32_e32 v141, v115, v217
	s_waitcnt vmcnt(11)
	v_fmac_f32_e32 v141, v116, v218
	v_fmac_f32_e32 v141, v117, v219
	v_fmac_f32_e32 v141, v118, v220
	v_fmac_f32_e32 v141, v119, v221
	s_waitcnt vmcnt(10)
	v_fmac_f32_e32 v141, v120, v222
	v_fmac_f32_e32 v141, v121, v223
	v_fmac_f32_e32 v141, v122, v224
	v_fmac_f32_e32 v141, v123, v225
	s_waitcnt vmcnt(9)
	v_fmac_f32_e32 v141, v124, v226
	v_fmac_f32_e32 v141, v125, v227
	v_fmac_f32_e32 v141, v126, v228
	v_fmac_f32_e32 v141, v127, v229
	s_waitcnt vmcnt(8)
	v_fmac_f32_e32 v141, v136, v230
	v_fmac_f32_e32 v141, v137, v231
	v_fmac_f32_e32 v141, v134, v232
	v_fmac_f32_e32 v141, v135, v233
	v_lshl_add_u64 v[4:5], v[4:5], 0, s[56:57]
	global_load_dwordx4 v[202:205], v[4:5], off
	global_load_dwordx4 v[206:209], v[4:5], off offset:1024
	global_load_dwordx4 v[210:213], v[4:5], off offset:2048
	global_load_dwordx4 v[214:217], v[4:5], off offset:3072
	v_add_co_u32_e64 v4, s[0:1], s65, v4
	s_nop 1
	v_addc_co_u32_e64 v5, s[0:1], 0, v5, s[0:1]
	global_load_dwordx4 v[218:221], v[4:5], off
	global_load_dwordx4 v[222:225], v[4:5], off offset:1024
	global_load_dwordx4 v[226:229], v[4:5], off offset:2048
	global_load_dwordx4 v[230:233], v[4:5], off offset:3072
	s_waitcnt vmcnt(15)
	v_fma_f32 v142, v102, v160, 0
	v_fmac_f32_e32 v142, v103, v161
	v_fmac_f32_e32 v142, v100, v162
	v_fmac_f32_e32 v142, v101, v163
	s_waitcnt vmcnt(14)
	v_fmac_f32_e32 v142, v104, v178
	v_fmac_f32_e32 v142, v105, v179
	v_fmac_f32_e32 v142, v106, v180
	v_fmac_f32_e32 v142, v107, v181
	s_waitcnt vmcnt(13)
	v_fmac_f32_e32 v142, v108, v182
	v_fmac_f32_e32 v142, v109, v183
	v_fmac_f32_e32 v142, v110, v184
	v_fmac_f32_e32 v142, v111, v185
	s_waitcnt vmcnt(12)
	v_fmac_f32_e32 v142, v112, v186
	v_fmac_f32_e32 v142, v113, v187
	v_fmac_f32_e32 v142, v114, v188
	v_fmac_f32_e32 v142, v115, v189
	s_waitcnt vmcnt(11)
	v_fmac_f32_e32 v142, v116, v190
	v_fmac_f32_e32 v142, v117, v191
	v_fmac_f32_e32 v142, v118, v192
	v_fmac_f32_e32 v142, v119, v193
	s_waitcnt vmcnt(10)
	v_fmac_f32_e32 v142, v120, v194
	v_fmac_f32_e32 v142, v121, v195
	v_fmac_f32_e32 v142, v122, v196
	v_fmac_f32_e32 v142, v123, v197
	s_waitcnt vmcnt(9)
	v_fmac_f32_e32 v142, v124, v198
	v_fmac_f32_e32 v142, v125, v199
	v_fmac_f32_e32 v142, v126, v200
	v_fmac_f32_e32 v142, v127, v201
	s_waitcnt vmcnt(8)
; __device__ __forceinline__ gv4p launder_g(const float* q) { asm volatile("" : "+v"(q)); return (gv4p)q; }
; __device__ void phase_ln2_route(const Params& p) {
;     ...
;     {
;       const float* wr0_ = wrT + (long)gi[0] * 8 * DM;
;       const float* wr1_ = wrT + (long)gi[1] * 8 * DM;
;       f32x4 wb[2][8];
;       {
;         gv4p wp = launder_g(wr0_ + lane * 4);
; #pragma unroll
;         for (int i = 0; i < 8; i++) wb[0][i] = wp[CH(i) >> 2];
;       }
; #pragma unroll
;       for (int u = 0; u < 16; u++) {
;         if (u + 1 < 16) {
;           gv4p wp = launder_g((((u + 1) >> 3) ? wr1_ : wr0_) + ((u + 1) & 7) * DM + lane * 4);
; #pragma unroll
;           for (int i = 0; i < 8; i++) wb[(u + 1) & 1][i] = wp[CH(i) >> 2];
;         }
;         __builtin_amdgcn_sched_barrier(0);
;         float s0 = 0.f;
; #pragma unroll
;         for (int i = 0; i < 8; i++)
; #pragma unroll
;           for (int e = 0; e < 4; e++) s0 += wb[u & 1][i][e] * v[u >> 3][i * 4 + e];
;         le[u >> 3][u & 7] = s0;
;         __builtin_amdgcn_sched_barrier(0);
;       }
	v_fmac_f32_e32 v142, v136, v234
	v_fmac_f32_e32 v142, v137, v235
	v_fmac_f32_e32 v142, v134, v236
	v_fmac_f32_e32 v142, v135, v237
	v_lshl_add_u64 v[4:5], s[16:17], 0, v[44:45]
	v_mov_b64_e32 v[170:171], v[4:5]
	global_load_dwordx4 v[160:163], v[170:171], off
	global_load_dwordx4 v[178:181], v[170:171], off offset:1024
	global_load_dwordx4 v[182:185], v[170:171], off offset:2048
	global_load_dwordx4 v[186:189], v[170:171], off offset:3072
	v_add_co_u32_e64 v170, s[0:1], s65, v170
	s_nop 1
	v_addc_co_u32_e64 v171, s[0:1], 0, v171, s[0:1]
	global_load_dwordx4 v[190:193], v[170:171], off
	global_load_dwordx4 v[194:197], v[170:171], off offset:1024
	global_load_dwordx4 v[198:201], v[170:171], off offset:2048
	global_load_dwordx4 v[234:237], v[170:171], off offset:3072
	s_waitcnt vmcnt(15)
	v_fma_f32 v102, v102, v202, 0
	v_fmac_f32_e32 v102, v103, v203
	v_fmac_f32_e32 v102, v100, v204
	v_fmac_f32_e32 v102, v101, v205
	s_waitcnt vmcnt(14)
	v_fmac_f32_e32 v102, v104, v206
	v_fmac_f32_e32 v102, v105, v207
	v_fmac_f32_e32 v102, v106, v208
	v_fmac_f32_e32 v102, v107, v209
	s_waitcnt vmcnt(13)
	v_fmac_f32_e32 v102, v108, v210
	v_fmac_f32_e32 v102, v109, v211
	v_fmac_f32_e32 v102, v110, v212
	v_fmac_f32_e32 v102, v111, v213
	s_waitcnt vmcnt(12)
	v_fmac_f32_e32 v102, v112, v214
	v_fmac_f32_e32 v102, v113, v215
	v_fmac_f32_e32 v102, v114, v216
	v_fmac_f32_e32 v102, v115, v217
	s_waitcnt vmcnt(11)
	v_fmac_f32_e32 v102, v116, v218
	v_fmac_f32_e32 v102, v117, v219
	v_fmac_f32_e32 v102, v118, v220
	v_fmac_f32_e32 v102, v119, v221
	s_waitcnt vmcnt(10)
	v_fmac_f32_e32 v102, v120, v222
	v_fmac_f32_e32 v102, v121, v223
	v_fmac_f32_e32 v102, v122, v224
	v_fmac_f32_e32 v102, v123, v225
	s_waitcnt vmcnt(9)
	v_fmac_f32_e32 v102, v124, v226
	v_fmac_f32_e32 v102, v125, v227
	v_fmac_f32_e32 v102, v126, v228
	v_fmac_f32_e32 v102, v127, v229
	s_waitcnt vmcnt(8)
	v_fmac_f32_e32 v102, v136, v230
	v_fmac_f32_e32 v102, v137, v231
	v_fmac_f32_e32 v102, v134, v232
	v_fmac_f32_e32 v102, v135, v233
	v_lshl_add_u64 v[100:101], v[4:5], 0, s[44:45]
	global_load_dwordx4 v[104:107], v[100:101], off
	global_load_dwordx4 v[108:111], v[100:101], off offset:1024
	global_load_dwordx4 v[112:115], v[100:101], off offset:2048
	global_load_dwordx4 v[116:119], v[100:101], off offset:3072
	v_add_co_u32_e64 v100, s[0:1], s65, v100
	s_nop 1
	v_addc_co_u32_e64 v101, s[0:1], 0, v101, s[0:1]
	global_load_dwordx4 v[120:123], v[100:101], off
	global_load_dwordx4 v[124:127], v[100:101], off offset:1024
	global_load_dwordx4 v[134:137], v[100:101], off offset:2048
	global_load_dwordx4 v[202:205], v[100:101], off offset:3072
	s_waitcnt vmcnt(15)
	v_fma_f32 v100, v22, v160, 0
	v_fmac_f32_e32 v100, v23, v161
	v_fmac_f32_e32 v100, v20, v162
	v_fmac_f32_e32 v100, v21, v163
	s_waitcnt vmcnt(14)
	v_fmac_f32_e32 v100, v26, v178
	v_fmac_f32_e32 v100, v27, v179
	v_fmac_f32_e32 v100, v24, v180
	v_fmac_f32_e32 v100, v25, v181
	s_waitcnt vmcnt(13)
	v_fmac_f32_e32 v100, v30, v182
	v_fmac_f32_e32 v100, v31, v183
	v_fmac_f32_e32 v100, v28, v184
	v_fmac_f32_e32 v100, v29, v185
	s_waitcnt vmcnt(12)
	v_fmac_f32_e32 v100, v34, v186
	v_fmac_f32_e32 v100, v35, v187
	v_fmac_f32_e32 v100, v32, v188
	v_fmac_f32_e32 v100, v33, v189
	s_waitcnt vmcnt(11)
	v_fmac_f32_e32 v100, v38, v190
	v_fmac_f32_e32 v100, v39, v191
	v_fmac_f32_e32 v100, v36, v192
	v_fmac_f32_e32 v100, v37, v193
	s_waitcnt vmcnt(10)
	v_fmac_f32_e32 v100, v42, v194
	v_fmac_f32_e32 v100, v43, v195
	v_fmac_f32_e32 v100, v40, v196
	v_fmac_f32_e32 v100, v41, v197
	s_waitcnt vmcnt(9)
	v_fmac_f32_e32 v100, v94, v198
	v_fmac_f32_e32 v100, v95, v199
	v_fmac_f32_e32 v100, v92, v200
	v_fmac_f32_e32 v100, v93, v201
	s_waitcnt vmcnt(8)
	v_fmac_f32_e32 v100, v98, v234
	v_fmac_f32_e32 v100, v99, v235
	v_fmac_f32_e32 v100, v96, v236
	v_fmac_f32_e32 v100, v97, v237
	v_lshl_add_u64 v[170:171], v[4:5], 0, s[46:47]
	global_load_dwordx4 v[160:163], v[170:171], off
	global_load_dwordx4 v[178:181], v[170:171], off offset:1024
	global_load_dwordx4 v[182:185], v[170:171], off offset:2048
	global_load_dwordx4 v[186:189], v[170:171], off offset:3072
	v_add_co_u32_e64 v170, s[0:1], s65, v170
	s_nop 1
	v_addc_co_u32_e64 v171, s[0:1], 0, v171, s[0:1]
	global_load_dwordx4 v[190:193], v[170:171], off
	global_load_dwordx4 v[194:197], v[170:171], off offset:1024
	global_load_dwordx4 v[198:201], v[170:171], off offset:2048
	global_load_dwordx4 v[206:209], v[170:171], off offset:3072
	s_waitcnt vmcnt(15)
	v_fma_f32 v101, v22, v104, 0
	v_fmac_f32_e32 v101, v23, v105
	v_fmac_f32_e32 v101, v20, v106
	v_fmac_f32_e32 v101, v21, v107
	s_waitcnt vmcnt(14)
	v_fmac_f32_e32 v101, v26, v108
	v_fmac_f32_e32 v101, v27, v109
	v_fmac_f32_e32 v101, v24, v110
	v_fmac_f32_e32 v101, v25, v111
	s_waitcnt vmcnt(13)
	v_fmac_f32_e32 v101, v30, v112
	v_fmac_f32_e32 v101, v31, v113
	v_fmac_f32_e32 v101, v28, v114
	v_fmac_f32_e32 v101, v29, v115
	s_waitcnt vmcnt(12)
	v_fmac_f32_e32 v101, v34, v116
	v_fmac_f32_e32 v101, v35, v117
	v_fmac_f32_e32 v101, v32, v118
	v_fmac_f32_e32 v101, v33, v119
	s_waitcnt vmcnt(11)
	v_fmac_f32_e32 v101, v38, v120
	v_fmac_f32_e32 v101, v39, v121
	v_fmac_f32_e32 v101, v36, v122
	v_fmac_f32_e32 v101, v37, v123
	s_waitcnt vmcnt(10)
	v_fmac_f32_e32 v101, v42, v124
	v_fmac_f32_e32 v101, v43, v125
	v_fmac_f32_e32 v101, v40, v126
	v_fmac_f32_e32 v101, v41, v127
	s_waitcnt vmcnt(9)
	v_fmac_f32_e32 v101, v94, v134
	v_fmac_f32_e32 v101, v95, v135
	v_fmac_f32_e32 v101, v92, v136
	v_fmac_f32_e32 v101, v93, v137
	s_waitcnt vmcnt(8)
; __device__ __forceinline__ gv4p launder_g(const float* q) { asm volatile("" : "+v"(q)); return (gv4p)q; }
; __device__ void phase_ln2_route(const Params& p) {
;     ...
; #pragma unroll
;       for (int u = 0; u < 16; u++) {
;         if (u + 1 < 16) {
;           gv4p wp = launder_g((((u + 1) >> 3) ? wr1_ : wr0_) + ((u + 1) & 7) * DM + lane * 4);
; #pragma unroll
;           for (int i = 0; i < 8; i++) wb[(u + 1) & 1][i] = wp[CH(i) >> 2];
;         }
;         __builtin_amdgcn_sched_barrier(0);
;         float s0 = 0.f;
; #pragma unroll
;         for (int i = 0; i < 8; i++)
; #pragma unroll
;           for (int e = 0; e < 4; e++) s0 += wb[u & 1][i][e] * v[u >> 3][i * 4 + e];
;         le[u >> 3][u & 7] = s0;
;         __builtin_amdgcn_sched_barrier(0);
;       }
	v_fmac_f32_e32 v101, v98, v202
	v_fmac_f32_e32 v101, v99, v203
	v_fmac_f32_e32 v101, v96, v204
	v_fmac_f32_e32 v101, v97, v205
	v_lshl_add_u64 v[120:121], v[4:5], 0, s[48:49]
	global_load_dwordx4 v[104:107], v[120:121], off
	global_load_dwordx4 v[108:111], v[120:121], off offset:1024
	global_load_dwordx4 v[112:115], v[120:121], off offset:2048
	global_load_dwordx4 v[116:119], v[120:121], off offset:3072
	v_add_co_u32_e64 v170, s[0:1], s65, v120
	s_nop 1
	v_addc_co_u32_e64 v171, s[0:1], 0, v121, s[0:1]
	global_load_dwordx4 v[120:123], v[170:171], off
	global_load_dwordx4 v[124:127], v[170:171], off offset:1024
	global_load_dwordx4 v[134:137], v[170:171], off offset:2048
	global_load_dwordx4 v[202:205], v[170:171], off offset:3072
	s_waitcnt vmcnt(15)
	v_fma_f32 v103, v22, v160, 0
	v_fmac_f32_e32 v103, v23, v161
	v_fmac_f32_e32 v103, v20, v162
	v_fmac_f32_e32 v103, v21, v163
	s_waitcnt vmcnt(14)
	v_fmac_f32_e32 v103, v26, v178
	v_fmac_f32_e32 v103, v27, v179
	v_fmac_f32_e32 v103, v24, v180
	v_fmac_f32_e32 v103, v25, v181
	s_waitcnt vmcnt(13)
	v_fmac_f32_e32 v103, v30, v182
	v_fmac_f32_e32 v103, v31, v183
	v_fmac_f32_e32 v103, v28, v184
	v_fmac_f32_e32 v103, v29, v185
	s_waitcnt vmcnt(12)
	v_fmac_f32_e32 v103, v34, v186
	v_fmac_f32_e32 v103, v35, v187
	v_fmac_f32_e32 v103, v32, v188
	v_fmac_f32_e32 v103, v33, v189
	s_waitcnt vmcnt(11)
	v_fmac_f32_e32 v103, v38, v190
	v_fmac_f32_e32 v103, v39, v191
	v_fmac_f32_e32 v103, v36, v192
	v_fmac_f32_e32 v103, v37, v193
	s_waitcnt vmcnt(10)
	v_fmac_f32_e32 v103, v42, v194
	v_fmac_f32_e32 v103, v43, v195
	v_fmac_f32_e32 v103, v40, v196
	v_fmac_f32_e32 v103, v41, v197
	s_waitcnt vmcnt(9)
	v_fmac_f32_e32 v103, v94, v198
	v_fmac_f32_e32 v103, v95, v199
	v_fmac_f32_e32 v103, v92, v200
	v_fmac_f32_e32 v103, v93, v201
	s_waitcnt vmcnt(8)
	v_fmac_f32_e32 v103, v98, v206
	v_fmac_f32_e32 v103, v99, v207
	v_fmac_f32_e32 v103, v96, v208
	v_fmac_f32_e32 v103, v97, v209
	v_lshl_add_u64 v[170:171], v[4:5], 0, s[50:51]
	global_load_dwordx4 v[160:163], v[170:171], off
	global_load_dwordx4 v[178:181], v[170:171], off offset:1024
	global_load_dwordx4 v[182:185], v[170:171], off offset:2048
	global_load_dwordx4 v[186:189], v[170:171], off offset:3072
	v_add_co_u32_e64 v170, s[0:1], s65, v170
	s_nop 1
	v_addc_co_u32_e64 v171, s[0:1], 0, v171, s[0:1]
	global_load_dwordx4 v[190:193], v[170:171], off
	global_load_dwordx4 v[194:197], v[170:171], off offset:1024
	global_load_dwordx4 v[198:201], v[170:171], off offset:2048
	global_load_dwordx4 v[206:209], v[170:171], off offset:3072
	s_waitcnt vmcnt(15)
	v_fma_f32 v143, v22, v104, 0
	v_fmac_f32_e32 v143, v23, v105
	v_fmac_f32_e32 v143, v20, v106
	v_fmac_f32_e32 v143, v21, v107
	s_waitcnt vmcnt(14)
	v_fmac_f32_e32 v143, v26, v108
	v_fmac_f32_e32 v143, v27, v109
	v_fmac_f32_e32 v143, v24, v110
	v_fmac_f32_e32 v143, v25, v111
	s_waitcnt vmcnt(13)
	v_fmac_f32_e32 v143, v30, v112
	v_fmac_f32_e32 v143, v31, v113
	v_fmac_f32_e32 v143, v28, v114
	v_fmac_f32_e32 v143, v29, v115
	s_waitcnt vmcnt(12)
	v_fmac_f32_e32 v143, v34, v116
	v_fmac_f32_e32 v143, v35, v117
	v_fmac_f32_e32 v143, v32, v118
	v_fmac_f32_e32 v143, v33, v119
	s_waitcnt vmcnt(11)
	v_fmac_f32_e32 v143, v38, v120
	v_fmac_f32_e32 v143, v39, v121
	v_fmac_f32_e32 v143, v36, v122
	v_fmac_f32_e32 v143, v37, v123
	s_waitcnt vmcnt(10)
	v_fmac_f32_e32 v143, v42, v124
	v_fmac_f32_e32 v143, v43, v125
	v_fmac_f32_e32 v143, v40, v126
	v_fmac_f32_e32 v143, v41, v127
	s_waitcnt vmcnt(9)
	v_fmac_f32_e32 v143, v94, v134
	v_fmac_f32_e32 v143, v95, v135
	v_fmac_f32_e32 v143, v92, v136
	v_fmac_f32_e32 v143, v93, v137
	s_waitcnt vmcnt(8)
	v_fmac_f32_e32 v143, v98, v202
	v_fmac_f32_e32 v143, v99, v203
	v_fmac_f32_e32 v143, v96, v204
	v_fmac_f32_e32 v143, v97, v205
	v_lshl_add_u64 v[120:121], v[4:5], 0, s[52:53]
	global_load_dwordx4 v[104:107], v[120:121], off
	global_load_dwordx4 v[108:111], v[120:121], off offset:1024
	global_load_dwordx4 v[112:115], v[120:121], off offset:2048
	global_load_dwordx4 v[116:119], v[120:121], off offset:3072
	v_add_co_u32_e64 v170, s[0:1], s65, v120
	s_nop 1
	v_addc_co_u32_e64 v171, s[0:1], 0, v121, s[0:1]
	global_load_dwordx4 v[120:123], v[170:171], off
	global_load_dwordx4 v[124:127], v[170:171], off offset:1024
	global_load_dwordx4 v[134:137], v[170:171], off offset:2048
	global_load_dwordx4 v[202:205], v[170:171], off offset:3072
	s_waitcnt vmcnt(15)
	v_fma_f32 v144, v22, v160, 0
	v_fmac_f32_e32 v144, v23, v161
	v_fmac_f32_e32 v144, v20, v162
	v_fmac_f32_e32 v144, v21, v163
	s_waitcnt vmcnt(14)
	v_fmac_f32_e32 v144, v26, v178
	v_fmac_f32_e32 v144, v27, v179
	v_fmac_f32_e32 v144, v24, v180
	v_fmac_f32_e32 v144, v25, v181
	s_waitcnt vmcnt(13)
	v_fmac_f32_e32 v144, v30, v182
	v_fmac_f32_e32 v144, v31, v183
	v_fmac_f32_e32 v144, v28, v184
	v_fmac_f32_e32 v144, v29, v185
	s_waitcnt vmcnt(12)
	v_fmac_f32_e32 v144, v34, v186
	v_fmac_f32_e32 v144, v35, v187
	v_fmac_f32_e32 v144, v32, v188
	v_fmac_f32_e32 v144, v33, v189
	s_waitcnt vmcnt(11)
	v_fmac_f32_e32 v144, v38, v190
	v_fmac_f32_e32 v144, v39, v191
	v_fmac_f32_e32 v144, v36, v192
	v_fmac_f32_e32 v144, v37, v193
	s_waitcnt vmcnt(10)
	v_fmac_f32_e32 v144, v42, v194
	v_fmac_f32_e32 v144, v43, v195
	v_fmac_f32_e32 v144, v40, v196
	v_fmac_f32_e32 v144, v41, v197
	s_waitcnt vmcnt(9)
	v_fmac_f32_e32 v144, v94, v198
	v_fmac_f32_e32 v144, v95, v199
	v_fmac_f32_e32 v144, v92, v200
	v_fmac_f32_e32 v144, v93, v201
	s_waitcnt vmcnt(8)
; __device__ __forceinline__ gv4p launder_g(const float* q) { asm volatile("" : "+v"(q)); return (gv4p)q; }
; __device__ __forceinline__ void wave_reduce8(float (&a)[8], int lane) {
;   float b[4], c[2], d;
;   const bool h5 = lane & 32, h4 = lane & 16, h3 = lane & 8;
; #pragma unroll
;   for (int k = 0; k < 4; k++) {
;     float send = h5 ? a[k] : a[k + 4];
;     float keep = h5 ? a[k + 4] : a[k];
;     b[k] = keep + __shfl_xor(send, 32);
;   }
; #pragma unroll
;   for (int k = 0; k < 2; k++) {
;     float send = h4 ? b[k] : b[k + 2];
;     float keep = h4 ? b[k + 2] : b[k];
;     c[k] = keep + __shfl_xor(send, 16);
;   }
;   {
;     float send = h3 ? c[0] : c[1];
;     float keep = h3 ? c[1] : c[0];
;     d = keep + __shfl_xor(send, 8);
;   }
;   d += __shfl_xor(d, 4);
;   d += __shfl_xor(d, 2);
;   d += __shfl_xor(d, 1);
; #pragma unroll
;   for (int g = 0; g < 8; g++) a[g] = __shfl(d, ((g >> 2) & 1) * 32 + ((g >> 1) & 1) * 16 + (g & 1) * 8);
; }
; __device__ void phase_ln2_route(const Params& p) {
;     ...
; #pragma unroll
;       for (int u = 0; u < 16; u++) {
;         if (u + 1 < 16) {
;           gv4p wp = launder_g((((u + 1) >> 3) ? wr1_ : wr0_) + ((u + 1) & 7) * DM + lane * 4);
; #pragma unroll
;           for (int i = 0; i < 8; i++) wb[(u + 1) & 1][i] = wp[CH(i) >> 2];
;         }
;         __builtin_amdgcn_sched_barrier(0);
;         float s0 = 0.f;
; #pragma unroll
;         for (int i = 0; i < 8; i++)
; #pragma unroll
;           for (int e = 0; e < 4; e++) s0 += wb[u & 1][i][e] * v[u >> 3][i * 4 + e];
;         le[u >> 3][u & 7] = s0;
;         __builtin_amdgcn_sched_barrier(0);
;       }
;     }
;     wave_reduce8(le[0], lane);
;     wave_reduce8(le[1], lane);
; #pragma unroll
	v_fmac_f32_e32 v144, v98, v206
	v_fmac_f32_e32 v144, v99, v207
	v_fmac_f32_e32 v144, v96, v208
	v_fmac_f32_e32 v144, v97, v209
	v_lshl_add_u64 v[170:171], v[4:5], 0, s[54:55]
	global_load_dwordx4 v[160:163], v[170:171], off
	global_load_dwordx4 v[178:181], v[170:171], off offset:1024
	global_load_dwordx4 v[182:185], v[170:171], off offset:2048
	global_load_dwordx4 v[186:189], v[170:171], off offset:3072
	v_add_co_u32_e64 v170, s[0:1], s65, v170
	s_nop 1
	v_addc_co_u32_e64 v171, s[0:1], 0, v171, s[0:1]
	global_load_dwordx4 v[190:193], v[170:171], off
	global_load_dwordx4 v[194:197], v[170:171], off offset:1024
	global_load_dwordx4 v[198:201], v[170:171], off offset:2048
	global_load_dwordx4 v[206:209], v[170:171], off offset:3072
	s_waitcnt vmcnt(15)
	v_fma_f32 v170, v22, v104, 0
	v_fmac_f32_e32 v170, v23, v105
	v_fmac_f32_e32 v170, v20, v106
	v_fmac_f32_e32 v170, v21, v107
	s_waitcnt vmcnt(14)
	v_fmac_f32_e32 v170, v26, v108
	v_fmac_f32_e32 v170, v27, v109
	v_fmac_f32_e32 v170, v24, v110
	v_fmac_f32_e32 v170, v25, v111
	s_waitcnt vmcnt(13)
	v_fmac_f32_e32 v170, v30, v112
	v_fmac_f32_e32 v170, v31, v113
	v_fmac_f32_e32 v170, v28, v114
	v_fmac_f32_e32 v170, v29, v115
	s_waitcnt vmcnt(12)
	v_fmac_f32_e32 v170, v34, v116
	v_fmac_f32_e32 v170, v35, v117
	v_fmac_f32_e32 v170, v32, v118
	v_fmac_f32_e32 v170, v33, v119
	s_waitcnt vmcnt(11)
	v_fmac_f32_e32 v170, v38, v120
	v_fmac_f32_e32 v170, v39, v121
	v_fmac_f32_e32 v170, v36, v122
	v_fmac_f32_e32 v170, v37, v123
	s_waitcnt vmcnt(10)
	v_fmac_f32_e32 v170, v42, v124
	v_fmac_f32_e32 v170, v43, v125
	v_fmac_f32_e32 v170, v40, v126
	v_fmac_f32_e32 v170, v41, v127
	s_waitcnt vmcnt(9)
	v_fmac_f32_e32 v170, v94, v134
	v_fmac_f32_e32 v170, v95, v135
	v_fmac_f32_e32 v170, v92, v136
	v_fmac_f32_e32 v170, v93, v137
	s_waitcnt vmcnt(8)
	v_fmac_f32_e32 v170, v98, v202
	v_fmac_f32_e32 v170, v99, v203
	v_fmac_f32_e32 v170, v96, v204
	v_fmac_f32_e32 v170, v97, v205
	v_lshl_add_u64 v[4:5], v[4:5], 0, s[56:57]
	global_load_dwordx4 v[104:107], v[4:5], off
	global_load_dwordx4 v[108:111], v[4:5], off offset:1024
	global_load_dwordx4 v[112:115], v[4:5], off offset:2048
	global_load_dwordx4 v[116:119], v[4:5], off offset:3072
	v_add_co_u32_e64 v4, s[0:1], s65, v4
	s_nop 1
	v_addc_co_u32_e64 v5, s[0:1], 0, v5, s[0:1]
	global_load_dwordx4 v[120:123], v[4:5], off
	global_load_dwordx4 v[124:127], v[4:5], off offset:1024
	global_load_dwordx4 v[134:137], v[4:5], off offset:2048
	global_load_dwordx4 v[202:205], v[4:5], off offset:3072
	s_waitcnt vmcnt(15)
	v_fma_f32 v4, v22, v160, 0
	v_fmac_f32_e32 v4, v23, v161
	v_fmac_f32_e32 v4, v20, v162
	v_fmac_f32_e32 v4, v21, v163
	s_waitcnt vmcnt(14)
	v_fmac_f32_e32 v4, v26, v178
	v_fmac_f32_e32 v4, v27, v179
	v_fmac_f32_e32 v4, v24, v180
	v_fmac_f32_e32 v4, v25, v181
	s_waitcnt vmcnt(13)
	v_fmac_f32_e32 v4, v30, v182
	v_fmac_f32_e32 v4, v31, v183
	v_fmac_f32_e32 v4, v28, v184
	v_fmac_f32_e32 v4, v29, v185
	s_waitcnt vmcnt(12)
	v_fmac_f32_e32 v4, v34, v186
	v_fmac_f32_e32 v4, v35, v187
	v_fmac_f32_e32 v4, v32, v188
	v_fmac_f32_e32 v4, v33, v189
	s_waitcnt vmcnt(11)
	v_fmac_f32_e32 v4, v38, v190
	v_fmac_f32_e32 v4, v39, v191
	v_fmac_f32_e32 v4, v36, v192
	v_fmac_f32_e32 v4, v37, v193
	s_waitcnt vmcnt(10)
	v_fmac_f32_e32 v4, v42, v194
	v_fmac_f32_e32 v4, v43, v195
	v_fmac_f32_e32 v4, v40, v196
	v_fmac_f32_e32 v4, v41, v197
	s_waitcnt vmcnt(9)
	v_fmac_f32_e32 v4, v94, v198
	v_fmac_f32_e32 v4, v95, v199
	v_fmac_f32_e32 v4, v92, v200
	v_fmac_f32_e32 v4, v93, v201
	s_waitcnt vmcnt(8)
	v_fmac_f32_e32 v4, v98, v206
	v_fmac_f32_e32 v4, v99, v207
	v_fmac_f32_e32 v4, v96, v208
	v_fmac_f32_e32 v4, v97, v209
	s_waitcnt vmcnt(7)
	v_fma_f32 v5, v22, v104, 0
	v_fmac_f32_e32 v5, v23, v105
	v_fmac_f32_e32 v5, v20, v106
	v_fmac_f32_e32 v5, v21, v107
	s_waitcnt vmcnt(6)
	v_fmac_f32_e32 v5, v26, v108
	v_fmac_f32_e32 v5, v27, v109
	v_fmac_f32_e32 v5, v24, v110
	v_fmac_f32_e32 v5, v25, v111
	s_waitcnt vmcnt(5)
	v_fmac_f32_e32 v5, v30, v112
	v_fmac_f32_e32 v5, v31, v113
	v_fmac_f32_e32 v5, v28, v114
	v_fmac_f32_e32 v5, v29, v115
	s_waitcnt vmcnt(4)
	v_fmac_f32_e32 v5, v34, v116
	v_fmac_f32_e32 v5, v35, v117
	v_fmac_f32_e32 v5, v32, v118
	v_fmac_f32_e32 v5, v33, v119
	s_waitcnt vmcnt(3)
	v_fmac_f32_e32 v5, v38, v120
	v_fmac_f32_e32 v5, v39, v121
	v_fmac_f32_e32 v5, v36, v122
	v_fmac_f32_e32 v5, v37, v123
	s_waitcnt vmcnt(2)
	v_fmac_f32_e32 v5, v42, v124
	v_fmac_f32_e32 v5, v43, v125
	v_fmac_f32_e32 v5, v40, v126
	v_fmac_f32_e32 v5, v41, v127
	s_waitcnt vmcnt(1)
	v_fmac_f32_e32 v5, v94, v134
	v_fmac_f32_e32 v5, v95, v135
	v_fmac_f32_e32 v5, v92, v136
	v_fmac_f32_e32 v5, v93, v137
	s_waitcnt vmcnt(0)
	v_fmac_f32_e32 v5, v98, v202
	v_fmac_f32_e32 v5, v99, v203
	v_fmac_f32_e32 v5, v96, v204
	v_fmac_f32_e32 v5, v97, v205
	v_cndmask_b32_e64 v20, v6, v140, s[6:7]
	ds_bpermute_b32 v20, v89, v20
	v_cndmask_b32_e64 v6, v140, v6, s[6:7]
	v_cndmask_b32_e64 v21, v7, v141, s[6:7]
	ds_bpermute_b32 v21, v89, v21
	v_cndmask_b32_e64 v22, v139, v102, s[6:7]
	s_waitcnt lgkmcnt(1)
	v_add_f32_e32 v6, v6, v20
	v_cndmask_b32_e64 v20, v138, v142, s[6:7]
	ds_bpermute_b32 v20, v89, v20
	ds_bpermute_b32 v22, v89, v22
	v_cndmask_b32_e64 v7, v141, v7, s[6:7]
	s_waitcnt lgkmcnt(2)
	v_add_f32_e32 v7, v7, v21
	v_cndmask_b32_e64 v21, v142, v138, s[6:7]
	s_waitcnt lgkmcnt(1)
	v_add_f32_e32 v20, v21, v20
	v_cndmask_b32_e64 v21, v102, v139, s[6:7]
	s_waitcnt lgkmcnt(0)
	v_add_f32_e32 v21, v21, v22
	v_cndmask_b32_e64 v22, v6, v20, s[8:9]
	v_cndmask_b32_e64 v23, v7, v21, s[8:9]
	ds_bpermute_b32 v22, v145, v22
	ds_bpermute_b32 v23, v145, v23
	v_cndmask_b32_e64 v6, v20, v6, s[8:9]
	v_cndmask_b32_e64 v7, v21, v7, s[8:9]
	v_cndmask_b32_e64 v21, v170, v101, s[6:7]
	s_waitcnt lgkmcnt(1)
; __device__ __forceinline__ void wave_reduce8(float (&a)[8], int lane) {
;   float b[4], c[2], d;
;   const bool h5 = lane & 32, h4 = lane & 16, h3 = lane & 8;
; #pragma unroll
;   for (int k = 0; k < 4; k++) {
;     float send = h5 ? a[k] : a[k + 4];
;     float keep = h5 ? a[k + 4] : a[k];
;     b[k] = keep + __shfl_xor(send, 32);
; __device__ void phase_ln2_route(const Params& p) {
;     ...
; #pragma unroll
;     for (int q = 0; q < 2; q++) {
; #pragma unroll
;       for (int g = 0; g < 8; g++) lg[q][g] += p.b_group[g];
;       int bi = 0; float gm = lg[q][0];
; #pragma unroll
;       for (int g = 1; g < 8; g++) if (lg[q][g] > gm) { gm = lg[q][g]; bi = g; }
;       float gs = 0.f;
; #pragma unroll
;       for (int g = 0; g < 8; g++) gs += __expf(lg[q][g] - gm);
;       gval[q] = 1.f / gs;
;       gi[q] = __builtin_amdgcn_readfirstlane(bi);
;     }
;     float le[2][8];
;     {
;       const float* wr0_ = wrT + (long)gi[0] * 8 * DM;
;       const float* wr1_ = wrT + (long)gi[1] * 8 * DM;
;       f32x4 wb[2][8];
;       {
;         gv4p wp = launder_g(wr0_ + lane * 4);
; #pragma unroll
;         for (int i = 0; i < 8; i++) wb[0][i] = wp[CH(i) >> 2];
;       }
; #pragma unroll
;       for (int u = 0; u < 16; u++) {
;         if (u + 1 < 16) {
;           gv4p wp = launder_g((((u + 1) >> 3) ? wr1_ : wr0_) + ((u + 1) & 7) * DM + lane * 4);
; #pragma unroll
;           for (int i = 0; i < 8; i++) wb[(u + 1) & 1][i] = wp[CH(i) >> 2];
;         }
;         __builtin_amdgcn_sched_barrier(0);
;         float s0 = 0.f;
; #pragma unroll
;         for (int i = 0; i < 8; i++)
; #pragma unroll
;           for (int e = 0; e < 4; e++) s0 += wb[u & 1][i][e] * v[u >> 3][i * 4 + e];
;         le[u >> 3][u & 7] = s0;
;         __builtin_amdgcn_sched_barrier(0);
;       }
;     }
;     wave_reduce8(le[0], lane);
;     wave_reduce8(le[1], lane);
; #pragma unroll
;     for (int q = 0; q < 2; q++) {
; #pragma unroll
;       for (int g = 0; g < 8; g++) le[q][g] += p.b_router[gi[q] * 8 + g];
;       int i1 = 0; float v1 = le[q][0];
; #pragma unroll
;       for (int g = 1; g < 8; g++) if (le[q][g] > v1) { v1 = le[q][g]; i1 = g; }
;       int i2 = 0; float v2 = -3.0e38f;
; #pragma unroll
;       for (int g = 0; g < 8; g++) if (g != i1 && le[q][g] > v2) { v2 = le[q][g]; i2 = g; }
;       float e2 = __expf(v2 - v1);
;       float g1 = gval[q] / (1.f + e2), g2 = gval[q] * e2 / (1.f + e2);
	v_add_f32_e32 v6, v6, v22
	s_waitcnt lgkmcnt(0)
	v_add_f32_e32 v7, v7, v23
	v_cndmask_b32_e64 v20, v6, v7, s[10:11]
	ds_bpermute_b32 v20, v146, v20
	v_cndmask_b32_e64 v6, v7, v6, s[10:11]
	v_cndmask_b32_e64 v22, v103, v4, s[6:7]
	v_cndmask_b32_e64 v23, v143, v5, s[6:7]
	ds_bpermute_b32 v22, v89, v22
	s_waitcnt lgkmcnt(1)
	v_add_f32_e32 v6, v6, v20
	ds_bpermute_b32 v7, v147, v6
	v_cndmask_b32_e64 v20, v100, v144, s[6:7]
	ds_bpermute_b32 v20, v89, v20
	ds_bpermute_b32 v23, v89, v23
	v_cndmask_b32_e64 v4, v4, v103, s[6:7]
	s_waitcnt lgkmcnt(2)
	v_add_f32_e32 v6, v6, v7
	v_cndmask_b32_e64 v7, v144, v100, s[6:7]
	s_waitcnt lgkmcnt(1)
	v_add_f32_e32 v7, v7, v20
	v_cndmask_b32_e64 v20, v101, v170, s[6:7]
	ds_bpermute_b32 v20, v89, v20
	v_cndmask_b32_e64 v5, v5, v143, s[6:7]
	v_add_f32_e32 v4, v4, v22
	s_waitcnt lgkmcnt(1)
	v_add_f32_e32 v5, v5, v23
	ds_bpermute_b32 v23, v148, v6
	s_waitcnt lgkmcnt(1)
	v_add_f32_e32 v20, v21, v20
	v_cndmask_b32_e64 v21, v7, v4, s[8:9]
	v_cndmask_b32_e64 v22, v20, v5, s[8:9]
	ds_bpermute_b32 v21, v145, v21
	ds_bpermute_b32 v22, v145, v22
	v_cndmask_b32_e64 v4, v4, v7, s[8:9]
	v_cndmask_b32_e64 v5, v5, v20, s[8:9]
	s_waitcnt lgkmcnt(2)
	v_add_f32_e32 v6, v6, v23
	s_waitcnt lgkmcnt(1)
	v_add_f32_e32 v4, v4, v21
	s_waitcnt lgkmcnt(0)
	v_add_f32_e32 v5, v5, v22
	v_cndmask_b32_e64 v7, v4, v5, s[10:11]
	ds_bpermute_b32 v7, v146, v7
	v_cndmask_b32_e64 v4, v5, v4, s[10:11]
	ds_bpermute_b32 v20, v149, v6
	s_waitcnt lgkmcnt(1)
	v_add_f32_e32 v4, v4, v7
	ds_bpermute_b32 v5, v147, v4
	s_waitcnt lgkmcnt(1)
	v_add_f32_e32 v20, v6, v20
	ds_bpermute_b32 v6, v150, v20
	ds_bpermute_b32 v7, v151, v20
	ds_bpermute_b32 v26, v152, v20
	s_waitcnt lgkmcnt(3)
	v_add_f32_e32 v4, v4, v5
	ds_bpermute_b32 v5, v148, v4
	ds_bpermute_b32 v27, v153, v20
	ds_bpermute_b32 v28, v154, v20
	ds_bpermute_b32 v29, v155, v20
	ds_bpermute_b32 v30, v156, v20
	s_waitcnt lgkmcnt(4)
	v_add_f32_e32 v4, v4, v5
	ds_bpermute_b32 v5, v149, v4
	ds_bpermute_b32 v31, v157, v20
	s_waitcnt lgkmcnt(1)
	v_add_f32_e32 v25, v4, v5
	ds_bpermute_b32 v4, v150, v25
	ds_bpermute_b32 v5, v151, v25
	ds_bpermute_b32 v20, v152, v25
	ds_bpermute_b32 v21, v153, v25
	ds_bpermute_b32 v22, v154, v25
	ds_bpermute_b32 v23, v155, v25
	ds_bpermute_b32 v24, v156, v25
	ds_bpermute_b32 v25, v157, v25
	s_and_saveexec_b64 s[60:61], s[12:13]
	s_cbranch_execz .LBB0_817
	s_lshl_b32 s62, s24, 3
	s_ashr_i32 s63, s62, 31
	v_readlane_b32 s76, v255, 8
	s_lshl_b64 s[0:1], s[62:63], 2
	v_readlane_b32 s82, v255, 14
	v_readlane_b32 s83, v255, 15
	s_add_u32 s0, s82, s0
	s_addc_u32 s1, s83, s1
	global_load_dwordx4 v[32:35], v45, s[0:1] offset:16
	global_load_dwordx4 v[36:39], v45, s[0:1]
	v_cndmask_b32_e32 v40, v91, v87, vcc
	v_sub_f32_e32 v2, v2, v40
	v_sub_f32_e32 v3, v3, v40
	v_mul_f32_e32 v2, 0x3fb8aa3b, v2
	v_sub_f32_e32 v15, v15, v40
	v_mul_f32_e32 v3, 0x3fb8aa3b, v3
	v_exp_f32_e32 v2, v2
	v_sub_f32_e32 v16, v16, v40
	v_mul_f32_e32 v15, 0x3fb8aa3b, v15
	v_exp_f32_e32 v3, v3
	v_sub_f32_e32 v17, v17, v40
	v_mul_f32_e32 v16, 0x3fb8aa3b, v16
	v_exp_f32_e32 v15, v15
	v_sub_f32_e32 v18, v18, v40
	v_mul_f32_e32 v17, 0x3fb8aa3b, v17
	v_exp_f32_e32 v16, v16
	v_sub_f32_e32 v19, v19, v40
	v_mul_f32_e32 v18, 0x3fb8aa3b, v18
	v_exp_f32_e32 v17, v17
	v_add_f32_e32 v2, 0, v2
	v_sub_f32_e32 v40, v87, v40
	v_mul_f32_e32 v19, 0x3fb8aa3b, v19
	v_exp_f32_e32 v18, v18
	v_add_f32_e32 v2, v3, v2
	v_mul_f32_e32 v40, 0x3fb8aa3b, v40
	v_exp_f32_e32 v19, v19
	v_add_f32_e32 v2, v15, v2
	v_exp_f32_e32 v40, v40
	v_add_f32_e32 v2, v16, v2
	v_add_f32_e32 v2, v17, v2
	v_add_f32_e32 v2, v18, v2
	v_add_f32_e32 v2, v19, v2
	v_add_f32_e32 v15, v40, v2
	v_div_scale_f32 v2, s[0:1], v15, v15, 1.0
	v_rcp_f32_e32 v3, v2
	v_div_scale_f32 v16, vcc, 1.0, v15, 1.0
	v_cndmask_b32_e64 v14, v14, v8, s[14:15]
	v_fma_f32 v17, -v2, v3, 1.0
	v_fmac_f32_e32 v3, v17, v3
	v_mul_f32_e32 v17, v16, v3
	v_fma_f32 v18, -v2, v17, v16
	v_fmac_f32_e32 v17, v18, v3
	v_fma_f32 v2, -v2, v17, v16
	v_div_fmas_f32 v16, v2, v3, v17
	v_sub_f32_e32 v0, v0, v14
	v_mul_f32_e32 v0, 0x3fb8aa3b, v0
	v_sub_f32_e32 v12, v12, v14
	v_mul_f32_e32 v12, 0x3fb8aa3b, v12
	v_sub_f32_e32 v11, v11, v14
	v_exp_f32_e32 v12, v12
	v_mul_f32_e32 v11, 0x3fb8aa3b, v11
	v_sub_f32_e32 v10, v10, v14
	v_exp_f32_e32 v11, v11
	v_mul_f32_e32 v10, 0x3fb8aa3b, v10
	v_sub_f32_e32 v9, v9, v14
	v_exp_f32_e32 v10, v10
	v_mul_f32_e32 v9, 0x3fb8aa3b, v9
	v_sub_f32_e32 v8, v8, v14
	v_exp_f32_e32 v9, v9
	v_mul_f32_e32 v8, 0x3fb8aa3b, v8
	v_exp_f32_e32 v8, v8
	v_ashrrev_i32_e32 v87, 31, v86
	v_readlane_b32 s77, v255, 9
	v_readlane_b32 s78, v255, 10
	v_readlane_b32 s79, v255, 11
	v_readlane_b32 s80, v255, 12
	v_readlane_b32 s81, v255, 13
	v_readlane_b32 s84, v255, 16
	v_readlane_b32 s85, v255, 17
	v_readlane_b32 s86, v255, 18
	v_readlane_b32 s87, v255, 19
	v_readlane_b32 s88, v255, 20
	v_readlane_b32 s89, v255, 21
	v_readlane_b32 s90, v255, 22
	v_readlane_b32 s91, v255, 23
	s_waitcnt vmcnt(1)
	v_add_f32_e32 v28, v32, v28
	s_waitcnt vmcnt(0)
	v_pk_add_f32 v[2:3], v[36:37], v[6:7]
	v_add_f32_e32 v26, v38, v26
	v_cmp_gt_f32_e32 vcc, v3, v2
	v_add_f32_e32 v27, v39, v27
	v_add_f32_e32 v19, v33, v29
	v_cndmask_b32_e32 v6, v2, v3, vcc
	v_cmp_gt_f32_e64 s[16:17], v26, v6
	v_cndmask_b32_e64 v7, 0, 1, vcc
	v_add_f32_e32 v18, v34, v30
	v_cndmask_b32_e64 v6, v6, v26, s[16:17]
	v_cmp_gt_f32_e32 vcc, v27, v6
	v_cndmask_b32_e64 v7, v7, 2, s[16:17]
	s_waitcnt lgkmcnt(8)
; __device__ void phase_ln2_route(const Params& p) {
;     ...
;       float gs = 0.f;
; #pragma unroll
;       for (int g = 0; g < 8; g++) gs += __expf(lg[q][g] - gm);
;       gval[q] = 1.f / gs;
;     ...
;     for (int q = 0; q < 2; q++) {
; #pragma unroll
;       for (int g = 0; g < 8; g++) le[q][g] += p.b_router[gi[q] * 8 + g];
;       int i1 = 0; float v1 = le[q][0];
; #pragma unroll
;       for (int g = 1; g < 8; g++) if (le[q][g] > v1) { v1 = le[q][g]; i1 = g; }
;       int i2 = 0; float v2 = -3.0e38f;
; #pragma unroll
;       for (int g = 0; g < 8; g++) if (g != i1 && le[q][g] > v2) { v2 = le[q][g]; i2 = g; }
;       float e2 = __expf(v2 - v1);
;       float g1 = gval[q] / (1.f + e2), g2 = gval[q] * e2 / (1.f + e2);
;       if (lane == 0) {
;         const int r = rb + q;
;         int ea = gi[q] * 8 + i1, eb = gi[q] * 8 + i2;
;         int pa = atomicAdd(&p.cnt()[ea * 32], 1);
;         p.rowlist()[ea * SEQ + pa] = 2 * r;
;         p.gates()[2 * r] = g1;
;         int pb = atomicAdd(&p.cnt()[eb * 32], 1);
;         p.rowlist()[eb * SEQ + pb] = 2 * r + 1;
;         p.gates()[2 * r + 1] = g2;
;       }
;     }
	v_add_f32_e32 v17, v35, v31
	v_cndmask_b32_e32 v6, v6, v27, vcc
	v_cmp_gt_f32_e64 s[16:17], v28, v6
	v_cndmask_b32_e64 v7, v7, 3, vcc
	v_cmp_lt_f32_e64 s[0:1], s69, v2
	v_cndmask_b32_e64 v6, v6, v28, s[16:17]
	v_cmp_gt_f32_e32 vcc, v19, v6
	v_cndmask_b32_e64 v7, v7, 4, s[16:17]
	s_nop 0
	v_cndmask_b32_e32 v6, v6, v19, vcc
	v_cmp_gt_f32_e64 s[16:17], v18, v6
	v_cndmask_b32_e64 v7, v7, 5, vcc
	s_nop 0
	v_cndmask_b32_e64 v6, v6, v18, s[16:17]
	v_cndmask_b32_e64 v7, v7, 6, s[16:17]
	v_cmp_ngt_f32_e32 vcc, v17, v6
	s_and_b64 s[2:3], s[16:17], vcc
	s_nop 0
	v_cndmask_b32_e32 v7, 7, v7, vcc
	v_cmp_ne_u32_e64 s[26:27], 0, v7
	s_and_b64 s[0:1], s[26:27], s[0:1]
	v_cndmask_b32_e64 v2, v159, v2, s[0:1]
	v_cmp_ne_u32_e64 s[24:25], 1, v7
	v_cmp_gt_f32_e64 s[0:1], v3, v2
	s_and_b64 s[26:27], s[24:25], s[0:1]
	v_cndmask_b32_e64 v2, v2, v3, s[26:27]
	v_cmp_ne_u32_e64 s[20:21], 2, v7
	v_cmp_gt_f32_e64 s[0:1], v26, v2
	s_and_b64 s[20:21], s[20:21], s[0:1]
	v_cndmask_b32_e64 v2, v2, v26, s[20:21]
	v_cmp_ne_u32_e64 s[22:23], 3, v7
	v_cmp_gt_f32_e64 s[0:1], v27, v2
	s_and_b64 s[22:23], s[22:23], s[0:1]
	v_cndmask_b32_e64 v2, v2, v27, s[22:23]
	v_cmp_ne_u32_e64 s[18:19], 4, v7
	v_cmp_gt_f32_e64 s[0:1], v28, v2
	s_and_b64 s[24:25], s[18:19], s[0:1]
	v_cndmask_b32_e64 v2, v2, v28, s[24:25]
	v_cmp_ne_u32_e64 s[16:17], 5, v7
	v_cmp_gt_f32_e64 s[0:1], v19, v2
	s_and_b64 s[0:1], s[16:17], s[0:1]
	v_or_b32_e32 v7, s62, v7
	v_cndmask_b32_e64 v2, v2, v19, s[0:1]
	v_cmp_ngt_f32_e64 s[16:17], v18, v2
	s_or_b64 s[16:17], s[2:3], s[16:17]
	v_cndmask_b32_e32 v6, v17, v6, vcc
	v_cndmask_b32_e64 v2, v18, v2, s[16:17]
	v_exp_f32_e32 v18, v0
	v_sub_f32_e32 v0, v1, v14
	v_mul_f32_e32 v0, 0x3fb8aa3b, v0
	v_exp_f32_e32 v19, v0
	v_sub_f32_e32 v0, v13, v14
	v_mul_f32_e32 v13, 0x3fb8aa3b, v0
	v_lshlrev_b32_e32 v0, 5, v7
	v_ashrrev_i32_e32 v1, 31, v0
	v_lshl_add_u64 v[0:1], v[0:1], 2, s[34:35]
	global_atomic_add v1, v[0:1], v158, off sc0
	v_exp_f32_e32 v0, v13
	v_add_f32_e32 v13, 0, v18
	v_add_f32_e32 v13, v19, v13
	v_cmp_gt_f32_e64 s[18:19], v17, v2
	v_add_f32_e32 v0, v0, v13
	v_add_f32_e32 v0, v12, v0
	v_add_f32_e32 v0, v11, v0
	v_add_f32_e32 v0, v10, v0
	v_add_f32_e32 v0, v9, v0
	v_add_f32_e32 v0, v8, v0
	v_div_scale_f32 v8, s[2:3], v0, v0, 1.0
	v_rcp_f32_e32 v9, v8
	s_and_b64 s[18:19], vcc, s[18:19]
	v_cndmask_b32_e64 v2, v2, v17, s[18:19]
	v_sub_f32_e32 v2, v2, v6
	v_fma_f32 v10, -v8, v9, 1.0
	v_fmac_f32_e32 v9, v10, v9
	v_div_scale_f32 v10, s[14:15], 1.0, v0, 1.0
	v_mul_f32_e32 v11, v10, v9
	v_fma_f32 v12, -v8, v11, v10
	v_mul_f32_e32 v2, 0x3fb8aa3b, v2
	v_fmac_f32_e32 v11, v12, v9
	v_exp_f32_e32 v2, v2
	v_fma_f32 v8, -v8, v11, v10
	s_mov_b64 vcc, s[14:15]
	v_div_fmas_f32 v6, v8, v9, v11
	v_div_fixup_f32 v0, v6, v0, 1.0
	v_mul_f32_e32 v6, v0, v2
	v_add_f32_e32 v8, 1.0, v2
	v_div_scale_f32 v2, s[2:3], v8, v8, v6
	v_rcp_f32_e32 v9, v2
	v_cndmask_b32_e64 v3, 0, 1, s[26:27]
	v_cndmask_b32_e64 v3, v3, 2, s[20:21]
	v_cndmask_b32_e64 v3, v3, 3, s[22:23]
	v_fma_f32 v10, -v2, v9, 1.0
	v_fmac_f32_e32 v9, v10, v9
	v_div_scale_f32 v10, vcc, v6, v8, v6
	v_mul_f32_e32 v11, v10, v9
	v_cndmask_b32_e64 v3, v3, 4, s[24:25]
	v_fma_f32 v12, -v2, v11, v10
	v_cndmask_b32_e64 v3, v3, 5, s[0:1]
	v_fmac_f32_e32 v11, v12, v9
	v_div_scale_f32 v12, s[0:1], v8, v8, v0
	v_rcp_f32_e32 v13, v12
	v_fma_f32 v2, -v2, v11, v10
	v_div_fmas_f32 v9, v2, v9, v11
	v_cndmask_b32_e64 v3, 6, v3, s[16:17]
	v_fma_f32 v2, -v12, v13, 1.0
	v_fmac_f32_e32 v13, v2, v13
	v_div_scale_f32 v2, vcc, v0, v8, v0
	v_mul_f32_e32 v10, v2, v13
	v_fma_f32 v11, -v12, v10, v2
	v_fmac_f32_e32 v10, v11, v13
	v_fma_f32 v2, -v12, v10, v2
	v_div_fmas_f32 v2, v2, v13, v10
	v_cndmask_b32_e64 v3, v3, 7, s[18:19]
	v_div_fixup_f32 v10, v2, v8, v0
	v_add_u32_e32 v11, s62, v3
	v_add_u32_e32 v0, -1, v86
	s_lshl_b32 s26, s58, 3
	s_ashr_i32 s27, s26, 31
	s_lshl_b64 s[0:1], s[26:27], 2
	s_add_u32 s0, s82, s0
	s_addc_u32 s1, s83, s1
	s_waitcnt vmcnt(0)
	v_lshl_add_u32 v2, v7, 13, v1
	v_ashrrev_i32_e32 v3, 31, v2
	v_lshl_add_u64 v[2:3], v[2:3], 2, s[36:37]
	v_ashrrev_i32_e32 v1, 31, v0
	global_store_dword v[2:3], v0, off
	v_lshl_add_u64 v[0:1], v[0:1], 2, s[38:39]
	global_store_dword v[0:1], v10, off
	v_lshlrev_b32_e32 v0, 5, v11
	v_ashrrev_i32_e32 v1, 31, v0
	v_lshl_add_u64 v[0:1], v[0:1], 2, s[34:35]
	global_atomic_add v2, v[0:1], v158, off sc0
	v_lshl_add_u64 v[0:1], v[86:87], 2, s[38:39]
	v_div_fixup_f32 v3, v9, v8, v6
	global_store_dword v[0:1], v3, off
	v_add_u32_e32 v10, 1, v86
	s_waitcnt vmcnt(1)
; __device__ void phase_ln2_route(const Params& p) {
;     ...
;     for (int q = 0; q < 2; q++) {
; #pragma unroll
;       for (int g = 0; g < 8; g++) le[q][g] += p.b_router[gi[q] * 8 + g];
;       int i1 = 0; float v1 = le[q][0];
; #pragma unroll
;       for (int g = 1; g < 8; g++) if (le[q][g] > v1) { v1 = le[q][g]; i1 = g; }
;       int i2 = 0; float v2 = -3.0e38f;
; #pragma unroll
;       for (int g = 0; g < 8; g++) if (g != i1 && le[q][g] > v2) { v2 = le[q][g]; i2 = g; }
;       float e2 = __expf(v2 - v1);
;       float g1 = gval[q] / (1.f + e2), g2 = gval[q] * e2 / (1.f + e2);
;       if (lane == 0) {
;         const int r = rb + q;
;         int ea = gi[q] * 8 + i1, eb = gi[q] * 8 + i2;
;         int pa = atomicAdd(&p.cnt()[ea * 32], 1);
;         p.rowlist()[ea * SEQ + pa] = 2 * r;
;         p.gates()[2 * r] = g1;
;         int pb = atomicAdd(&p.cnt()[eb * 32], 1);
;         p.rowlist()[eb * SEQ + pb] = 2 * r + 1;
;         p.gates()[2 * r + 1] = g2;
;       }
;     }
	v_lshl_add_u32 v0, v11, 13, v2
	v_ashrrev_i32_e32 v1, 31, v0
	v_lshl_add_u64 v[0:1], v[0:1], 2, s[36:37]
	global_store_dword v[0:1], v86, off
	global_load_dwordx4 v[0:3], v45, s[0:1] offset:16
	s_nop 0
	global_load_dwordx4 v[6:9], v45, s[0:1]
	v_ashrrev_i32_e32 v11, 31, v10
	s_waitcnt vmcnt(1) lgkmcnt(2)
	v_add_f32_e32 v14, v1, v23
	v_add_f32_e32 v17, v0, v22
	s_waitcnt vmcnt(0)
	v_pk_add_f32 v[0:1], v[6:7], v[4:5]
	s_waitcnt lgkmcnt(1)
	v_add_f32_e32 v13, v2, v24
	v_cmp_gt_f32_e32 vcc, v1, v0
	v_add_f32_e32 v8, v8, v20
	v_add_f32_e32 v9, v9, v21
	v_cndmask_b32_e32 v2, v0, v1, vcc
	v_cmp_gt_f32_e64 s[0:1], v8, v2
	s_waitcnt lgkmcnt(0)
	v_add_f32_e32 v12, v3, v25
	v_cndmask_b32_e64 v3, 0, 1, vcc
	v_cndmask_b32_e64 v2, v2, v8, s[0:1]
	v_cmp_gt_f32_e32 vcc, v9, v2
	v_cndmask_b32_e64 v3, v3, 2, s[0:1]
	v_cmp_lt_f32_e64 s[14:15], s69, v0
	v_cndmask_b32_e32 v2, v2, v9, vcc
	v_cmp_gt_f32_e64 s[0:1], v17, v2
	v_cndmask_b32_e64 v3, v3, 3, vcc
	s_nop 0
	v_cndmask_b32_e64 v2, v2, v17, s[0:1]
	v_cmp_gt_f32_e32 vcc, v14, v2
	v_cndmask_b32_e64 v3, v3, 4, s[0:1]
	s_nop 0
	v_cndmask_b32_e32 v2, v2, v14, vcc
	v_cmp_gt_f32_e64 s[0:1], v13, v2
	s_nop 1
	v_cndmask_b32_e64 v4, v2, v13, s[0:1]
	v_cndmask_b32_e64 v2, v3, 5, vcc
	v_cndmask_b32_e64 v2, v2, 6, s[0:1]
	v_cmp_ngt_f32_e32 vcc, v12, v4
	s_and_b64 s[2:3], s[0:1], vcc
	s_nop 0
	v_cndmask_b32_e32 v5, 7, v2, vcc
	v_or_b32_e32 v6, s26, v5
	v_lshlrev_b32_e32 v2, 5, v6
	v_ashrrev_i32_e32 v3, 31, v2
	v_lshl_add_u64 v[2:3], v[2:3], 2, s[34:35]
	global_atomic_add v7, v[2:3], v158, off sc0
	v_cmp_ne_u32_e64 s[24:25], 0, v5
	s_and_b64 s[14:15], s[24:25], s[14:15]
	v_cndmask_b32_e64 v0, v159, v0, s[14:15]
	v_cmp_ne_u32_e64 s[22:23], 1, v5
	v_cmp_gt_f32_e64 s[14:15], v1, v0
	s_and_b64 s[14:15], s[22:23], s[14:15]
	v_cmp_ne_u32_e64 s[20:21], 2, v5
	v_cndmask_b32_e64 v0, v0, v1, s[14:15]
	v_cmp_gt_f32_e64 s[22:23], v8, v0
	v_cndmask_b32_e64 v1, 0, 1, s[14:15]
	s_and_b64 s[14:15], s[20:21], s[22:23]
	v_cndmask_b32_e64 v0, v0, v8, s[14:15]
	v_cmp_ne_u32_e64 s[18:19], 3, v5
	v_cmp_gt_f32_e64 s[20:21], v9, v0
	v_cndmask_b32_e64 v1, v1, 2, s[14:15]
	s_and_b64 s[14:15], s[18:19], s[20:21]
	v_cndmask_b32_e64 v0, v0, v9, s[14:15]
	v_cmp_ne_u32_e64 s[16:17], 4, v5
	v_cmp_gt_f32_e64 s[18:19], v17, v0
	v_cndmask_b32_e64 v1, v1, 3, s[14:15]
	s_and_b64 s[14:15], s[16:17], s[18:19]
	v_cndmask_b32_e64 v0, v0, v17, s[14:15]
	v_cmp_ne_u32_e64 s[0:1], 5, v5
	v_cmp_gt_f32_e64 s[16:17], v14, v0
	s_and_b64 s[0:1], s[0:1], s[16:17]
	v_cndmask_b32_e64 v0, v0, v14, s[0:1]
	v_cndmask_b32_e64 v1, v1, 4, s[14:15]
	v_cmp_ngt_f32_e64 s[14:15], v13, v0
	v_cndmask_b32_e64 v1, v1, 5, s[0:1]
	s_or_b64 s[0:1], s[2:3], s[14:15]
	v_cndmask_b32_e64 v0, v13, v0, s[0:1]
	v_cmp_gt_f32_e64 s[14:15], v12, v0
	v_cndmask_b32_e32 v4, v12, v4, vcc
	s_and_b64 vcc, vcc, s[14:15]
	v_cndmask_b32_e32 v0, v0, v12, vcc
	v_sub_f32_e32 v0, v0, v4
	v_mul_f32_e32 v0, 0x3fb8aa3b, v0
	v_exp_f32_e32 v5, v0
	v_lshl_add_u64 v[2:3], v[10:11], 2, s[38:39]
	v_div_fixup_f32 v11, v16, v15, 1.0
	v_cndmask_b32_e64 v1, 6, v1, s[0:1]
	v_mul_f32_e32 v8, v11, v5
	v_add_f32_e32 v5, 1.0, v5
	v_div_scale_f32 v9, s[0:1], v5, v5, v8
	v_div_scale_f32 v13, s[0:1], v5, v5, v11
	v_rcp_f32_e32 v14, v9
	v_rcp_f32_e32 v15, v13
	v_cndmask_b32_e64 v1, v1, 7, vcc
	v_div_scale_f32 v12, vcc, v8, v5, v8
	v_fma_f32 v17, -v9, v14, 1.0
	v_fma_f32 v18, -v13, v15, 1.0
	v_fmac_f32_e32 v14, v17, v14
	v_div_scale_f32 v16, s[0:1], v11, v5, v11
	v_fmac_f32_e32 v15, v18, v15
	v_mul_f32_e32 v17, v12, v14
	v_mul_f32_e32 v18, v16, v15
	v_fma_f32 v19, -v9, v17, v12
	v_fma_f32 v20, -v13, v18, v16
	v_fmac_f32_e32 v17, v19, v14
	v_fmac_f32_e32 v18, v20, v15
	v_fma_f32 v9, -v9, v17, v12
	v_fma_f32 v12, -v13, v18, v16
	v_div_fmas_f32 v9, v9, v14, v17
	s_mov_b64 vcc, s[0:1]
	v_div_fmas_f32 v12, v12, v15, v18
	v_div_fixup_f32 v11, v12, v5, v11
	v_add_u32_e32 v4, s26, v1
	global_store_dword v[2:3], v11, off
	v_lshlrev_b32_e32 v0, 5, v4
	v_ashrrev_i32_e32 v1, 31, v0
	v_lshl_add_u64 v[0:1], v[0:1], 2, s[34:35]
	s_waitcnt vmcnt(1)
	v_lshl_add_u32 v2, v6, 13, v7
	v_ashrrev_i32_e32 v3, 31, v2
	v_lshl_add_u64 v[2:3], v[2:3], 2, s[36:37]
	global_store_dword v[2:3], v10, off
	global_atomic_add v6, v[0:1], v158, off sc0
	v_add_u32_e32 v0, 2, v86
	v_ashrrev_i32_e32 v1, 31, v0
	v_lshl_add_u64 v[2:3], v[0:1], 2, s[38:39]
	v_div_fixup_f32 v1, v9, v5, v8
	s_waitcnt vmcnt(0)
	v_lshl_add_u32 v4, v4, 13, v6
	v_ashrrev_i32_e32 v5, 31, v4
	v_lshl_add_u64 v[4:5], v[4:5], 2, s[36:37]
	global_store_dword v[4:5], v0, off
	global_store_dword v[2:3], v1, off
	s_branch .LBB0_817

; __device__ __forceinline__ float bflo(uint32_t w) { return __uint_as_float(w << 16); }
; __device__ __forceinline__ float bfhi(uint32_t w) { return __uint_as_float(w & 0xffff0000u); }
; template <class G, class T> __device__ __forceinline__ G opaque_g(T* q) { asm volatile("" : "+v"(q)); return (G)q; }
; template <int MODE>
; __device__ void phase_ln(const Params& p, u16* smem) {
;     ...
;   for (int rb = (blockIdx.x * 4 + wid) * 2; rb < SEQ; rb += gridDim.x * 8) {
;     float v[2][32];
; #pragma unroll
;     for (int q = 0; q < 2; q++) {
;       const int r = rb + q;
;       if (MODE == 0) {
;         g_cv4 pr = opaque_g<g_cv4>(p.pre() + (long)r * DM + lane * 4);
; #pragma unroll
;         for (int i = 0; i < 8; i++) {
;           f32x4 a = pr[i * 64];
;           v[q][i * 4 + 0] = a[0]; v[q][i * 4 + 1] = a[1]; v[q][i * 4 + 2] = a[2]; v[q][i * 4 + 3] = a[3];
;         }
;       } else {
;         g_cu2 ph = opaque_g<g_cu2>(p.hb() + (long)r * DM + lane * 4);
;         g_cu2 py0 = opaque_g<g_cu2>(p.yslot() + (long)(2 * r) * DM + lane * 4);
;         g_cu2 py1 = opaque_g<g_cu2>(p.yslot() + (long)(2 * r + 1) * DM + lane * 4);
; #pragma unroll
;         for (int i = 0; i < 8; i++) {
;           u32x2 hw = ph[i * 64], y0 = py0[i * 64], y1 = py1[i * 64];
;           v[q][i * 4 + 0] = DN_ALPHA * bflo(hw[0]) + (bflo(y0[0]) + bflo(y1[0]));
;           v[q][i * 4 + 1] = DN_ALPHA * bfhi(hw[0]) + (bfhi(y0[0]) + bfhi(y1[0]));
;           v[q][i * 4 + 2] = DN_ALPHA * bflo(hw[1]) + (bflo(y0[1]) + bflo(y1[1]));
;           v[q][i * 4 + 3] = DN_ALPHA * bfhi(hw[1]) + (bfhi(y0[1]) + bfhi(y1[1]));
;         }
;       }
.LBB0_1054:
	v_cmp_lt_i32_e32 vcc, v102, v101
	v_ashrrev_i32_e32 v133, 31, v132
	v_add_u32_e32 v0, -3, v18
	v_cndmask_b32_e32 v26, v100, v102, vcc
	v_cmp_lt_i32_e32 vcc, v103, v101
	v_add_u32_e32 v2, -2, v18
	v_lshlrev_b64 v[6:7], 12, v[132:133]
	v_cndmask_b32_e32 v27, v100, v103, vcc
	v_ashrrev_i32_e32 v1, 31, v0
	v_ashrrev_i32_e32 v3, 31, v2
	v_lshlrev_b32_e32 v113, 2, v26
	v_lshlrev_b32_e32 v112, 2, v27
	v_lshlrev_b64 v[26:27], 13, v[132:133]
	v_lshl_add_u64 v[6:7], v[12:13], 0, v[6:7]
	v_lshlrev_b64 v[0:1], 12, v[0:1]
	v_lshlrev_b64 v[2:3], 12, v[2:3]
	v_lshl_add_u64 v[58:59], v[16:17], 0, v[26:27]
	v_mov_b64_e32 v[26:27], v[6:7]
	v_lshl_add_u64 v[0:1], v[14:15], 0, v[0:1]
	v_lshl_add_u64 v[2:3], v[14:15], 0, v[2:3]
	global_load_dwordx2 v[84:85], v[26:27], off offset:3584 nt
	global_load_dwordx2 v[86:87], v[0:1], off offset:3584 nt
	global_load_dwordx2 v[88:89], v[2:3], off offset:3584 nt
	global_load_dwordx2 v[90:91], v[26:27], off nt
	global_load_dwordx2 v[92:93], v[0:1], off nt
	global_load_dwordx2 v[94:95], v[2:3], off nt
	global_load_dwordx2 v[96:97], v[26:27], off offset:512 nt
	global_load_dwordx2 v[98:99], v[0:1], off offset:512 nt
	global_load_dwordx2 v[114:115], v[2:3], off offset:512 nt
	global_load_dwordx2 v[116:117], v[26:27], off offset:2048 nt
	global_load_dwordx2 v[118:119], v[26:27], off offset:2560 nt
	global_load_dwordx2 v[72:73], v[26:27], off offset:3072 nt
	global_load_dwordx2 v[120:121], v[26:27], off offset:1024 nt
	global_load_dwordx2 v[122:123], v[0:1], off offset:1024 nt
	global_load_dwordx2 v[124:125], v[0:1], off offset:2048 nt
	global_load_dwordx2 v[126:127], v[0:1], off offset:2560 nt
	global_load_dwordx2 v[74:75], v[0:1], off offset:3072 nt
	global_load_dwordx2 v[128:129], v[2:3], off offset:1024 nt
	global_load_dwordx2 v[130:131], v[2:3], off offset:2048 nt
	global_load_dwordx2 v[134:135], v[2:3], off offset:2560 nt
	global_load_dwordx2 v[82:83], v[2:3], off offset:3072 nt
	global_load_dwordx2 v[136:137], v[26:27], off offset:1536 nt
	global_load_dwordx2 v[138:139], v[0:1], off offset:1536 nt
	global_load_dwordx2 v[140:141], v[2:3], off offset:1536 nt
	v_cmp_lt_i32_e32 vcc, v104, v101
	v_ashrrev_i32_e32 v19, 31, v18
	v_add_u32_e32 v44, 1, v132
	v_cndmask_b32_e32 v28, v100, v104, vcc
	v_lshlrev_b32_e32 v111, 2, v28
	v_cmp_lt_i32_e32 vcc, v105, v101
	v_lshlrev_b64 v[24:25], 12, v[18:19]
	v_add_u32_e32 v4, -1, v18
	v_cndmask_b32_e32 v29, v100, v105, vcc
	v_lshlrev_b32_e32 v110, 2, v29
	v_cmp_lt_i32_e32 vcc, v106, v101
	v_ashrrev_i32_e32 v45, 31, v44
	v_ashrrev_i32_e32 v5, 31, v4
	v_cndmask_b32_e32 v30, v100, v106, vcc
	v_lshlrev_b32_e32 v109, 2, v30
	v_cmp_lt_i32_e32 vcc, v107, v101
	v_lshlrev_b64 v[28:29], 12, v[44:45]
	v_lshlrev_b64 v[4:5], 12, v[4:5]
	v_cndmask_b32_e32 v31, v100, v107, vcc
	v_lshlrev_b32_e32 v19, 2, v31
	v_lshl_add_u64 v[80:81], v[14:15], 0, v[24:25]
	v_lshl_add_u64 v[24:25], v[12:13], 0, v[28:29]
	v_lshl_add_u64 v[4:5], v[14:15], 0, v[4:5]
	v_mov_b64_e32 v[28:29], v[24:25]
	v_mov_b64_e32 v[20:21], v[8:9]
	v_mov_b64_e32 v[22:23], v[10:11]
	global_load_dwordx2 v[66:67], v[28:29], off nt
	global_load_dwordx2 v[60:61], v[28:29], off offset:512 nt
	global_load_dwordx2 v[52:53], v[28:29], off offset:1024 nt
	global_load_dwordx2 v[46:47], v[28:29], off offset:1536 nt
	global_load_dwordx2 v[68:69], v[4:5], off nt
	global_load_dwordx2 v[62:63], v[4:5], off offset:512 nt
	global_load_dwordx2 v[54:55], v[4:5], off offset:1024 nt
	global_load_dwordx2 v[48:49], v[4:5], off offset:1536 nt
	global_load_dwordx2 v[70:71], v[80:81], off nt
	global_load_dwordx2 v[64:65], v[80:81], off offset:512 nt
	global_load_dwordx2 v[56:57], v[80:81], off offset:1024 nt
	global_load_dwordx2 v[50:51], v[80:81], off offset:1536 nt
	global_load_dwordx2 v[38:39], v[28:29], off offset:2048 nt
	global_load_dwordx2 v[32:33], v[28:29], off offset:2560 nt
	global_load_dwordx2 v[26:27], v[28:29], off offset:3072 nt
	global_load_dwordx2 v[76:77], v[28:29], off offset:3584 nt
	global_load_dwordx2 v[40:41], v[4:5], off offset:2048 nt
	global_load_dwordx2 v[34:35], v[4:5], off offset:2560 nt
	s_nop 0
	global_load_dwordx2 v[28:29], v[4:5], off offset:3072 nt
	global_load_dwordx2 v[78:79], v[4:5], off offset:3584 nt
	global_load_dwordx2 v[42:43], v[80:81], off offset:2048 nt
	global_load_dwordx2 v[36:37], v[80:81], off offset:2560 nt
	global_load_dwordx2 v[30:31], v[80:81], off offset:3072 nt
	s_nop 0
	global_load_dwordx2 v[80:81], v[80:81], off offset:3584 nt
	global_load_dwordx4 v[0:3], v[20:21], off
	global_load_dwordx4 v[4:7], v[22:23], off
	v_add_u32_e32 v132, s3, v132
	v_add_u32_e32 v18, s4, v18
	s_waitcnt vmcnt(49)
	v_and_b32_e32 v142, 0xffff0000, v84
	s_waitcnt vmcnt(48)
	v_and_b32_e32 v144, 0xffff0000, v86
	v_lshlrev_b32_e32 v145, 16, v86
	s_waitcnt vmcnt(47)
	v_and_b32_e32 v146, 0xffff0000, v88
	v_lshlrev_b32_e32 v147, 16, v88
	v_and_b32_e32 v86, 0xffff0000, v87
	v_lshlrev_b32_e32 v87, 16, v87
	v_and_b32_e32 v88, 0xffff0000, v89
	v_lshlrev_b32_e32 v89, 16, v89
	s_waitcnt vmcnt(45)
	v_lshlrev_b32_e32 v150, 16, v92
	v_and_b32_e32 v151, 0xffff0000, v92
	s_waitcnt vmcnt(44)
	v_lshlrev_b32_e32 v152, 16, v94
	v_and_b32_e32 v153, 0xffff0000, v94
	v_lshlrev_b32_e32 v143, 16, v84
	v_and_b32_e32 v84, 0xffff0000, v85
	v_lshlrev_b32_e32 v85, 16, v85
	v_lshlrev_b32_e32 v148, 16, v90
	v_and_b32_e32 v149, 0xffff0000, v90
	s_waitcnt vmcnt(33)
	v_lshlrev_b32_e32 v186, 16, v74
	v_and_b32_e32 v187, 0xffff0000, v74
	s_waitcnt vmcnt(29)
; __device__ __forceinline__ float bflo(uint32_t w) { return __uint_as_float(w << 16); }
; __device__ __forceinline__ float bfhi(uint32_t w) { return __uint_as_float(w & 0xffff0000u); }
; __device__ __forceinline__ void ln_stats(const float (&v)[32], float& mean, float& rstd) {
;   float s = 0.f;
; #pragma unroll
;   for (int i = 0; i < 32; i++) s += v[i];
;   mean = wave_sum(s) * (1.f / DM);
; template <int MODE>
; __device__ void phase_ln(const Params& p, u16* smem) {
;     ...
;         for (int i = 0; i < 8; i++) {
;           u32x2 hw = ph[i * 64], y0 = py0[i * 64], y1 = py1[i * 64];
;           v[q][i * 4 + 0] = DN_ALPHA * bflo(hw[0]) + (bflo(y0[0]) + bflo(y1[0]));
;           v[q][i * 4 + 1] = DN_ALPHA * bfhi(hw[0]) + (bfhi(y0[0]) + bfhi(y1[0]));
;           v[q][i * 4 + 2] = DN_ALPHA * bflo(hw[1]) + (bflo(y0[1]) + bflo(y1[1]));
;           v[q][i * 4 + 3] = DN_ALPHA * bfhi(hw[1]) + (bfhi(y0[1]) + bfhi(y1[1]));
;         }
	v_lshlrev_b32_e32 v188, 16, v82
	v_and_b32_e32 v189, 0xffff0000, v82
	v_lshlrev_b32_e32 v74, 16, v75
	v_and_b32_e32 v75, 0xffff0000, v75
	v_lshlrev_b32_e32 v82, 16, v83
	v_and_b32_e32 v83, 0xffff0000, v83
	v_pk_add_f32 v[144:145], v[144:145], v[146:147]
	v_pk_add_f32 v[86:87], v[86:87], v[88:89]
	v_pk_add_f32 v[88:89], v[150:151], v[152:153]
	v_lshlrev_b32_e32 v92, 16, v93
	v_and_b32_e32 v93, 0xffff0000, v93
	v_lshlrev_b32_e32 v94, 16, v95
	v_and_b32_e32 v95, 0xffff0000, v95
	v_lshlrev_b32_e32 v184, 16, v72
	v_and_b32_e32 v185, 0xffff0000, v72
	v_lshlrev_b32_e32 v72, 16, v73
	v_and_b32_e32 v73, 0xffff0000, v73
	v_pk_add_f32 v[74:75], v[74:75], v[82:83]
	v_pk_fma_f32 v[82:83], v[142:143], s[2:3], v[144:145] op_sel_hi:[1,0,1]
	v_pk_fma_f32 v[142:143], v[84:85], s[2:3], v[86:87] op_sel_hi:[1,0,1]
	v_pk_fma_f32 v[84:85], v[148:149], s[2:3], v[88:89] op_sel_hi:[1,0,1]
	v_lshlrev_b32_e32 v90, 16, v91
	v_and_b32_e32 v91, 0xffff0000, v91
	v_pk_add_f32 v[92:93], v[92:93], v[94:95]
	v_pk_fma_f32 v[72:73], v[72:73], s[2:3], v[74:75] op_sel_hi:[1,0,1]
	v_add_f32_e32 v74, 0, v84
	v_lshlrev_b32_e32 v156, 16, v98
	v_and_b32_e32 v157, 0xffff0000, v98
	v_lshlrev_b32_e32 v158, 16, v114
	v_and_b32_e32 v159, 0xffff0000, v114
	v_pk_fma_f32 v[86:87], v[90:91], s[2:3], v[92:93] op_sel_hi:[1,0,1]
	v_add_f32_e32 v74, v85, v74
	v_lshlrev_b32_e32 v154, 16, v96
	v_and_b32_e32 v155, 0xffff0000, v96
	v_pk_add_f32 v[94:95], v[156:157], v[158:159]
	v_add_f32_e32 v74, v86, v74
	v_lshlrev_b32_e32 v98, 16, v99
	v_and_b32_e32 v99, 0xffff0000, v99
	v_lshlrev_b32_e32 v114, 16, v115
	v_and_b32_e32 v115, 0xffff0000, v115
	v_pk_fma_f32 v[88:89], v[154:155], s[2:3], v[94:95] op_sel_hi:[1,0,1]
	v_add_f32_e32 v74, v87, v74
	v_lshlrev_b32_e32 v96, 16, v97
	v_and_b32_e32 v97, 0xffff0000, v97
	v_pk_add_f32 v[98:99], v[98:99], v[114:115]
	v_add_f32_e32 v74, v88, v74
	v_lshlrev_b32_e32 v162, 16, v122
	v_and_b32_e32 v163, 0xffff0000, v122
	v_lshlrev_b32_e32 v164, 16, v128
	v_and_b32_e32 v165, 0xffff0000, v128
	v_pk_fma_f32 v[90:91], v[96:97], s[2:3], v[98:99] op_sel_hi:[1,0,1]
	v_add_f32_e32 v74, v89, v74
	v_lshlrev_b32_e32 v160, 16, v120
	v_and_b32_e32 v161, 0xffff0000, v120
	v_pk_add_f32 v[114:115], v[162:163], v[164:165]
	v_add_f32_e32 v74, v90, v74
	v_lshlrev_b32_e32 v122, 16, v123
	v_and_b32_e32 v123, 0xffff0000, v123
	v_lshlrev_b32_e32 v128, 16, v129
	v_and_b32_e32 v129, 0xffff0000, v129
	v_pk_fma_f32 v[92:93], v[160:161], s[2:3], v[114:115] op_sel_hi:[1,0,1]
	v_add_f32_e32 v74, v91, v74
	v_lshlrev_b32_e32 v120, 16, v121
	v_and_b32_e32 v121, 0xffff0000, v121
	v_pk_add_f32 v[122:123], v[122:123], v[128:129]
	v_add_f32_e32 v74, v92, v74
	s_waitcnt vmcnt(27)
	v_lshlrev_b32_e32 v168, 16, v138
	v_and_b32_e32 v169, 0xffff0000, v138
	s_waitcnt vmcnt(26)
	v_lshlrev_b32_e32 v170, 16, v140
	v_and_b32_e32 v171, 0xffff0000, v140
	v_pk_fma_f32 v[94:95], v[120:121], s[2:3], v[122:123] op_sel_hi:[1,0,1]
	v_add_f32_e32 v74, v93, v74
	v_lshlrev_b32_e32 v166, 16, v136
	v_and_b32_e32 v167, 0xffff0000, v136
	v_pk_add_f32 v[128:129], v[168:169], v[170:171]
	v_add_f32_e32 v74, v94, v74
	v_lshlrev_b32_e32 v138, 16, v139
	v_and_b32_e32 v139, 0xffff0000, v139
	v_lshlrev_b32_e32 v140, 16, v141
	v_and_b32_e32 v141, 0xffff0000, v141
	v_pk_fma_f32 v[96:97], v[166:167], s[2:3], v[128:129] op_sel_hi:[1,0,1]
	v_add_f32_e32 v74, v95, v74
	v_lshlrev_b32_e32 v136, 16, v137
	v_and_b32_e32 v137, 0xffff0000, v137
	v_pk_add_f32 v[138:139], v[138:139], v[140:141]
	v_add_f32_e32 v74, v96, v74
	v_lshlrev_b32_e32 v174, 16, v124
	v_and_b32_e32 v175, 0xffff0000, v124
	v_lshlrev_b32_e32 v176, 16, v130
	v_and_b32_e32 v177, 0xffff0000, v130
	v_pk_fma_f32 v[98:99], v[136:137], s[2:3], v[138:139] op_sel_hi:[1,0,1]
	v_add_f32_e32 v74, v97, v74
	v_lshlrev_b32_e32 v172, 16, v116
	v_and_b32_e32 v173, 0xffff0000, v116
	v_pk_add_f32 v[140:141], v[174:175], v[176:177]
	v_add_f32_e32 v74, v98, v74
	v_lshlrev_b32_e32 v124, 16, v125
	v_and_b32_e32 v125, 0xffff0000, v125
	v_lshlrev_b32_e32 v130, 16, v131
	v_and_b32_e32 v131, 0xffff0000, v131
	v_pk_fma_f32 v[114:115], v[172:173], s[2:3], v[140:141] op_sel_hi:[1,0,1]
	v_add_f32_e32 v74, v99, v74
	v_lshlrev_b32_e32 v116, 16, v117
	v_and_b32_e32 v117, 0xffff0000, v117
	v_pk_add_f32 v[124:125], v[124:125], v[130:131]
	v_add_f32_e32 v74, v114, v74
	v_lshlrev_b32_e32 v180, 16, v126
	v_and_b32_e32 v181, 0xffff0000, v126
	v_lshlrev_b32_e32 v182, 16, v134
	v_and_b32_e32 v183, 0xffff0000, v134
	v_pk_fma_f32 v[116:117], v[116:117], s[2:3], v[124:125] op_sel_hi:[1,0,1]
	v_add_f32_e32 v74, v115, v74
	v_lshlrev_b32_e32 v178, 16, v118
	v_and_b32_e32 v179, 0xffff0000, v118
	v_pk_add_f32 v[130:131], v[180:181], v[182:183]
	v_add_f32_e32 v74, v116, v74
	v_lshlrev_b32_e32 v126, 16, v127
	v_and_b32_e32 v127, 0xffff0000, v127
	v_lshlrev_b32_e32 v134, 16, v135
	v_and_b32_e32 v135, 0xffff0000, v135
	v_pk_fma_f32 v[120:121], v[178:179], s[2:3], v[130:131] op_sel_hi:[1,0,1]
	v_add_f32_e32 v74, v117, v74
	v_lshlrev_b32_e32 v118, 16, v119
	v_and_b32_e32 v119, 0xffff0000, v119
	v_pk_add_f32 v[126:127], v[126:127], v[134:135]
	v_add_f32_e32 v74, v120, v74
	v_pk_fma_f32 v[118:119], v[118:119], s[2:3], v[126:127] op_sel_hi:[1,0,1]
	v_add_f32_e32 v74, v121, v74
	v_pk_add_f32 v[134:135], v[186:187], v[188:189]
	v_add_f32_e32 v74, v118, v74
	v_pk_fma_f32 v[122:123], v[184:185], s[2:3], v[134:135] op_sel_hi:[1,0,1]
	v_add_f32_e32 v74, v119, v74
	v_add_f32_e32 v74, v122, v74
	v_add_f32_e32 v74, v123, v74
	v_add_f32_e32 v74, v72, v74
	v_add_f32_e32 v74, v73, v74
	v_add_f32_e32 v74, v83, v74
	v_add_f32_e32 v74, v82, v74
	v_add_f32_e32 v74, v143, v74
	v_add_f32_e32 v74, v142, v74
	ds_bpermute_b32 v75, v113, v74
	s_waitcnt vmcnt(9)
; __device__ __forceinline__ float wave_sum(float v) {
; #pragma unroll
;   for (int o = 32; o; o >>= 1) v += __shfl_xor(v, o);
;   return v;
; __device__ __forceinline__ void ln_stats(const float (&v)[32], float& mean, float& rstd) {
;   float s = 0.f;
; #pragma unroll
;   for (int i = 0; i < 32; i++) s += v[i];
;   mean = wave_sum(s) * (1.f / DM);
;   float q = 0.f;
; #pragma unroll
;   for (int i = 0; i < 32; i++) { float d = v[i] - mean; q += d * d; }
;   rstd = rsqrtf(wave_sum(q) * (1.f / DM) + 1e-5f);
; }
	v_lshlrev_b32_e32 v158, 16, v41
	v_and_b32_e32 v159, 0xffff0000, v41
	s_waitcnt vmcnt(8)
	v_lshlrev_b32_e32 v162, 16, v34
	v_and_b32_e32 v163, 0xffff0000, v34
	s_waitcnt lgkmcnt(0)
	v_add_f32_e32 v74, v74, v75
	ds_bpermute_b32 v75, v112, v74
	v_lshlrev_b32_e32 v160, 16, v32
	v_and_b32_e32 v161, 0xffff0000, v32
	v_lshlrev_b32_e32 v34, 16, v35
	v_and_b32_e32 v35, 0xffff0000, v35
	s_waitcnt lgkmcnt(0)
	v_add_f32_e32 v74, v74, v75
	ds_bpermute_b32 v75, v111, v74
	v_lshlrev_b32_e32 v32, 16, v33
	v_and_b32_e32 v33, 0xffff0000, v33
	s_waitcnt lgkmcnt(0)
	v_add_f32_e32 v74, v74, v75
	ds_bpermute_b32 v75, v110, v74
	s_waitcnt lgkmcnt(0)
	v_add_f32_e32 v74, v74, v75
	ds_bpermute_b32 v75, v109, v74
	s_waitcnt lgkmcnt(0)
	v_add_f32_e32 v74, v74, v75
	ds_bpermute_b32 v75, v19, v74
	s_waitcnt lgkmcnt(0)
	v_add_f32_e32 v74, v74, v75
	v_mul_f32_e32 v74, 0x3a000000, v74
	v_pk_add_f32 v[124:125], v[84:85], v[74:75] op_sel_hi:[1,0] neg_lo:[0,1] neg_hi:[0,1]
	v_pk_add_f32 v[126:127], v[86:87], v[74:75] op_sel_hi:[1,0] neg_lo:[0,1] neg_hi:[0,1]
	v_pk_add_f32 v[86:87], v[72:73], v[74:75] op_sel_hi:[1,0] neg_lo:[0,1] neg_hi:[0,1]
	v_pk_add_f32 v[72:73], v[82:83], v[74:75] op_sel_hi:[1,0] neg_lo:[0,1] neg_hi:[0,1]
	v_pk_mul_f32 v[82:83], v[124:125], v[124:125]
	v_pk_add_f32 v[134:135], v[92:93], v[74:75] op_sel_hi:[1,0] neg_lo:[0,1] neg_hi:[0,1]
	v_pk_add_f32 v[92:93], v[114:115], v[74:75] op_sel_hi:[1,0] neg_lo:[0,1] neg_hi:[0,1]
	v_pk_mul_f32 v[114:115], v[126:127], v[126:127]
	v_add_f32_e32 v82, v82, v83
	v_pk_add_f32 v[128:129], v[88:89], v[74:75] op_sel_hi:[1,0] neg_lo:[0,1] neg_hi:[0,1]
	v_add_f32_e32 v82, v114, v82
	v_pk_add_f32 v[136:137], v[94:95], v[74:75] op_sel_hi:[1,0] neg_lo:[0,1] neg_hi:[0,1]
	v_pk_add_f32 v[94:95], v[116:117], v[74:75] op_sel_hi:[1,0] neg_lo:[0,1] neg_hi:[0,1]
	v_pk_mul_f32 v[116:117], v[128:129], v[128:129]
	v_add_f32_e32 v82, v115, v82
	v_pk_add_f32 v[130:131], v[90:91], v[74:75] op_sel_hi:[1,0] neg_lo:[0,1] neg_hi:[0,1]
	v_add_f32_e32 v82, v116, v82
	v_pk_add_f32 v[90:91], v[118:119], v[74:75] op_sel_hi:[1,0] neg_lo:[0,1] neg_hi:[0,1]
	v_pk_mul_f32 v[118:119], v[130:131], v[130:131]
	v_add_f32_e32 v82, v117, v82
	v_add_f32_e32 v82, v118, v82
	v_pk_add_f32 v[88:89], v[120:121], v[74:75] op_sel_hi:[1,0] neg_lo:[0,1] neg_hi:[0,1]
	v_pk_mul_f32 v[120:121], v[134:135], v[134:135]
	v_add_f32_e32 v82, v119, v82
	v_add_f32_e32 v82, v120, v82
	v_pk_add_f32 v[84:85], v[122:123], v[74:75] op_sel_hi:[1,0] neg_lo:[0,1] neg_hi:[0,1]
	v_pk_mul_f32 v[122:123], v[136:137], v[136:137]
	v_add_f32_e32 v82, v121, v82
	v_pk_add_f32 v[96:97], v[96:97], v[74:75] op_sel_hi:[1,0] neg_lo:[0,1] neg_hi:[0,1]
	v_add_f32_e32 v82, v122, v82
	v_pk_mul_f32 v[138:139], v[96:97], v[96:97]
	v_add_f32_e32 v82, v123, v82
	v_pk_add_f32 v[98:99], v[98:99], v[74:75] op_sel_hi:[1,0] neg_lo:[0,1] neg_hi:[0,1]
	v_add_f32_e32 v82, v138, v82
	v_pk_mul_f32 v[140:141], v[98:99], v[98:99]
	v_add_f32_e32 v82, v139, v82
	v_add_f32_e32 v82, v140, v82
	v_pk_add_f32 v[74:75], v[142:143], v[74:75] op_sel_hi:[1,0] neg_lo:[0,1] neg_hi:[0,1]
	v_pk_mul_f32 v[142:143], v[92:93], v[92:93]
	v_add_f32_e32 v82, v141, v82
	v_add_f32_e32 v82, v142, v82
	v_pk_mul_f32 v[144:145], v[94:95], v[94:95]
	v_add_f32_e32 v82, v143, v82
	v_add_f32_e32 v82, v144, v82
	v_pk_mul_f32 v[146:147], v[88:89], v[88:89]
	v_add_f32_e32 v82, v145, v82
	v_add_f32_e32 v82, v146, v82
	v_pk_mul_f32 v[148:149], v[90:91], v[90:91]
	v_add_f32_e32 v82, v147, v82
	v_add_f32_e32 v82, v148, v82
	v_pk_mul_f32 v[150:151], v[84:85], v[84:85]
	v_add_f32_e32 v82, v149, v82
	v_add_f32_e32 v82, v150, v82
	v_pk_mul_f32 v[152:153], v[86:87], v[86:87]
	v_add_f32_e32 v82, v151, v82
	v_add_f32_e32 v82, v152, v82
	v_pk_mul_f32 v[154:155], v[72:73], v[72:73]
	v_add_f32_e32 v82, v153, v82
	v_add_f32_e32 v82, v155, v82
	v_pk_mul_f32 v[156:157], v[74:75], v[74:75]
	v_add_f32_e32 v82, v154, v82
	v_add_f32_e32 v82, v157, v82
	v_add_f32_e32 v82, v156, v82
	ds_bpermute_b32 v83, v113, v82
	v_lshlrev_b32_e32 v138, 16, v67
	v_and_b32_e32 v139, 0xffff0000, v67
	v_lshlrev_b32_e32 v140, 16, v69
	v_and_b32_e32 v141, 0xffff0000, v69
	s_waitcnt lgkmcnt(0)
	v_add_f32_e32 v82, v82, v83
	ds_bpermute_b32 v83, v112, v82
	s_waitcnt vmcnt(6)
	v_and_b32_e32 v122, 0xffff0000, v78
	v_lshlrev_b32_e32 v123, 16, v78
	v_lshlrev_b32_e32 v150, 16, v38
	v_and_b32_e32 v151, 0xffff0000, v38
	s_waitcnt lgkmcnt(0)
	v_add_f32_e32 v82, v82, v83
	ds_bpermute_b32 v83, v111, v82
	v_lshlrev_b32_e32 v152, 16, v40
	v_and_b32_e32 v153, 0xffff0000, v40
	v_lshlrev_b32_e32 v156, 16, v39
	v_and_b32_e32 v157, 0xffff0000, v39
	s_waitcnt lgkmcnt(0)
	v_add_f32_e32 v82, v82, v83
	ds_bpermute_b32 v83, v110, v82
	v_lshlrev_b32_e32 v146, 16, v47
	v_and_b32_e32 v147, 0xffff0000, v47
	v_lshlrev_b32_e32 v148, 16, v49
	v_and_b32_e32 v149, 0xffff0000, v49
	s_waitcnt lgkmcnt(0)
	v_add_f32_e32 v82, v82, v83
	ds_bpermute_b32 v83, v109, v82
	v_lshlrev_b32_e32 v142, 16, v60
	v_and_b32_e32 v143, 0xffff0000, v60
	v_lshlrev_b32_e32 v60, 16, v61
	v_and_b32_e32 v61, 0xffff0000, v61
	s_waitcnt lgkmcnt(0)
	v_add_f32_e32 v82, v82, v83
	ds_bpermute_b32 v83, v19, v82
	v_lshlrev_b32_e32 v144, 16, v50
	v_and_b32_e32 v145, 0xffff0000, v50
	v_lshlrev_b32_e32 v50, 16, v51
	v_and_b32_e32 v51, 0xffff0000, v51
	s_waitcnt lgkmcnt(0)
	v_add_f32_e32 v82, v82, v83
	v_fmamk_f32 v82, v82, 0x3a000000, v108
	v_mul_f32_e32 v83, 0x4b800000, v82
	v_cmp_gt_f32_e32 vcc, s5, v82
	v_pk_add_f32 v[50:51], v[148:149], v[50:51]
	s_waitcnt vmcnt(5)
; template <class G, class T> __device__ __forceinline__ G opaque_g(T* q) { asm volatile("" : "+v"(q)); return (G)q; }
; __device__ __forceinline__ void ln_stats(const float (&v)[32], float& mean, float& rstd) {
;     ...
;   rstd = rsqrtf(wave_sum(q) * (1.f / DM) + 1e-5f);
; template <int MODE>
; __device__ void phase_ln(const Params& p, u16* smem) {
;     ...
;     g_cv4 pg = opaque_g<g_cv4>(gam + lane * 4);
;     g_cv4 pb = opaque_g<g_cv4>(bet + lane * 4);
; #pragma unroll
;     for (int q = 0; q < 2; q++) {
;       g_v4 po = opaque_g<g_v4>(p.out + (long)(rb + q) * DM + lane * 4);
;       g_u2 ph = opaque_g<g_u2>(p.hb() + (long)(rb + q) * DM + lane * 4);
; #pragma unroll
;       for (int i = 0; i < 8; i++) {
;         f32x4 g = pg[i * 64], b = pb[i * 64];
;         f32x4 o4;
; #pragma unroll
;         for (int e = 0; e < 4; e++) o4[e] = (v[q][i * 4 + e] - mean[q]) * rstd[q] * g[e] + b[e];
;         if (MODE == 2) po[i * 64] = o4;
;         else { u32x2 w = {pack2(o4[0], o4[1]), pack2(o4[2], o4[3])}; ph[i * 64] = w; }
;       }
	v_lshlrev_b32_e32 v154, 16, v42
	v_cndmask_b32_e32 v82, v82, v83, vcc
	v_rsq_f32_e32 v82, v82
	v_and_b32_e32 v155, 0xffff0000, v42
	v_pk_fma_f32 v[50:51], v[146:147], s[2:3], v[50:51] op_sel_hi:[1,0,1]
	v_lshlrev_b32_e32 v42, 16, v43
	v_mul_f32_e32 v83, 0x45800000, v82
	v_cndmask_b32_e32 v82, v82, v83, vcc
	v_pk_mul_f32 v[114:115], v[124:125], v[82:83] op_sel_hi:[1,0]
	v_pk_mul_f32 v[116:117], v[126:127], v[82:83] op_sel_hi:[1,0]
	s_waitcnt vmcnt(0)
	v_pk_fma_f32 v[0:1], v[0:1], v[114:115], v[4:5]
	v_pk_fma_f32 v[2:3], v[2:3], v[116:117], v[6:7]
	global_store_dwordx4 v[58:59], v[0:3], off
	global_load_dwordx4 v[0:3], v[20:21], off offset:1024
	s_nop 0
	global_load_dwordx4 v[4:7], v[22:23], off offset:1024
	v_pk_mul_f32 v[114:115], v[130:131], v[82:83] op_sel_hi:[1,0]
	v_pk_mul_f32 v[116:117], v[128:129], v[82:83] op_sel_hi:[1,0]
	v_lshlrev_b32_e32 v130, 16, v66
	v_and_b32_e32 v131, 0xffff0000, v66
	v_pk_mul_f32 v[66:67], v[96:97], v[82:83] op_sel_hi:[1,0]
	v_and_b32_e32 v124, 0xffff0000, v80
	v_lshlrev_b32_e32 v125, 16, v80
	v_and_b32_e32 v126, 0xffff0000, v79
	v_lshlrev_b32_e32 v127, 16, v79
	v_and_b32_e32 v128, 0xffff0000, v81
	v_lshlrev_b32_e32 v129, 16, v81
	v_pk_mul_f32 v[40:41], v[94:95], v[82:83] op_sel_hi:[1,0]
	v_pk_mul_f32 v[38:39], v[92:93], v[82:83] op_sel_hi:[1,0]
	v_lshlrev_b32_e32 v96, 16, v64
	v_and_b32_e32 v97, 0xffff0000, v64
	v_lshlrev_b32_e32 v64, 16, v65
	v_and_b32_e32 v65, 0xffff0000, v65
	v_pk_add_f32 v[92:93], v[122:123], v[124:125]
	v_and_b32_e32 v43, 0xffff0000, v43
	v_pk_add_f32 v[42:43], v[158:159], v[42:43]
	v_pk_add_f32 v[94:95], v[126:127], v[128:129]
	v_pk_fma_f32 v[42:43], v[156:157], s[2:3], v[42:43] op_sel_hi:[1,0,1]
	s_waitcnt vmcnt(0)
	v_pk_fma_f32 v[0:1], v[0:1], v[116:117], v[4:5]
	v_pk_fma_f32 v[2:3], v[2:3], v[114:115], v[6:7]
	global_store_dwordx4 v[58:59], v[0:3], off offset:1024
	global_load_dwordx4 v[0:3], v[20:21], off offset:2048
	s_nop 0
	global_load_dwordx4 v[4:7], v[22:23], off offset:2048
	v_pk_mul_f32 v[114:115], v[136:137], v[82:83] op_sel_hi:[1,0]
	v_pk_mul_f32 v[116:117], v[134:135], v[82:83] op_sel_hi:[1,0]
	v_lshlrev_b32_e32 v134, 16, v68
	v_and_b32_e32 v135, 0xffff0000, v68
	v_pk_mul_f32 v[68:69], v[98:99], v[82:83] op_sel_hi:[1,0]
	v_lshlrev_b32_e32 v98, 16, v52
	v_and_b32_e32 v99, 0xffff0000, v52
	v_lshlrev_b32_e32 v136, 16, v70
	v_and_b32_e32 v137, 0xffff0000, v70
	v_pk_add_f32 v[122:123], v[134:135], v[136:137]
	v_lshlrev_b32_e32 v70, 16, v71
	v_and_b32_e32 v71, 0xffff0000, v71
	v_pk_add_f32 v[70:71], v[140:141], v[70:71]
	v_lshlrev_b32_e32 v52, 16, v53
	v_pk_fma_f32 v[70:71], v[138:139], s[2:3], v[70:71] op_sel_hi:[1,0,1]
	v_and_b32_e32 v53, 0xffff0000, v53
	s_waitcnt vmcnt(0)
	v_pk_fma_f32 v[0:1], v[0:1], v[116:117], v[4:5]
	v_pk_fma_f32 v[2:3], v[2:3], v[114:115], v[6:7]
	global_store_dwordx4 v[58:59], v[0:3], off offset:2048
	global_load_dwordx4 v[114:117], v[20:21], off offset:3072
	global_load_dwordx4 v[118:121], v[22:23], off offset:3072
	v_lshlrev_b64 v[0:1], 13, v[44:45]
	v_lshl_add_u64 v[4:5], v[16:17], 0, v[0:1]
	v_add_co_u32_e32 v0, vcc, s6, v20
	v_and_b32_e32 v44, 0xffff0000, v76
	s_nop 0
	v_addc_co_u32_e32 v1, vcc, 0, v21, vcc
	v_add_co_u32_e32 v2, vcc, s6, v22
	v_lshlrev_b32_e32 v45, 16, v76
	s_nop 0
	v_addc_co_u32_e32 v3, vcc, 0, v23, vcc
	v_add_co_u32_e32 v6, vcc, s6, v58
	v_pk_fma_f32 v[44:45], v[44:45], s[2:3], v[92:93] op_sel_hi:[1,0,1]
	s_nop 0
	v_addc_co_u32_e32 v7, vcc, 0, v59, vcc
	v_and_b32_e32 v76, 0xffff0000, v77
	v_lshlrev_b32_e32 v77, 16, v77
	v_pk_fma_f32 v[76:77], v[76:77], s[2:3], v[94:95] op_sel_hi:[1,0,1]
	s_waitcnt vmcnt(0)
	v_pk_fma_f32 v[66:67], v[114:115], v[66:67], v[118:119]
	v_pk_fma_f32 v[68:69], v[116:117], v[68:69], v[120:121]
	global_store_dwordx4 v[58:59], v[66:69], off offset:3072
	global_load_dwordx4 v[66:69], v[0:1], off
	s_nop 0
	global_load_dwordx4 v[78:81], v[2:3], off
	v_lshlrev_b32_e32 v118, 16, v46
	v_and_b32_e32 v119, 0xffff0000, v46
	v_lshlrev_b32_e32 v120, 16, v48
	v_and_b32_e32 v121, 0xffff0000, v48
	v_lshlrev_b32_e32 v58, 16, v62
	v_and_b32_e32 v59, 0xffff0000, v62
	v_lshlrev_b32_e32 v62, 16, v63
	v_and_b32_e32 v63, 0xffff0000, v63
	v_lshlrev_b32_e32 v114, 16, v54
	v_and_b32_e32 v115, 0xffff0000, v54
	v_lshlrev_b32_e32 v116, 16, v56
	v_and_b32_e32 v117, 0xffff0000, v56
	v_pk_add_f32 v[62:63], v[62:63], v[64:65]
	v_pk_add_f32 v[64:65], v[114:115], v[116:117]
	v_pk_fma_f32 v[60:61], v[60:61], s[2:3], v[62:63] op_sel_hi:[1,0,1]
	v_pk_fma_f32 v[62:63], v[98:99], s[2:3], v[64:65] op_sel_hi:[1,0,1]
	v_pk_add_f32 v[58:59], v[58:59], v[96:97]
	v_lshlrev_b32_e32 v54, 16, v55
	v_pk_fma_f32 v[58:59], v[142:143], s[2:3], v[58:59] op_sel_hi:[1,0,1]
	v_and_b32_e32 v55, 0xffff0000, v55
	v_lshlrev_b32_e32 v56, 16, v57
	v_and_b32_e32 v57, 0xffff0000, v57
	v_pk_add_f32 v[54:55], v[54:55], v[56:57]
	v_pk_add_f32 v[56:57], v[120:121], v[144:145]
	v_pk_fma_f32 v[52:53], v[52:53], s[2:3], v[54:55] op_sel_hi:[1,0,1]
	v_pk_fma_f32 v[54:55], v[118:119], s[2:3], v[56:57] op_sel_hi:[1,0,1]
	v_pk_add_f32 v[96:97], v[152:153], v[154:155]
	s_waitcnt vmcnt(0)
; template <class G, class T> __device__ __forceinline__ G opaque_g(T* q) { asm volatile("" : "+v"(q)); return (G)q; }
; __device__ __forceinline__ void ln_stats(const float (&v)[32], float& mean, float& rstd) {
;   float s = 0.f;
; #pragma unroll
;   for (int i = 0; i < 32; i++) s += v[i];
;   mean = wave_sum(s) * (1.f / DM);
;   float q = 0.f;
; #pragma unroll
;   for (int i = 0; i < 32; i++) { float d = v[i] - mean; q += d * d; }
;   rstd = rsqrtf(wave_sum(q) * (1.f / DM) + 1e-5f);
; }
; template <int MODE>
; __device__ void phase_ln(const Params& p, u16* smem) {
;     ...
;     g_cv4 pg = opaque_g<g_cv4>(gam + lane * 4);
;     g_cv4 pb = opaque_g<g_cv4>(bet + lane * 4);
; #pragma unroll
;     for (int q = 0; q < 2; q++) {
;       g_v4 po = opaque_g<g_v4>(p.out + (long)(rb + q) * DM + lane * 4);
;       g_u2 ph = opaque_g<g_u2>(p.hb() + (long)(rb + q) * DM + lane * 4);
; #pragma unroll
;       for (int i = 0; i < 8; i++) {
;         f32x4 g = pg[i * 64], b = pb[i * 64];
;         f32x4 o4;
; #pragma unroll
;         for (int e = 0; e < 4; e++) o4[e] = (v[q][i * 4 + e] - mean[q]) * rstd[q] * g[e] + b[e];
;         if (MODE == 2) po[i * 64] = o4;
;         else { u32x2 w = {pack2(o4[0], o4[1]), pack2(o4[2], o4[3])}; ph[i * 64] = w; }
;       }
	v_pk_fma_f32 v[38:39], v[66:67], v[38:39], v[78:79]
	v_pk_fma_f32 v[40:41], v[68:69], v[40:41], v[80:81]
	global_store_dwordx4 v[6:7], v[38:41], off
	global_load_dwordx4 v[38:41], v[0:1], off offset:1024
	s_nop 0
	global_load_dwordx4 v[46:49], v[2:3], off offset:1024
	v_lshlrev_b32_e32 v66, 16, v36
	v_and_b32_e32 v67, 0xffff0000, v36
	v_lshlrev_b32_e32 v78, 16, v28
	v_and_b32_e32 v79, 0xffff0000, v28
	v_lshlrev_b32_e32 v80, 16, v30
	v_and_b32_e32 v81, 0xffff0000, v30
	v_lshlrev_b32_e32 v28, 16, v29
	v_and_b32_e32 v29, 0xffff0000, v29
	v_lshlrev_b32_e32 v30, 16, v31
	v_and_b32_e32 v31, 0xffff0000, v31
	v_lshlrev_b32_e32 v68, 16, v26
	v_and_b32_e32 v69, 0xffff0000, v26
	v_lshlrev_b32_e32 v26, 16, v27
	v_and_b32_e32 v27, 0xffff0000, v27
	v_pk_add_f32 v[66:67], v[162:163], v[66:67]
	v_pk_add_f32 v[28:29], v[28:29], v[30:31]
	v_pk_fma_f32 v[64:65], v[160:161], s[2:3], v[66:67] op_sel_hi:[1,0,1]
	v_pk_fma_f32 v[66:67], v[26:27], s[2:3], v[28:29] op_sel_hi:[1,0,1]
	v_pk_mul_f32 v[28:29], v[90:91], v[82:83] op_sel_hi:[1,0]
	v_pk_mul_f32 v[26:27], v[88:89], v[82:83] op_sel_hi:[1,0]
	v_lshlrev_b32_e32 v36, 16, v37
	v_and_b32_e32 v37, 0xffff0000, v37
	v_pk_add_f32 v[34:35], v[34:35], v[36:37]
	v_pk_add_f32 v[36:37], v[78:79], v[80:81]
	v_pk_fma_f32 v[34:35], v[32:33], s[2:3], v[34:35] op_sel_hi:[1,0,1]
	v_pk_fma_f32 v[78:79], v[130:131], s[2:3], v[122:123] op_sel_hi:[1,0,1]
	v_pk_fma_f32 v[36:37], v[68:69], s[2:3], v[36:37] op_sel_hi:[1,0,1]
	v_add_f32_e32 v68, 0, v78
	v_pk_fma_f32 v[56:57], v[150:151], s[2:3], v[96:97] op_sel_hi:[1,0,1]
	s_waitcnt vmcnt(0)
	v_pk_fma_f32 v[26:27], v[38:39], v[26:27], v[46:47]
	v_pk_fma_f32 v[28:29], v[40:41], v[28:29], v[48:49]
	global_store_dwordx4 v[6:7], v[26:29], off offset:1024
	global_load_dwordx4 v[26:29], v[0:1], off offset:2048
	s_nop 0
	global_load_dwordx4 v[30:33], v[2:3], off offset:2048
	v_add_f32_e32 v38, v79, v68
	v_add_f32_e32 v38, v70, v38
	v_add_f32_e32 v38, v71, v38
	v_add_f32_e32 v38, v58, v38
	v_add_f32_e32 v38, v59, v38
	v_add_f32_e32 v38, v60, v38
	v_add_f32_e32 v38, v61, v38
	v_add_f32_e32 v38, v62, v38
	v_add_f32_e32 v38, v63, v38
	v_add_f32_e32 v38, v52, v38
	v_add_f32_e32 v38, v53, v38
	v_add_f32_e32 v38, v54, v38
	v_add_f32_e32 v38, v55, v38
	v_add_f32_e32 v38, v50, v38
	v_add_f32_e32 v38, v51, v38
	v_add_f32_e32 v38, v56, v38
	v_add_f32_e32 v38, v57, v38
	v_add_f32_e32 v38, v42, v38
	v_add_f32_e32 v38, v43, v38
	v_add_f32_e32 v38, v64, v38
	v_add_f32_e32 v38, v65, v38
	v_add_f32_e32 v38, v34, v38
	v_add_f32_e32 v38, v35, v38
	v_add_f32_e32 v38, v36, v38
	v_add_f32_e32 v38, v37, v38
	v_add_f32_e32 v38, v66, v38
	v_add_f32_e32 v38, v67, v38
	v_add_f32_e32 v38, v45, v38
	v_add_f32_e32 v38, v44, v38
	v_add_f32_e32 v38, v77, v38
	v_add_f32_e32 v38, v76, v38
	ds_bpermute_b32 v39, v113, v38
	v_pk_mul_f32 v[40:41], v[84:85], v[82:83] op_sel_hi:[1,0]
	s_waitcnt lgkmcnt(0)
	v_add_f32_e32 v38, v38, v39
	ds_bpermute_b32 v39, v112, v38
	s_waitcnt lgkmcnt(0)
	v_add_f32_e32 v38, v38, v39
	ds_bpermute_b32 v39, v111, v38
	s_waitcnt lgkmcnt(0)
	v_add_f32_e32 v38, v38, v39
	ds_bpermute_b32 v39, v110, v38
	s_waitcnt lgkmcnt(0)
	v_add_f32_e32 v46, v38, v39
	v_pk_mul_f32 v[38:39], v[86:87], v[82:83] op_sel_hi:[1,0]
	s_waitcnt vmcnt(0)
	v_pk_fma_f32 v[26:27], v[26:27], v[40:41], v[30:31]
	v_pk_fma_f32 v[28:29], v[28:29], v[38:39], v[32:33]
	global_store_dwordx4 v[6:7], v[26:29], off offset:2048
	global_load_dwordx4 v[26:29], v[0:1], off offset:3072
	s_nop 0
	global_load_dwordx4 v[30:33], v[2:3], off offset:3072
	ds_bpermute_b32 v38, v109, v46
	s_waitcnt lgkmcnt(0)
	v_add_f32_e32 v38, v46, v38
	ds_bpermute_b32 v39, v19, v38
	s_waitcnt lgkmcnt(0)
	v_add_f32_e32 v38, v38, v39
	v_mul_f32_e32 v38, 0x3a000000, v38
	v_pk_add_f32 v[40:41], v[78:79], v[38:39] op_sel_hi:[1,0] neg_lo:[0,1] neg_hi:[0,1]
	v_pk_add_f32 v[46:47], v[70:71], v[38:39] op_sel_hi:[1,0] neg_lo:[0,1] neg_hi:[0,1]
	v_pk_add_f32 v[48:49], v[58:59], v[38:39] op_sel_hi:[1,0] neg_lo:[0,1] neg_hi:[0,1]
	v_pk_add_f32 v[58:59], v[60:61], v[38:39] op_sel_hi:[1,0] neg_lo:[0,1] neg_hi:[0,1]
	v_pk_add_f32 v[60:61], v[62:63], v[38:39] op_sel_hi:[1,0] neg_lo:[0,1] neg_hi:[0,1]
	v_pk_add_f32 v[62:63], v[64:65], v[38:39] op_sel_hi:[1,0] neg_lo:[0,1] neg_hi:[0,1]
	v_pk_add_f32 v[64:65], v[66:67], v[38:39] op_sel_hi:[1,0] neg_lo:[0,1] neg_hi:[0,1]
	v_pk_mul_f32 v[66:67], v[40:41], v[40:41]
	v_pk_mul_f32 v[68:69], v[46:47], v[46:47]
	v_add_f32_e32 v66, v66, v67
	v_add_f32_e32 v66, v68, v66
	v_pk_mul_f32 v[70:71], v[48:49], v[48:49]
	v_add_f32_e32 v66, v69, v66
	v_add_f32_e32 v66, v70, v66
	v_pk_add_f32 v[52:53], v[52:53], v[38:39] op_sel_hi:[1,0] neg_lo:[0,1] neg_hi:[0,1]
	v_pk_add_f32 v[54:55], v[54:55], v[38:39] op_sel_hi:[1,0] neg_lo:[0,1] neg_hi:[0,1]
	v_pk_add_f32 v[50:51], v[50:51], v[38:39] op_sel_hi:[1,0] neg_lo:[0,1] neg_hi:[0,1]
	v_pk_add_f32 v[56:57], v[56:57], v[38:39] op_sel_hi:[1,0] neg_lo:[0,1] neg_hi:[0,1]
	v_pk_add_f32 v[42:43], v[42:43], v[38:39] op_sel_hi:[1,0] neg_lo:[0,1] neg_hi:[0,1]
	v_pk_add_f32 v[34:35], v[34:35], v[38:39] op_sel_hi:[1,0] neg_lo:[0,1] neg_hi:[0,1]
	v_pk_add_f32 v[36:37], v[36:37], v[38:39] op_sel_hi:[1,0] neg_lo:[0,1] neg_hi:[0,1]
	v_pk_add_f32 v[44:45], v[44:45], v[38:39] op_sel_hi:[1,0] neg_lo:[0,1] neg_hi:[0,1]
	v_pk_add_f32 v[38:39], v[76:77], v[38:39] op_sel_hi:[1,0] neg_lo:[0,1] neg_hi:[0,1]
	v_pk_mul_f32 v[76:77], v[58:59], v[58:59]
	v_add_f32_e32 v66, v71, v66
	v_add_f32_e32 v66, v76, v66
	v_pk_mul_f32 v[78:79], v[60:61], v[60:61]
	v_add_f32_e32 v66, v77, v66
	v_add_f32_e32 v66, v78, v66
	v_pk_mul_f32 v[80:81], v[52:53], v[52:53]
	v_add_f32_e32 v66, v79, v66
	v_add_f32_e32 v66, v80, v66
	v_pk_mul_f32 v[84:85], v[54:55], v[54:55]
	v_add_f32_e32 v66, v81, v66
	v_add_f32_e32 v66, v84, v66
	v_pk_mul_f32 v[86:87], v[50:51], v[50:51]
	v_add_f32_e32 v66, v85, v66
	v_add_f32_e32 v66, v86, v66
	v_add_f32_e32 v70, v87, v66
	v_pk_mul_f32 v[66:67], v[72:73], v[82:83] op_sel_hi:[1,0]
	v_pk_mul_f32 v[68:69], v[74:75], v[82:83] op_sel_hi:[1,0]
	v_pk_mul_f32 v[88:89], v[56:57], v[56:57]
	v_pk_mul_f32 v[90:91], v[42:43], v[42:43]
	v_pk_mul_f32 v[92:93], v[62:63], v[62:63]
	v_pk_mul_f32 v[94:95], v[34:35], v[34:35]
	v_pk_mul_f32 v[96:97], v[36:37], v[36:37]
	v_pk_mul_f32 v[98:99], v[64:65], v[64:65]
	v_pk_mul_f32 v[114:115], v[44:45], v[44:45]
	v_pk_mul_f32 v[116:117], v[38:39], v[38:39]
	s_waitcnt vmcnt(0)
; template <class G, class T> __device__ __forceinline__ G opaque_g(T* q) { asm volatile("" : "+v"(q)); return (G)q; }
; __device__ __forceinline__ void ln_stats(const float (&v)[32], float& mean, float& rstd) {
;   float s = 0.f;
; #pragma unroll
;   for (int i = 0; i < 32; i++) s += v[i];
;   mean = wave_sum(s) * (1.f / DM);
;   float q = 0.f;
; #pragma unroll
;   for (int i = 0; i < 32; i++) { float d = v[i] - mean; q += d * d; }
;   rstd = rsqrtf(wave_sum(q) * (1.f / DM) + 1e-5f);
; }
; template <int MODE>
; __device__ void phase_ln(const Params& p, u16* smem) {
;     ...
; #pragma unroll
;     for (int q = 0; q < 2; q++) {
;       g_v4 po = opaque_g<g_v4>(p.out + (long)(rb + q) * DM + lane * 4);
;       g_u2 ph = opaque_g<g_u2>(p.hb() + (long)(rb + q) * DM + lane * 4);
; #pragma unroll
;       for (int i = 0; i < 8; i++) {
;         f32x4 g = pg[i * 64], b = pb[i * 64];
;         f32x4 o4;
; #pragma unroll
;         for (int e = 0; e < 4; e++) o4[e] = (v[q][i * 4 + e] - mean[q]) * rstd[q] * g[e] + b[e];
;         if (MODE == 2) po[i * 64] = o4;
;         else { u32x2 w = {pack2(o4[0], o4[1]), pack2(o4[2], o4[3])}; ph[i * 64] = w; }
;       }
	v_pk_fma_f32 v[26:27], v[26:27], v[66:67], v[30:31] op_sel:[0,1,0] op_sel_hi:[1,0,1]
	v_pk_fma_f32 v[28:29], v[28:29], v[68:69], v[32:33] op_sel:[0,1,0] op_sel_hi:[1,0,1]
	global_store_dwordx4 v[6:7], v[26:29], off offset:3072
	global_load_dwordx4 v[24:27], v[20:21], off
	global_load_dwordx4 v[28:31], v[22:23], off
	v_add_f32_e32 v6, v88, v70
	v_add_f32_e32 v6, v89, v6
	v_add_f32_e32 v6, v90, v6
	v_add_f32_e32 v6, v91, v6
	v_add_f32_e32 v6, v92, v6
	v_add_f32_e32 v6, v93, v6
	v_add_f32_e32 v6, v94, v6
	v_add_f32_e32 v6, v95, v6
	v_add_f32_e32 v6, v96, v6
	v_add_f32_e32 v6, v97, v6
	v_add_f32_e32 v6, v98, v6
	v_add_f32_e32 v6, v99, v6
	v_add_f32_e32 v6, v115, v6
	v_add_f32_e32 v6, v114, v6
	v_add_f32_e32 v6, v117, v6
	v_add_f32_e32 v6, v116, v6
	ds_bpermute_b32 v7, v113, v6
	s_waitcnt lgkmcnt(0)
	v_add_f32_e32 v6, v6, v7
	ds_bpermute_b32 v7, v112, v6
	s_waitcnt lgkmcnt(0)
	v_add_f32_e32 v6, v6, v7
	ds_bpermute_b32 v7, v111, v6
	s_waitcnt lgkmcnt(0)
	v_add_f32_e32 v6, v6, v7
	ds_bpermute_b32 v7, v110, v6
	s_waitcnt lgkmcnt(0)
	v_add_f32_e32 v6, v6, v7
	ds_bpermute_b32 v7, v109, v6
	s_waitcnt lgkmcnt(0)
	v_add_f32_e32 v6, v6, v7
	ds_bpermute_b32 v7, v19, v6
	s_waitcnt lgkmcnt(0)
	v_add_f32_e32 v6, v6, v7
	v_fmamk_f32 v6, v6, 0x3a000000, v108
	v_mul_f32_e32 v7, 0x4b800000, v6
	v_cmp_gt_f32_e32 vcc, s5, v6
	s_nop 1
	v_cndmask_b32_e32 v6, v6, v7, vcc
	v_rsq_f32_e32 v6, v6
	s_nop 0
	v_mul_f32_e32 v7, 0x45800000, v6
	v_cndmask_b32_e32 v32, v6, v7, vcc
	v_pk_mul_f32 v[6:7], v[46:47], v[32:33] op_sel_hi:[1,0]
	v_pk_mul_f32 v[40:41], v[40:41], v[32:33] op_sel_hi:[1,0]
	s_waitcnt vmcnt(0)
	v_pk_fma_f32 v[26:27], v[26:27], v[6:7], v[30:31]
	v_pk_fma_f32 v[24:25], v[24:25], v[40:41], v[28:29]
	global_store_dwordx4 v[4:5], v[24:27], off
	global_load_dwordx4 v[24:27], v[20:21], off offset:1024
	s_nop 0
	global_load_dwordx4 v[28:31], v[22:23], off offset:1024
	v_pk_mul_f32 v[6:7], v[58:59], v[32:33] op_sel_hi:[1,0]
	v_pk_mul_f32 v[40:41], v[48:49], v[32:33] op_sel_hi:[1,0]
	s_waitcnt vmcnt(0)
	v_pk_fma_f32 v[26:27], v[26:27], v[6:7], v[30:31]
	v_pk_fma_f32 v[24:25], v[24:25], v[40:41], v[28:29]
	global_store_dwordx4 v[4:5], v[24:27], off offset:1024
	global_load_dwordx4 v[24:27], v[20:21], off offset:2048
	s_nop 0
	global_load_dwordx4 v[28:31], v[22:23], off offset:2048
	v_pk_mul_f32 v[6:7], v[52:53], v[32:33] op_sel_hi:[1,0]
	v_pk_mul_f32 v[40:41], v[60:61], v[32:33] op_sel_hi:[1,0]
	s_waitcnt vmcnt(0)
	v_pk_fma_f32 v[26:27], v[26:27], v[6:7], v[30:31]
	v_pk_fma_f32 v[24:25], v[24:25], v[40:41], v[28:29]
	global_store_dwordx4 v[4:5], v[24:27], off offset:2048
	global_load_dwordx4 v[24:27], v[20:21], off offset:3072
	s_nop 0
	global_load_dwordx4 v[28:31], v[22:23], off offset:3072
	v_pk_mul_f32 v[6:7], v[50:51], v[32:33] op_sel_hi:[1,0]
	v_pk_mul_f32 v[20:21], v[54:55], v[32:33] op_sel_hi:[1,0]
	s_waitcnt vmcnt(0)
	v_pk_fma_f32 v[22:23], v[26:27], v[6:7], v[30:31]
	v_pk_fma_f32 v[20:21], v[24:25], v[20:21], v[28:29]
	global_store_dwordx4 v[4:5], v[20:23], off offset:3072
	global_load_dwordx4 v[20:23], v[0:1], off
	s_nop 0
	global_load_dwordx4 v[24:27], v[2:3], off
	v_pk_mul_f32 v[6:7], v[42:43], v[32:33] op_sel_hi:[1,0]
	v_pk_mul_f32 v[28:29], v[56:57], v[32:33] op_sel_hi:[1,0]
	v_add_co_u32_e32 v30, vcc, s6, v4
	s_waitcnt vmcnt(0)
	v_pk_fma_f32 v[6:7], v[6:7], v[22:23], v[26:27]
	v_addc_co_u32_e32 v31, vcc, 0, v5, vcc
	v_pk_fma_f32 v[4:5], v[28:29], v[20:21], v[24:25]
	global_store_dwordx4 v[30:31], v[4:7], off
	global_load_dwordx4 v[4:7], v[0:1], off offset:1024
	s_nop 0
	global_load_dwordx4 v[20:23], v[2:3], off offset:1024
	v_pk_mul_f32 v[24:25], v[34:35], v[32:33] op_sel_hi:[1,0]
	v_pk_mul_f32 v[26:27], v[62:63], v[32:33] op_sel_hi:[1,0]
	v_cmp_lt_i32_e32 vcc, s7, v132
	s_or_b64 s[0:1], vcc, s[0:1]
	s_waitcnt vmcnt(0)
	v_pk_fma_f32 v[4:5], v[26:27], v[4:5], v[20:21]
	v_pk_fma_f32 v[6:7], v[24:25], v[6:7], v[22:23]
	global_store_dwordx4 v[30:31], v[4:7], off offset:1024
	global_load_dwordx4 v[4:7], v[0:1], off offset:2048
	s_nop 0
	global_load_dwordx4 v[20:23], v[2:3], off offset:2048
	v_pk_mul_f32 v[24:25], v[64:65], v[32:33] op_sel_hi:[1,0]
	v_pk_mul_f32 v[26:27], v[36:37], v[32:33] op_sel_hi:[1,0]
	s_waitcnt vmcnt(0)
	v_pk_fma_f32 v[6:7], v[24:25], v[6:7], v[22:23]
	v_pk_fma_f32 v[4:5], v[26:27], v[4:5], v[20:21]
	global_store_dwordx4 v[30:31], v[4:7], off offset:2048
	global_load_dwordx4 v[4:7], v[0:1], off offset:3072
	s_nop 0
	global_load_dwordx4 v[20:23], v[2:3], off offset:3072
	v_pk_mul_f32 v[0:1], v[44:45], v[32:33] op_sel_hi:[1,0]
	v_pk_mul_f32 v[2:3], v[38:39], v[32:33] op_sel_hi:[1,0]
	s_waitcnt vmcnt(0)
	v_pk_fma_f32 v[0:1], v[0:1], v[4:5], v[20:21] op_sel:[1,0,0] op_sel_hi:[0,1,1]
	v_pk_fma_f32 v[2:3], v[2:3], v[6:7], v[22:23] op_sel:[1,0,0] op_sel_hi:[0,1,1]
	global_store_dwordx4 v[30:31], v[0:3], off offset:3072
	s_andn2_b64 exec, exec, s[0:1]
	s_cbranch_execnz .LBB0_1054
